# mixer phase staggered (half the WGs run SGU unit first) + batched gate_b/residual epilogue loads
# speedup vs baseline: 1.0024x; 1.0024x over previous
; __device__ __forceinline__ void attn_unit(LAS unsigned char* lds, bf16* Q, const bf16* Kg, const bf16* Vg, const float* snk, int unit, int tid) {
;     const int lane = tid & 63, wave = tid >> 6, fr = lane & 15, fq = lane >> 4;
;     const int b = unit >> 6, n = (unit >> 1) & 31, h = unit & 1, r0 = b * SEQ + n * 128, hq = 8 * h + wave;
;     const v4u zero4 = {0u, 0u, 0u, 0u};
;     bf16* qbase = Q + (size_t)(r0 + fr) * 1024 + hq * 64;
;     bf16x8_t qf[8][2];
; #pragma unroll
;     for (int mt = 0; mt < 8; ++mt) { qf[mt][0] = *(const bf16x8_t*)(qbase + (size_t)mt * 16 * 1024 + 8 * fq); qf[mt][1] = *(const bf16x8_t*)(qbase + (size_t)mt * 16 * 1024 + 32 + 8 * fq); }
; #pragma unroll
;     for (int i = 0; i < 4; ++i) { const int idx = tid + 512 * i, j = idx >> 3, c = idx & 7, p = n * 128 - 128 + j;
;         v4u w = zero4; if (p >= 0) w = *(const v4u*)(Kg + (size_t)(b * SEQ + p) * 128 + h * 64 + c * 8);
;         *(LAS v4u*)(lds + j * ATT_KP + c * 16) = w; }
; #pragma unroll
;     for (int i = 0; i < 2; ++i) { const int idx = tid + 512 * i, j = (idx >> 3) * 2, c = idx & 7, p = n * 128 - 128 + j;
;         v4u w0 = zero4, w1 = zero4;
;         if (p >= 0) { w0 = *(const v4u*)(Vg + (size_t)(b * SEQ + p) * 128 + h * 64 + c * 8); w1 = *(const v4u*)(Vg + (size_t)(b * SEQ + p + 1) * 128 + h * 64 + c * 8); }
;         const unsigned A0[4] = {w0.x, w0.y, w0.z, w0.w}, A1[4] = {w1.x, w1.y, w1.z, w1.w};
; #pragma unroll
;         for (int e = 0; e < 8; ++e) { const unsigned lo = (e & 1) ? (A0[e >> 1] >> 16) : (A0[e >> 1] & 0xffffu), hi = (e & 1) ? (A1[e >> 1] & 0xffff0000u) : (A1[e >> 1] << 16);
;             *(LAS unsigned*)(lds + ATT_VOFF + (8 * c + e) * ATT_VP + j * 2) = lo | hi; } }
;     __syncthreads();
;     const float sink = snk[hq] * 1.4426950408889634f;
;     bool lo_ok[4];
; #pragma unroll
;     for (int i = 0; i < 4; ++i) lo_ok[i] = (4 * fq + i - fr) > 0;
; __global__ void __launch_bounds__(512, 2) fwd_mega(Args a) {
;     ...
;         {
;             int tid_ = threadIdx.x; asm volatile("" : "+v"(tid_));
;             for (int it = bx; it < 512; it += G) {
;                 if (it < 256) attn_unit(lds, WSP(WS_Q), WSP(WS_K), WSP(WS_V), INF(7) + l * 16, it, tid_);
;                 else sgu_unit(lds, WSP(WS_U), WSP(WS_VS), (const float*)(a.ws + WS_SGS), INF(8) + l * 1024, INF(9) + l * 1024, (const v4u*)(a.ws + WS_WF), INF(11) + l * 8 * 128, it - 256, tid_);
.LBB0_491:
	s_or_b64 exec, exec, s[4:5]
	s_cmpk_lt_i32 s2, 0x200
	s_cselect_b64 s[4:5], -1, 0
	v_mov_b32_e32 v161, v0
	v_writelane_b32 v246, s4, 18
	s_cmpk_gt_i32 s2, 0x1ff
	s_waitcnt lgkmcnt(0)
	s_barrier
	v_writelane_b32 v246, s5, 19
	s_cbranch_scc1 .LBB0_512
	s_load_dwordx2 s[14:15], s[0:1], 0xb8
	s_load_dwordx2 s[42:43], s[0:1], 0x58
	v_and_b32_e32 v6, 7, v161
	v_add_u32_e32 v8, 0x200, v161
	v_lshlrev_b32_e32 v170, 3, v6
	v_mul_u32_u24_e32 v10, 0x110, v6
	v_bfe_u32 v15, v161, 4, 2
	v_lshlrev_b32_e32 v4, 4, v6
	s_waitcnt vmcnt(1)
	v_mul_u32_u24_e32 v20, 0x1080, v6
	v_ashrrev_i32_e32 v6, 2, v8
	v_ashrrev_i32_e32 v169, 6, v161
	s_movk_i32 s6, 0x4400
	v_add_u32_e32 v9, 0x400, v161
	v_and_b32_e32 v177, -2, v6
	v_lshlrev_b32_e32 v6, 2, v15
	s_waitcnt lgkmcnt(0)
	s_add_u32 s48, s14, 0x4b00000
	v_and_b32_e32 v3, 63, v161
	v_and_b32_e32 v163, 15, v161
	v_mul_lo_u32 v5, v169, s6
	v_ashrrev_i32_e32 v173, 3, v8
	v_ashrrev_i32_e32 v174, 3, v9
	v_add_u32_e32 v9, 0x600, v161
	v_or_b32_e32 v8, 2, v6
	s_addc_u32 s49, s15, 0
	v_mov_b32_e32 v147, 0
	v_ashrrev_i32_e32 v175, 3, v9
	v_ashrrev_i32_e32 v9, 2, v161
	v_cmp_gt_u32_e64 s[10:11], v8, v163
	v_or_b32_e32 v8, 3, v6
	v_lshlrev_b32_e32 v146, 4, v3
	s_add_u32 s52, s14, 0xf400000
	v_add_u32_e32 v3, 0, v5
	v_lshrrev_b32_e32 v5, 1, v161
	v_bfe_u32 v2, v161, 3, 3
	v_and_b32_e32 v176, -2, v9
	v_cmp_gt_u32_e64 s[12:13], v8, v163
	v_lshl_add_u64 v[8:9], s[14:15], 0, v[146:147]
	s_mov_b64 s[16:17], 0x680000
	s_addc_u32 s53, s15, 0
	v_and_b32_e32 v146, 24, v5
	v_lshlrev_b32_e32 v167, 3, v161
	v_lshlrev_b32_e32 v7, 11, v2
	v_lshlrev_b32_e32 v11, 2, v2
	v_lshlrev_b32_e32 v12, 4, v2
	v_bfe_u32 v2, v161, 3, 1
	v_lshl_add_u64 v[148:149], v[8:9], 0, s[16:17]
	v_lshl_add_u64 v[8:9], s[14:15], 0, v[146:147]
	s_mov_b64 s[16:17], 0x9300000
	s_add_u32 s56, s14, 0x6b00000
	v_mov_b32_e32 v5, v147
	v_and_or_b32 v2, v167, 56, v2
	s_load_dwordx4 s[28:31], s[0:1], 0x38
	s_load_dwordx2 s[50:51], s[0:1], 0x48
	v_lshl_add_u64 v[150:151], v[8:9], 0, s[16:17]
	s_addc_u32 s57, s15, 0
	v_add_u32_e32 v8, 0, v4
	v_lshl_add_u64 v[4:5], s[14:15], 0, v[4:5]
	s_mov_b64 s[14:15], 0x8b00000
	v_mul_u32_u24_e32 v14, 0x110, v2
	v_lshlrev_b32_e32 v2, 3, v15
	v_lshl_add_u64 v[152:153], v[4:5], 0, s[14:15]
	s_mov_b64 s[14:15], 0x8f00000
	v_lshl_add_u32 v9, v15, 4, 0
	v_and_b32_e32 v13, 48, v161
	v_ashrrev_i32_e32 v171, 3, v161
	s_movk_i32 s18, 0x90
	v_add3_u32 v178, v3, v10, v11
	v_lshl_add_u64 v[154:155], v[4:5], 0, s[14:15]
	v_sub_u32_e32 v10, v9, v2
	s_movk_i32 s14, 0x210
	s_movk_i32 s4, 0x80
	v_mul_lo_u32 v16, v171, s18
	v_mul_lo_u32 v17, v173, s18
	v_mul_lo_u32 v18, v174, s18
	v_mul_lo_u32 v19, v175, s18
	v_add_u32_e32 v3, v3, v13
	v_lshl_add_u32 v4, v176, 1, 0
	v_lshl_add_u32 v5, v177, 1, 0
	v_mad_u32_u24 v180, v163, s14, v10
	s_lshl_b32 s14, s2, 2
	v_ashrrev_i32_e32 v165, 7, v161
	v_cmp_gt_i32_e64 s[4:5], s4, v161
	v_and_b32_e32 v168, 64, v161
	v_cmp_gt_u32_e64 s[6:7], v6, v163
	v_cmp_lt_u32_e64 s[8:9], v6, v163
	s_mov_b32 s55, 0
	v_mad_u32_u24 v179, v163, s18, v9
	s_add_i32 s23, s14, 0xfffffc00
	s_lshl_b32 s24, s3, 2
	s_lshl_b32 s25, s2, 6
	s_lshl_b32 s34, s3, 6
	s_movk_i32 s35, 0x1000
	s_movk_i32 s36, 0x2000
	s_movk_i32 s37, 0x3000
	s_movk_i32 s38, 0x4000
	s_mov_b32 s58, 0x3a800000
	s_mov_b32 s39, 0x800000
	v_lshlrev_b32_e32 v181, 1, v7
	s_mov_b32 s40, 0x8000
	s_mov_b32 s41, 0x10000
	s_mov_b32 s44, 0x18000
	s_mov_b32 s45, 0x20000
	s_mov_b32 s46, 0x28000
	s_mov_b32 s47, 0x30000
	s_mov_b32 s59, 0x38000
	v_add_u32_e32 v182, 0, v12
	s_mov_b32 s60, 0xffff0000
	v_add_u32_e32 v183, v3, v14
	v_lshlrev_b32_e32 v146, 1, v2
	v_add_u32_e32 v184, v8, v16
	v_add_u32_e32 v185, v8, v17
	v_add_u32_e32 v186, v8, v18
	v_add_u32_e32 v187, v8, v19
	s_mov_b32 s61, 0xffff
	v_add_u32_e32 v188, v4, v20
	v_add_u32_e32 v189, v5, v20
	s_mov_b32 s62, 0x3fb8aa3b
	v_lshlrev_b32_e32 v156, 1, v6
	v_mbcnt_hi_u32_b32 v190, -1, v1
	v_mov_b32_e32 v191, 0xff800000
	s_mov_b32 s63, s2
	s_mov_b32 s98, 0x100
	s_mov_b32 s101, 0
	s_bitcmp1_b32 s2, 3
	s_cbranch_scc0 .Lmix_noswap0
	s_addk_i32 s63, 0x100
	s_addk_i32 s23, 0x400
	s_addk_i32 s25, 0x4000
	s_mov_b32 s98, 0xffffff00
.Lmix_noswap0:
	s_lshl_b32 s99, s98, 2
	s_lshl_b32 s100, s98, 6
	s_branch .LBB0_495

; __global__ void __launch_bounds__(512, 2) fwd_mega(Args a) {
;     ...
;             for (int it = bx; it < 512; it += G) {
;                 if (it < 256) attn_unit(lds, WSP(WS_Q), WSP(WS_K), WSP(WS_V), INF(7) + l * 16, it, tid_);
;                 else sgu_unit(lds, WSP(WS_U), WSP(WS_VS), (const float*)(a.ws + WS_SGS), INF(8) + l * 1024, INF(9) + l * 1024, (const v4u*)(a.ws + WS_WF), INF(11) + l * 8 * 128, it - 256, tid_);
.LBB0_494:
	s_add_i32 s63, s63, s98
	s_add_i32 s23, s23, s99
	s_add_i32 s25, s25, s100
	s_add_i32 s101, s101, 1
	s_cmp_gt_i32 s101, 1
	s_waitcnt lgkmcnt(0)
	s_cbranch_scc1 .LBB0_512

; __device__ __forceinline__ float bf_lo(unsigned w) { return __uint_as_float(w << 16); }
; __device__ __forceinline__ float bf_hi(unsigned w) { return __uint_as_float(w & 0xffff0000u); }
; __device__ __forceinline__ u32x4 pack8(f32x4 v0, f32x4 v1) { u32x4 w; w.x = cvt_pk_bf16(v0[0], v0[1]); w.y = cvt_pk_bf16(v0[2], v0[3]); w.z = cvt_pk_bf16(v1[0], v1[1]); w.w = cvt_pk_bf16(v1[2], v1[3]); return w; }
;     __device__ __forceinline__ void operator()(f32x4 (&acc)[2][2][4][2], const Unit& u, int wr, int wc, int fr, int fq) const {
;         const int pn = u.pn, row0 = u.pm * BM + wr * 64 + fr, co = (pn & 3) * 256 + wc * 32 + 8 * fq;
; #pragma unroll
;         for (int ai = 0; ai < 2; ++ai) {
;             u32x4 gaq[4][2];
; #pragma unroll
;             for (int m = 0; m < 4; ++m)
; #pragma unroll
;                 for (int bj = 0; bj < 2; ++bj) gaq[m][bj] = *(const u32x4*)(GA + (size_t)(row0 + ai * HALF + m * 16) * 1024 + co + bj * HALF);
; #pragma unroll
;             for (int m = 0; m < 4; ++m) {
;                 const size_t ro = (size_t)(row0 + ai * HALF + m * 16) * 1024 + co;
; #pragma unroll
;                 for (int bj = 0; bj < 2; ++bj) {
;                     const u32x4 ga = gaq[m][bj];
;                     f32x4 a0 = {bf_lo(ga.x), bf_hi(ga.x), bf_lo(ga.y), bf_hi(ga.y)}, a1 = {bf_lo(ga.z), bf_hi(ga.z), bf_lo(ga.w), bf_hi(ga.w)};
; #pragma unroll
;                     for (int i = 0; i < 4; ++i) { a0[i] = fmaxf(a0[i], 1e-20f); a1[i] = fmaxf(a1[i], 1e-20f); }
;                     if (pn < 4) {
;                         const u32x4 gb = *(const u32x4*)(GB + ro + bj * HALF);
;                         const f32x4 b0 = {bf_lo(gb.x), bf_hi(gb.x), bf_lo(gb.y), bf_hi(gb.y)}, b1 = {bf_lo(gb.z), bf_hi(gb.z), bf_lo(gb.w), bf_hi(gb.w)};
; #pragma unroll
;                         for (int i = 0; i < 4; ++i) { acc[ai][bj][m][0][i] *= b0[i] * __builtin_amdgcn_rcpf(a0[i]); acc[ai][bj][m][1][i] *= b1[i] * __builtin_amdgcn_rcpf(a1[i]); }
;                     } else {
;                         *(u32x4*)(MG + ro + bj * HALF) = pack8(acc[ai][bj][m][0] * a0, acc[ai][bj][m][1] * a1);
.LBB0_588:
	s_lshl_b32 s8, s50, 8
	v_lshl_add_u32 v180, s52, 8, v173
	s_and_b32 s8, s8, 0x300
	v_or_b32_e32 v209, s8, v207
	v_or_b32_e32 v186, 16, v180
	v_or_b32_e32 v184, 32, v180
	v_lshlrev_b32_e32 v166, 1, v209
	v_ashrrev_i32_e32 v181, 31, v180
	v_or_b32_e32 v182, 48, v180
	v_ashrrev_i32_e32 v187, 31, v186
	v_ashrrev_i32_e32 v185, 31, v184
	v_lshl_add_u64 v[178:179], s[14:15], 0, v[166:167]
	v_lshlrev_b64 v[130:131], 11, v[180:181]
	v_ashrrev_i32_e32 v183, 31, v182
	v_lshlrev_b64 v[132:133], 11, v[186:187]
	v_lshlrev_b64 v[134:135], 11, v[184:185]
	v_lshl_add_u64 v[130:131], v[178:179], 0, v[130:131]
	v_lshlrev_b64 v[136:137], 11, v[182:183]
	v_lshl_add_u64 v[132:133], v[178:179], 0, v[132:133]
	v_lshl_add_u64 v[134:135], v[178:179], 0, v[134:135]
	global_load_dwordx4 v[192:195], v[130:131], off
	v_lshl_add_u64 v[188:189], v[178:179], 0, v[136:137]
	global_load_dwordx4 v[154:157], v[130:131], off offset:256
	global_load_dwordx4 v[150:153], v[132:133], off
	global_load_dwordx4 v[146:149], v[132:133], off offset:256
	global_load_dwordx4 v[142:145], v[134:135], off
	global_load_dwordx4 v[138:141], v[134:135], off offset:256
	s_cmp_gt_i32 s50, 3
	s_cbranch_scc1 .Lgbskip_0_0
	s_sub_u32 s98, s16, s14
	s_subb_u32 s99, s17, s15
	v_lshl_add_u64 v[252:253], v[130:131], 0, s[98:99]
	global_load_dwordx4 v[218:221], v[252:253], off
	global_load_dwordx4 v[222:225], v[252:253], off offset:256
	v_lshl_add_u64 v[252:253], v[132:133], 0, s[98:99]
	global_load_dwordx4 v[226:229], v[252:253], off
	global_load_dwordx4 v[230:233], v[252:253], off offset:256
	v_lshl_add_u64 v[252:253], v[134:135], 0, s[98:99]
	global_load_dwordx4 v[234:237], v[252:253], off
	global_load_dwordx4 v[238:241], v[252:253], off offset:256
	v_lshl_add_u64 v[252:253], v[188:189], 0, s[98:99]
	global_load_dwordx4 v[242:245], v[252:253], off
	global_load_dwordx4 v[248:251], v[252:253], off offset:256
.Lgbskip_0_0:
	s_nop 0
	global_load_dwordx4 v[134:137], v[188:189], off
	global_load_dwordx4 v[130:133], v[188:189], off offset:256
	s_cmp_gt_i32 s50, 3
	v_lshlrev_b64 v[190:191], 10, v[180:181]
	s_cselect_b64 s[38:39], -1, 0
	v_or_b32_e32 v190, v190, v209
	s_mov_b64 s[8:9], -1
	s_and_b64 vcc, exec, s[38:39]
	v_lshl_add_u64 v[188:189], v[190:191], 1, s[12:13]
	s_waitcnt vmcnt(0)
	v_lshlrev_b32_e32 v166, 16, v192
	v_and_b32_e32 v181, 0xffff0000, v192
	v_lshlrev_b32_e32 v192, 16, v193
	v_and_b32_e32 v193, 0xffff0000, v193
	v_lshlrev_b32_e32 v196, 16, v194
	v_and_b32_e32 v194, 0xffff0000, v194
	v_lshlrev_b32_e32 v197, 16, v195
	v_and_b32_e32 v195, 0xffff0000, v195
	v_max_f32_e32 v166, v166, v166
	v_max_f32_e32 v196, v196, v196
	v_max_f32_e32 v181, v181, v181
	v_max_f32_e32 v194, v194, v194
	v_max_f32_e32 v192, v192, v192
	v_max_f32_e32 v210, v197, v197
	v_max_f32_e32 v193, v193, v193
	v_max_f32_e32 v211, v195, v195
	v_max_f32_e32 v198, 0x1e3ce508, v166
	v_max_f32_e32 v196, 0x1e3ce508, v196
	v_max_f32_e32 v199, 0x1e3ce508, v181
	v_max_f32_e32 v197, 0x1e3ce508, v194
	v_max_f32_e32 v194, 0x1e3ce508, v192
	v_max_f32_e32 v192, 0x1e3ce508, v210
	v_max_f32_e32 v195, 0x1e3ce508, v193
	v_max_f32_e32 v193, 0x1e3ce508, v211
	s_cbranch_vccz .LBB0_590
	v_pk_mul_f32 v[212:213], v[128:129], v[194:195]
	v_pk_mul_f32 v[210:211], v[126:127], v[198:199]
	v_pk_mul_f32 v[214:215], v[124:125], v[192:193]
	v_pk_mul_f32 v[216:217], v[122:123], v[196:197]
	v_cvt_pk_bf16_f32 v210, v210, v211
	v_cvt_pk_bf16_f32 v211, v212, v213
	s_mov_b64 s[8:9], 0
	v_cvt_pk_bf16_f32 v212, v216, v217
	v_cvt_pk_bf16_f32 v213, v214, v215
	global_store_dwordx4 v[188:189], v[210:213], off
.LBB0_590:
	s_andn2_b64 vcc, exec, s[8:9]
	v_lshl_add_u64 v[190:191], v[190:191], 1, s[16:17]
	s_cbranch_vccnz .LBB0_592
	v_rcp_f32_e32 v198, v198
	v_rcp_f32_e32 v196, v196
	v_rcp_f32_e32 v199, v199
	v_rcp_f32_e32 v197, v197
	v_rcp_f32_e32 v194, v194
	v_rcp_f32_e32 v192, v192
	v_rcp_f32_e32 v195, v195
	v_rcp_f32_e32 v193, v193
	s_waitcnt vmcnt(0)
	v_mov_b32_e32 v210, v218
	v_mov_b32_e32 v211, v219
	v_mov_b32_e32 v212, v220
	v_mov_b32_e32 v213, v221
	v_lshlrev_b32_e32 v214, 16, v210
	v_and_b32_e32 v215, 0xffff0000, v210
	v_lshlrev_b32_e32 v216, 16, v212
	v_and_b32_e32 v217, 0xffff0000, v212
	v_lshlrev_b32_e32 v210, 16, v211
	v_and_b32_e32 v211, 0xffff0000, v211
	v_lshlrev_b32_e32 v212, 16, v213
	v_and_b32_e32 v213, 0xffff0000, v213
	v_pk_mul_f32 v[198:199], v[198:199], v[214:215]
	v_pk_mul_f32 v[196:197], v[196:197], v[216:217]
	v_pk_mul_f32 v[194:195], v[194:195], v[210:211]
	v_pk_mul_f32 v[192:193], v[192:193], v[212:213]
	v_pk_mul_f32 v[126:127], v[126:127], v[198:199]
	v_pk_mul_f32 v[122:123], v[122:123], v[196:197]
	v_pk_mul_f32 v[128:129], v[128:129], v[194:195]
	v_pk_mul_f32 v[124:125], v[124:125], v[192:193]

; __device__ __forceinline__ float bf_lo(unsigned w) { return __uint_as_float(w << 16); }
; __device__ __forceinline__ float bf_hi(unsigned w) { return __uint_as_float(w & 0xffff0000u); }
;     __device__ __forceinline__ void operator()(f32x4 (&acc)[2][2][4][2], const Unit& u, int wr, int wc, int fr, int fq) const {
;     ...
;                     if (pn < 4) {
;                         const u32x4 gb = *(const u32x4*)(GB + ro + bj * HALF);
;                         const f32x4 b0 = {bf_lo(gb.x), bf_hi(gb.x), bf_lo(gb.y), bf_hi(gb.y)}, b1 = {bf_lo(gb.z), bf_hi(gb.z), bf_lo(gb.w), bf_hi(gb.w)};
; #pragma unroll
;                         for (int i = 0; i < 4; ++i) { acc[ai][bj][m][0][i] *= b0[i] * __builtin_amdgcn_rcpf(a0[i]); acc[ai][bj][m][1][i] *= b1[i] * __builtin_amdgcn_rcpf(a1[i]); }
.LBB0_594:
	s_andn2_b64 vcc, exec, s[38:39]
	s_cbranch_vccnz .LBB0_596
	v_rcp_f32_e32 v194, v194
	v_rcp_f32_e32 v192, v192
	v_rcp_f32_e32 v195, v195
	v_rcp_f32_e32 v193, v193
	v_rcp_f32_e32 v156, v156
	v_rcp_f32_e32 v154, v154
	v_rcp_f32_e32 v157, v157
	v_rcp_f32_e32 v155, v155
	s_waitcnt vmcnt(0)
	v_mov_b32_e32 v188, v222
	v_mov_b32_e32 v189, v223
	v_mov_b32_e32 v190, v224
	v_mov_b32_e32 v191, v225
	v_lshlrev_b32_e32 v196, 16, v188
	v_and_b32_e32 v197, 0xffff0000, v188
	v_lshlrev_b32_e32 v198, 16, v190
	v_and_b32_e32 v199, 0xffff0000, v190
	v_lshlrev_b32_e32 v188, 16, v189
	v_and_b32_e32 v189, 0xffff0000, v189
	v_lshlrev_b32_e32 v190, 16, v191
	v_and_b32_e32 v191, 0xffff0000, v191
	v_pk_mul_f32 v[194:195], v[194:195], v[196:197]
	v_pk_mul_f32 v[192:193], v[192:193], v[198:199]
	v_pk_mul_f32 v[156:157], v[156:157], v[188:189]
	v_pk_mul_f32 v[154:155], v[154:155], v[190:191]
	v_pk_mul_f32 v[94:95], v[94:95], v[194:195]
	v_pk_mul_f32 v[90:91], v[90:91], v[192:193]
	v_pk_mul_f32 v[96:97], v[96:97], v[156:157]
	v_pk_mul_f32 v[92:93], v[92:93], v[154:155]

; __device__ __forceinline__ float bf_lo(unsigned w) { return __uint_as_float(w << 16); }
; __device__ __forceinline__ float bf_hi(unsigned w) { return __uint_as_float(w & 0xffff0000u); }
;     __device__ __forceinline__ void operator()(f32x4 (&acc)[2][2][4][2], const Unit& u, int wr, int wc, int fr, int fq) const {
;     ...
;                     if (pn < 4) {
;                         const u32x4 gb = *(const u32x4*)(GB + ro + bj * HALF);
;                         const f32x4 b0 = {bf_lo(gb.x), bf_hi(gb.x), bf_lo(gb.y), bf_hi(gb.y)}, b1 = {bf_lo(gb.z), bf_hi(gb.z), bf_lo(gb.w), bf_hi(gb.w)};
; #pragma unroll
;                         for (int i = 0; i < 4; ++i) { acc[ai][bj][m][0][i] *= b0[i] * __builtin_amdgcn_rcpf(a0[i]); acc[ai][bj][m][1][i] *= b1[i] * __builtin_amdgcn_rcpf(a1[i]); }
.LBB0_598:
	s_andn2_b64 vcc, exec, s[38:39]
	v_lshl_add_u64 v[152:153], v[190:191], 1, s[16:17]
	s_cbranch_vccnz .LBB0_600
	v_rcp_f32_e32 v188, v188
	v_rcp_f32_e32 v186, v186
	v_rcp_f32_e32 v189, v189
	v_rcp_f32_e32 v187, v187
	v_rcp_f32_e32 v156, v156
	v_rcp_f32_e32 v154, v154
	v_rcp_f32_e32 v157, v157
	v_rcp_f32_e32 v155, v155
	s_waitcnt vmcnt(0)
	v_mov_b32_e32 v190, v226
	v_mov_b32_e32 v191, v227
	v_mov_b32_e32 v192, v228
	v_mov_b32_e32 v193, v229
	v_lshlrev_b32_e32 v194, 16, v190
	v_and_b32_e32 v195, 0xffff0000, v190
	v_lshlrev_b32_e32 v196, 16, v192
	v_and_b32_e32 v197, 0xffff0000, v192
	v_lshlrev_b32_e32 v190, 16, v191
	v_and_b32_e32 v191, 0xffff0000, v191
	v_lshlrev_b32_e32 v192, 16, v193
	v_and_b32_e32 v193, 0xffff0000, v193
	v_pk_mul_f32 v[188:189], v[188:189], v[194:195]
	v_pk_mul_f32 v[186:187], v[186:187], v[196:197]
	v_pk_mul_f32 v[156:157], v[156:157], v[190:191]
	v_pk_mul_f32 v[154:155], v[154:155], v[192:193]
	v_pk_mul_f32 v[118:119], v[118:119], v[188:189]
	v_pk_mul_f32 v[114:115], v[114:115], v[186:187]
	v_pk_mul_f32 v[120:121], v[120:121], v[156:157]
	v_pk_mul_f32 v[116:117], v[116:117], v[154:155]

; __device__ __forceinline__ float bf_lo(unsigned w) { return __uint_as_float(w << 16); }
; __device__ __forceinline__ float bf_hi(unsigned w) { return __uint_as_float(w & 0xffff0000u); }
;     __device__ __forceinline__ void operator()(f32x4 (&acc)[2][2][4][2], const Unit& u, int wr, int wc, int fr, int fq) const {
;     ...
;                     if (pn < 4) {
;                         const u32x4 gb = *(const u32x4*)(GB + ro + bj * HALF);
;                         const f32x4 b0 = {bf_lo(gb.x), bf_hi(gb.x), bf_lo(gb.y), bf_hi(gb.y)}, b1 = {bf_lo(gb.z), bf_hi(gb.z), bf_lo(gb.w), bf_hi(gb.w)};
; #pragma unroll
;                         for (int i = 0; i < 4; ++i) { acc[ai][bj][m][0][i] *= b0[i] * __builtin_amdgcn_rcpf(a0[i]); acc[ai][bj][m][1][i] *= b1[i] * __builtin_amdgcn_rcpf(a1[i]); }
.LBB0_602:
	s_andn2_b64 vcc, exec, s[38:39]
	s_cbranch_vccnz .LBB0_604
	v_rcp_f32_e32 v156, v156
	v_rcp_f32_e32 v154, v154
	v_rcp_f32_e32 v157, v157
	v_rcp_f32_e32 v155, v155
	v_rcp_f32_e32 v148, v148
	v_rcp_f32_e32 v146, v146
	v_rcp_f32_e32 v149, v149
	v_rcp_f32_e32 v147, v147
	s_waitcnt vmcnt(0)
	v_mov_b32_e32 v150, v230
	v_mov_b32_e32 v151, v231
	v_mov_b32_e32 v152, v232
	v_mov_b32_e32 v153, v233
	v_lshlrev_b32_e32 v186, 16, v150
	v_and_b32_e32 v187, 0xffff0000, v150
	v_lshlrev_b32_e32 v188, 16, v152
	v_and_b32_e32 v189, 0xffff0000, v152
	v_lshlrev_b32_e32 v150, 16, v151
	v_and_b32_e32 v151, 0xffff0000, v151
	v_lshlrev_b32_e32 v152, 16, v153
	v_and_b32_e32 v153, 0xffff0000, v153
	v_pk_mul_f32 v[156:157], v[156:157], v[186:187]
	v_pk_mul_f32 v[154:155], v[154:155], v[188:189]
	v_pk_mul_f32 v[148:149], v[148:149], v[150:151]
	v_pk_mul_f32 v[146:147], v[146:147], v[152:153]
	v_pk_mul_f32 v[86:87], v[86:87], v[156:157]
	v_pk_mul_f32 v[82:83], v[82:83], v[154:155]
	v_pk_mul_f32 v[88:89], v[88:89], v[148:149]
	v_pk_mul_f32 v[84:85], v[84:85], v[146:147]

; __device__ __forceinline__ float bf_lo(unsigned w) { return __uint_as_float(w << 16); }
; __device__ __forceinline__ float bf_hi(unsigned w) { return __uint_as_float(w & 0xffff0000u); }
;     __device__ __forceinline__ void operator()(f32x4 (&acc)[2][2][4][2], const Unit& u, int wr, int wc, int fr, int fq) const {
;     ...
;                     if (pn < 4) {
;                         const u32x4 gb = *(const u32x4*)(GB + ro + bj * HALF);
;                         const f32x4 b0 = {bf_lo(gb.x), bf_hi(gb.x), bf_lo(gb.y), bf_hi(gb.y)}, b1 = {bf_lo(gb.z), bf_hi(gb.z), bf_lo(gb.w), bf_hi(gb.w)};
; #pragma unroll
;                         for (int i = 0; i < 4; ++i) { acc[ai][bj][m][0][i] *= b0[i] * __builtin_amdgcn_rcpf(a0[i]); acc[ai][bj][m][1][i] *= b1[i] * __builtin_amdgcn_rcpf(a1[i]); }
.LBB0_606:
	s_andn2_b64 vcc, exec, s[38:39]
	v_lshl_add_u64 v[144:145], v[154:155], 1, s[16:17]
	s_cbranch_vccnz .LBB0_608
	v_rcp_f32_e32 v152, v152
	v_rcp_f32_e32 v150, v150
	v_rcp_f32_e32 v153, v153
	v_rcp_f32_e32 v151, v151
	v_rcp_f32_e32 v148, v148
	v_rcp_f32_e32 v146, v146
	v_rcp_f32_e32 v149, v149
	v_rcp_f32_e32 v147, v147
	s_waitcnt vmcnt(0)
	v_mov_b32_e32 v154, v234
	v_mov_b32_e32 v155, v235
	v_mov_b32_e32 v156, v236
	v_mov_b32_e32 v157, v237
	v_lshlrev_b32_e32 v184, 16, v154
	v_and_b32_e32 v185, 0xffff0000, v154
	v_lshlrev_b32_e32 v186, 16, v156
	v_and_b32_e32 v187, 0xffff0000, v156
	v_lshlrev_b32_e32 v154, 16, v155
	v_and_b32_e32 v155, 0xffff0000, v155
	v_lshlrev_b32_e32 v156, 16, v157
	v_and_b32_e32 v157, 0xffff0000, v157
	v_pk_mul_f32 v[152:153], v[152:153], v[184:185]
	v_pk_mul_f32 v[150:151], v[150:151], v[186:187]
	v_pk_mul_f32 v[148:149], v[148:149], v[154:155]
	v_pk_mul_f32 v[146:147], v[146:147], v[156:157]
	v_pk_mul_f32 v[110:111], v[110:111], v[152:153]
	v_pk_mul_f32 v[106:107], v[106:107], v[150:151]
	v_pk_mul_f32 v[112:113], v[112:113], v[148:149]
	v_pk_mul_f32 v[108:109], v[108:109], v[146:147]

; __device__ __forceinline__ float bf_lo(unsigned w) { return __uint_as_float(w << 16); }
; __device__ __forceinline__ float bf_hi(unsigned w) { return __uint_as_float(w & 0xffff0000u); }
;     __device__ __forceinline__ void operator()(f32x4 (&acc)[2][2][4][2], const Unit& u, int wr, int wc, int fr, int fq) const {
;     ...
;                     if (pn < 4) {
;                         const u32x4 gb = *(const u32x4*)(GB + ro + bj * HALF);
;                         const f32x4 b0 = {bf_lo(gb.x), bf_hi(gb.x), bf_lo(gb.y), bf_hi(gb.y)}, b1 = {bf_lo(gb.z), bf_hi(gb.z), bf_lo(gb.w), bf_hi(gb.w)};
; #pragma unroll
;                         for (int i = 0; i < 4; ++i) { acc[ai][bj][m][0][i] *= b0[i] * __builtin_amdgcn_rcpf(a0[i]); acc[ai][bj][m][1][i] *= b1[i] * __builtin_amdgcn_rcpf(a1[i]); }
.LBB0_610:
	s_andn2_b64 vcc, exec, s[38:39]
	s_cbranch_vccnz .LBB0_612
	v_rcp_f32_e32 v148, v148
	v_rcp_f32_e32 v146, v146
	v_rcp_f32_e32 v149, v149
	v_rcp_f32_e32 v147, v147
	v_rcp_f32_e32 v140, v140
	v_rcp_f32_e32 v138, v138
	v_rcp_f32_e32 v141, v141
	v_rcp_f32_e32 v139, v139
	s_waitcnt vmcnt(0)
	v_mov_b32_e32 v142, v238
	v_mov_b32_e32 v143, v239
	v_mov_b32_e32 v144, v240
	v_mov_b32_e32 v145, v241
	v_lshlrev_b32_e32 v150, 16, v142
	v_and_b32_e32 v151, 0xffff0000, v142
	v_lshlrev_b32_e32 v152, 16, v144
	v_and_b32_e32 v153, 0xffff0000, v144
	v_lshlrev_b32_e32 v142, 16, v143
	v_and_b32_e32 v143, 0xffff0000, v143
	v_lshlrev_b32_e32 v144, 16, v145
	v_and_b32_e32 v145, 0xffff0000, v145
	v_pk_mul_f32 v[148:149], v[148:149], v[150:151]
	v_pk_mul_f32 v[146:147], v[146:147], v[152:153]
	v_pk_mul_f32 v[140:141], v[140:141], v[142:143]
	v_pk_mul_f32 v[138:139], v[138:139], v[144:145]
	v_pk_mul_f32 v[78:79], v[78:79], v[148:149]
	v_pk_mul_f32 v[74:75], v[74:75], v[146:147]
	v_pk_mul_f32 v[80:81], v[80:81], v[140:141]
	v_pk_mul_f32 v[76:77], v[76:77], v[138:139]

; __device__ __forceinline__ float bf_lo(unsigned w) { return __uint_as_float(w << 16); }
; __device__ __forceinline__ float bf_hi(unsigned w) { return __uint_as_float(w & 0xffff0000u); }
;     __device__ __forceinline__ void operator()(f32x4 (&acc)[2][2][4][2], const Unit& u, int wr, int wc, int fr, int fq) const {
;     ...
;                     if (pn < 4) {
;                         const u32x4 gb = *(const u32x4*)(GB + ro + bj * HALF);
;                         const f32x4 b0 = {bf_lo(gb.x), bf_hi(gb.x), bf_lo(gb.y), bf_hi(gb.y)}, b1 = {bf_lo(gb.z), bf_hi(gb.z), bf_lo(gb.w), bf_hi(gb.w)};
; #pragma unroll
;                         for (int i = 0; i < 4; ++i) { acc[ai][bj][m][0][i] *= b0[i] * __builtin_amdgcn_rcpf(a0[i]); acc[ai][bj][m][1][i] *= b1[i] * __builtin_amdgcn_rcpf(a1[i]); }
.LBB0_614:
	s_andn2_b64 vcc, exec, s[38:39]
	v_lshl_add_u64 v[136:137], v[146:147], 1, s[16:17]
	s_cbranch_vccnz .LBB0_616
	v_rcp_f32_e32 v144, v144
	v_rcp_f32_e32 v142, v142
	v_rcp_f32_e32 v145, v145
	v_rcp_f32_e32 v143, v143
	v_rcp_f32_e32 v140, v140
	v_rcp_f32_e32 v138, v138
	v_rcp_f32_e32 v141, v141
	v_rcp_f32_e32 v139, v139
	s_waitcnt vmcnt(0)
	v_mov_b32_e32 v146, v242
	v_mov_b32_e32 v147, v243
	v_mov_b32_e32 v148, v244
	v_mov_b32_e32 v149, v245
	v_lshlrev_b32_e32 v150, 16, v146
	v_and_b32_e32 v151, 0xffff0000, v146
	v_lshlrev_b32_e32 v152, 16, v148
	v_and_b32_e32 v153, 0xffff0000, v148
	v_lshlrev_b32_e32 v146, 16, v147
	v_and_b32_e32 v147, 0xffff0000, v147
	v_lshlrev_b32_e32 v148, 16, v149
	v_and_b32_e32 v149, 0xffff0000, v149
	v_pk_mul_f32 v[144:145], v[144:145], v[150:151]
	v_pk_mul_f32 v[142:143], v[142:143], v[152:153]
	v_pk_mul_f32 v[140:141], v[140:141], v[146:147]
	v_pk_mul_f32 v[138:139], v[138:139], v[148:149]
	v_pk_mul_f32 v[102:103], v[102:103], v[144:145]
	v_pk_mul_f32 v[98:99], v[98:99], v[142:143]
	v_pk_mul_f32 v[104:105], v[104:105], v[140:141]
	v_pk_mul_f32 v[100:101], v[100:101], v[138:139]

; __device__ __forceinline__ float bf_lo(unsigned w) { return __uint_as_float(w << 16); }
; __device__ __forceinline__ float bf_hi(unsigned w) { return __uint_as_float(w & 0xffff0000u); }
; __device__ __forceinline__ u32x4 pack8(f32x4 v0, f32x4 v1) { u32x4 w; w.x = cvt_pk_bf16(v0[0], v0[1]); w.y = cvt_pk_bf16(v0[2], v0[3]); w.z = cvt_pk_bf16(v1[0], v1[1]); w.w = cvt_pk_bf16(v1[2], v1[3]); return w; }
;     __device__ __forceinline__ void operator()(f32x4 (&acc)[2][2][4][2], const Unit& u, int wr, int wc, int fr, int fq) const {
;     ...
;         for (int ai = 0; ai < 2; ++ai) {
;             u32x4 gaq[4][2];
; #pragma unroll
;             for (int m = 0; m < 4; ++m)
; #pragma unroll
;                 for (int bj = 0; bj < 2; ++bj) gaq[m][bj] = *(const u32x4*)(GA + (size_t)(row0 + ai * HALF + m * 16) * 1024 + co + bj * HALF);
; #pragma unroll
;             for (int m = 0; m < 4; ++m) {
;                 const size_t ro = (size_t)(row0 + ai * HALF + m * 16) * 1024 + co;
; #pragma unroll
;                 for (int bj = 0; bj < 2; ++bj) {
;                     const u32x4 ga = gaq[m][bj];
;                     f32x4 a0 = {bf_lo(ga.x), bf_hi(ga.x), bf_lo(ga.y), bf_hi(ga.y)}, a1 = {bf_lo(ga.z), bf_hi(ga.z), bf_lo(ga.w), bf_hi(ga.w)};
; #pragma unroll
;                     for (int i = 0; i < 4; ++i) { a0[i] = fmaxf(a0[i], 1e-20f); a1[i] = fmaxf(a1[i], 1e-20f); }
;                     if (pn < 4) {
;                         const u32x4 gb = *(const u32x4*)(GB + ro + bj * HALF);
;                         const f32x4 b0 = {bf_lo(gb.x), bf_hi(gb.x), bf_lo(gb.y), bf_hi(gb.y)}, b1 = {bf_lo(gb.z), bf_hi(gb.z), bf_lo(gb.w), bf_hi(gb.w)};
; #pragma unroll
;                         for (int i = 0; i < 4; ++i) { acc[ai][bj][m][0][i] *= b0[i] * __builtin_amdgcn_rcpf(a0[i]); acc[ai][bj][m][1][i] *= b1[i] * __builtin_amdgcn_rcpf(a1[i]); }
;                     } else {
;                         *(u32x4*)(MG + ro + bj * HALF) = pack8(acc[ai][bj][m][0] * a0, acc[ai][bj][m][1] * a1);
.LBB0_618:
	s_andn2_b64 vcc, exec, s[38:39]
	s_cbranch_vccnz .LBB0_620
	v_rcp_f32_e32 v140, v140
	v_rcp_f32_e32 v138, v138
	v_rcp_f32_e32 v141, v141
	v_rcp_f32_e32 v139, v139
	v_rcp_f32_e32 v132, v132
	v_rcp_f32_e32 v130, v130
	v_rcp_f32_e32 v133, v133
	v_rcp_f32_e32 v131, v131
	s_waitcnt vmcnt(0)
	v_mov_b32_e32 v134, v248
	v_mov_b32_e32 v135, v249
	v_mov_b32_e32 v136, v250
	v_mov_b32_e32 v137, v251
	v_lshlrev_b32_e32 v142, 16, v134
	v_and_b32_e32 v143, 0xffff0000, v134
	v_lshlrev_b32_e32 v144, 16, v136
	v_and_b32_e32 v145, 0xffff0000, v136
	v_lshlrev_b32_e32 v134, 16, v135
	v_and_b32_e32 v135, 0xffff0000, v135
	v_lshlrev_b32_e32 v136, 16, v137
	v_and_b32_e32 v137, 0xffff0000, v137
	v_pk_mul_f32 v[140:141], v[140:141], v[142:143]
	v_pk_mul_f32 v[138:139], v[138:139], v[144:145]
	v_pk_mul_f32 v[132:133], v[132:133], v[134:135]
	v_pk_mul_f32 v[130:131], v[130:131], v[136:137]
	v_pk_mul_f32 v[70:71], v[70:71], v[140:141]
	v_pk_mul_f32 v[66:67], v[66:67], v[138:139]
	v_pk_mul_f32 v[72:73], v[72:73], v[132:133]
	v_pk_mul_f32 v[68:69], v[68:69], v[130:131]
.LBB0_620:
	v_add_u32_e32 v186, 0x80, v180
	v_add_u32_e32 v184, 0x90, v180
	v_add_u32_e32 v182, 0xa0, v180
	v_ashrrev_i32_e32 v187, 31, v186
	v_add_u32_e32 v180, 0xb0, v180
	v_ashrrev_i32_e32 v185, 31, v184
	v_ashrrev_i32_e32 v183, 31, v182
	v_lshlrev_b64 v[130:131], 11, v[186:187]
	v_ashrrev_i32_e32 v181, 31, v180
	v_lshlrev_b64 v[132:133], 11, v[184:185]
	v_lshlrev_b64 v[134:135], 11, v[182:183]
	v_lshl_add_u64 v[130:131], v[178:179], 0, v[130:131]
	v_lshlrev_b64 v[136:137], 11, v[180:181]
	v_lshl_add_u64 v[132:133], v[178:179], 0, v[132:133]
	v_lshl_add_u64 v[134:135], v[178:179], 0, v[134:135]
	global_load_dwordx4 v[188:191], v[130:131], off
	v_lshl_add_u64 v[178:179], v[178:179], 0, v[136:137]
	global_load_dwordx4 v[154:157], v[130:131], off offset:256
	global_load_dwordx4 v[150:153], v[132:133], off
	global_load_dwordx4 v[146:149], v[132:133], off offset:256
	global_load_dwordx4 v[142:145], v[134:135], off
	global_load_dwordx4 v[138:141], v[134:135], off offset:256
	s_cmp_gt_i32 s50, 3
	s_cbranch_scc1 .Lgbskip_0_1
	s_sub_u32 s98, s16, s14
	s_subb_u32 s99, s17, s15
	v_lshl_add_u64 v[252:253], v[130:131], 0, s[98:99]
	global_load_dwordx4 v[218:221], v[252:253], off
	global_load_dwordx4 v[222:225], v[252:253], off offset:256
	v_lshl_add_u64 v[252:253], v[132:133], 0, s[98:99]
	global_load_dwordx4 v[226:229], v[252:253], off
	global_load_dwordx4 v[230:233], v[252:253], off offset:256
	v_lshl_add_u64 v[252:253], v[134:135], 0, s[98:99]
	global_load_dwordx4 v[234:237], v[252:253], off
	global_load_dwordx4 v[238:241], v[252:253], off offset:256
	v_lshl_add_u64 v[252:253], v[178:179], 0, s[98:99]
	global_load_dwordx4 v[242:245], v[252:253], off
	global_load_dwordx4 v[248:251], v[252:253], off offset:256
.Lgbskip_0_1:
	s_nop 0
	global_load_dwordx4 v[134:137], v[178:179], off
	global_load_dwordx4 v[130:133], v[178:179], off offset:256
	v_lshlrev_b64 v[186:187], 10, v[186:187]
	v_or_b32_e32 v186, v186, v209
	s_mov_b64 s[38:39], -1
	s_and_b64 vcc, exec, s[8:9]
	s_waitcnt vmcnt(7)
	v_lshlrev_b32_e32 v166, 16, v188
	v_and_b32_e32 v178, 0xffff0000, v188
	v_lshlrev_b32_e32 v179, 16, v189
	v_and_b32_e32 v188, 0xffff0000, v189
	v_lshlrev_b32_e32 v189, 16, v190
	v_and_b32_e32 v190, 0xffff0000, v190
	v_lshlrev_b32_e32 v192, 16, v191
	v_and_b32_e32 v191, 0xffff0000, v191
	v_max_f32_e32 v166, v166, v166
	v_max_f32_e32 v189, v189, v189
	v_max_f32_e32 v178, v178, v178
	v_max_f32_e32 v190, v190, v190
	v_max_f32_e32 v179, v179, v179
	v_max_f32_e32 v196, v192, v192
	v_max_f32_e32 v197, v188, v188
	v_max_f32_e32 v198, v191, v191
	v_max_f32_e32 v194, 0x1e3ce508, v166
	v_max_f32_e32 v192, 0x1e3ce508, v189
	v_max_f32_e32 v195, 0x1e3ce508, v178
	v_max_f32_e32 v193, 0x1e3ce508, v190
	v_max_f32_e32 v190, 0x1e3ce508, v179
	v_max_f32_e32 v188, 0x1e3ce508, v196
	v_max_f32_e32 v191, 0x1e3ce508, v197
	v_max_f32_e32 v189, 0x1e3ce508, v198
	v_lshl_add_u64 v[178:179], v[186:187], 1, s[12:13]
	s_cbranch_vccnz .LBB0_622
	v_pk_mul_f32 v[198:199], v[64:65], v[190:191]
	v_pk_mul_f32 v[196:197], v[62:63], v[194:195]
	s_mov_b64 s[38:39], 0
	v_pk_mul_f32 v[210:211], v[60:61], v[188:189]
	v_pk_mul_f32 v[212:213], v[58:59], v[192:193]
	v_cvt_pk_bf16_f32 v196, v196, v197
	v_cvt_pk_bf16_f32 v197, v198, v199
	s_nop 0
	v_cvt_pk_bf16_f32 v198, v212, v213
	v_cvt_pk_bf16_f32 v199, v210, v211
	global_store_dwordx4 v[178:179], v[196:199], off
.LBB0_622:
	s_andn2_b64 vcc, exec, s[38:39]
	v_lshl_add_u64 v[186:187], v[186:187], 1, s[16:17]
	s_cbranch_vccnz .LBB0_624
	v_rcp_f32_e32 v194, v194
	v_rcp_f32_e32 v192, v192
	v_rcp_f32_e32 v195, v195
	v_rcp_f32_e32 v193, v193
	v_rcp_f32_e32 v190, v190
	v_rcp_f32_e32 v188, v188
	v_rcp_f32_e32 v191, v191
	v_rcp_f32_e32 v189, v189
	s_waitcnt vmcnt(0)
	v_mov_b32_e32 v196, v218
	v_mov_b32_e32 v197, v219
	v_mov_b32_e32 v198, v220
	v_mov_b32_e32 v199, v221
	v_lshlrev_b32_e32 v210, 16, v196
	v_and_b32_e32 v211, 0xffff0000, v196
	v_lshlrev_b32_e32 v212, 16, v198
	v_and_b32_e32 v213, 0xffff0000, v198
	v_lshlrev_b32_e32 v196, 16, v197
	v_and_b32_e32 v197, 0xffff0000, v197
	v_lshlrev_b32_e32 v198, 16, v199
	v_and_b32_e32 v199, 0xffff0000, v199
	v_pk_mul_f32 v[194:195], v[194:195], v[210:211]
	v_pk_mul_f32 v[192:193], v[192:193], v[212:213]
	v_pk_mul_f32 v[190:191], v[190:191], v[196:197]
	v_pk_mul_f32 v[188:189], v[188:189], v[198:199]
	v_pk_mul_f32 v[62:63], v[62:63], v[194:195]
	v_pk_mul_f32 v[58:59], v[58:59], v[192:193]
	v_pk_mul_f32 v[64:65], v[64:65], v[190:191]
	v_pk_mul_f32 v[60:61], v[60:61], v[188:189]

; __device__ __forceinline__ float bf_lo(unsigned w) { return __uint_as_float(w << 16); }
; __device__ __forceinline__ float bf_hi(unsigned w) { return __uint_as_float(w & 0xffff0000u); }
;     __device__ __forceinline__ void operator()(f32x4 (&acc)[2][2][4][2], const Unit& u, int wr, int wc, int fr, int fq) const {
;     ...
;                     if (pn < 4) {
;                         const u32x4 gb = *(const u32x4*)(GB + ro + bj * HALF);
;                         const f32x4 b0 = {bf_lo(gb.x), bf_hi(gb.x), bf_lo(gb.y), bf_hi(gb.y)}, b1 = {bf_lo(gb.z), bf_hi(gb.z), bf_lo(gb.w), bf_hi(gb.w)};
; #pragma unroll
;                         for (int i = 0; i < 4; ++i) { acc[ai][bj][m][0][i] *= b0[i] * __builtin_amdgcn_rcpf(a0[i]); acc[ai][bj][m][1][i] *= b1[i] * __builtin_amdgcn_rcpf(a1[i]); }
.LBB0_626:
	s_andn2_b64 vcc, exec, s[38:39]
	s_cbranch_vccnz .LBB0_628
	v_rcp_f32_e32 v178, v190
	v_rcp_f32_e32 v186, v188
	v_rcp_f32_e32 v179, v191
	v_rcp_f32_e32 v187, v189
	v_rcp_f32_e32 v156, v156
	v_rcp_f32_e32 v154, v154
	v_rcp_f32_e32 v157, v157
	v_rcp_f32_e32 v155, v155
	s_waitcnt vmcnt(0)
	v_mov_b32_e32 v192, v222
	v_mov_b32_e32 v193, v223
	v_mov_b32_e32 v194, v224
	v_mov_b32_e32 v195, v225
	v_lshlrev_b32_e32 v188, 16, v192
	v_and_b32_e32 v189, 0xffff0000, v192
	v_lshlrev_b32_e32 v190, 16, v194
	v_and_b32_e32 v191, 0xffff0000, v194
	v_lshlrev_b32_e32 v192, 16, v193
	v_and_b32_e32 v193, 0xffff0000, v193
	v_lshlrev_b32_e32 v194, 16, v195
	v_and_b32_e32 v195, 0xffff0000, v195
	v_pk_mul_f32 v[178:179], v[178:179], v[188:189]
	v_pk_mul_f32 v[186:187], v[186:187], v[190:191]
	v_pk_mul_f32 v[156:157], v[156:157], v[192:193]
	v_pk_mul_f32 v[154:155], v[154:155], v[194:195]
	v_pk_mul_f32 v[30:31], v[30:31], v[178:179]
	v_pk_mul_f32 v[26:27], v[26:27], v[186:187]
	v_pk_mul_f32 v[32:33], v[32:33], v[156:157]
	v_pk_mul_f32 v[28:29], v[28:29], v[154:155]

; __device__ __forceinline__ float bf_lo(unsigned w) { return __uint_as_float(w << 16); }
; __device__ __forceinline__ float bf_hi(unsigned w) { return __uint_as_float(w & 0xffff0000u); }
;     __device__ __forceinline__ void operator()(f32x4 (&acc)[2][2][4][2], const Unit& u, int wr, int wc, int fr, int fq) const {
;     ...
;                     if (pn < 4) {
;                         const u32x4 gb = *(const u32x4*)(GB + ro + bj * HALF);
;                         const f32x4 b0 = {bf_lo(gb.x), bf_hi(gb.x), bf_lo(gb.y), bf_hi(gb.y)}, b1 = {bf_lo(gb.z), bf_hi(gb.z), bf_lo(gb.w), bf_hi(gb.w)};
; #pragma unroll
;                         for (int i = 0; i < 4; ++i) { acc[ai][bj][m][0][i] *= b0[i] * __builtin_amdgcn_rcpf(a0[i]); acc[ai][bj][m][1][i] *= b1[i] * __builtin_amdgcn_rcpf(a1[i]); }
.LBB0_630:
	s_andn2_b64 vcc, exec, s[38:39]
	v_lshl_add_u64 v[152:153], v[186:187], 1, s[16:17]
	s_cbranch_vccnz .LBB0_632
	v_rcp_f32_e32 v184, v184
	v_rcp_f32_e32 v178, v178
	v_rcp_f32_e32 v185, v185
	v_rcp_f32_e32 v179, v179
	v_rcp_f32_e32 v156, v156
	v_rcp_f32_e32 v154, v154
	v_rcp_f32_e32 v157, v157
	v_rcp_f32_e32 v155, v155
	s_waitcnt vmcnt(0)
	v_mov_b32_e32 v186, v226
	v_mov_b32_e32 v187, v227
	v_mov_b32_e32 v188, v228
	v_mov_b32_e32 v189, v229
	v_lshlrev_b32_e32 v190, 16, v186
	v_and_b32_e32 v191, 0xffff0000, v186
	v_lshlrev_b32_e32 v192, 16, v188
	v_and_b32_e32 v193, 0xffff0000, v188
	v_lshlrev_b32_e32 v186, 16, v187
	v_and_b32_e32 v187, 0xffff0000, v187
	v_lshlrev_b32_e32 v188, 16, v189
	v_and_b32_e32 v189, 0xffff0000, v189
	v_pk_mul_f32 v[184:185], v[184:185], v[190:191]
	v_pk_mul_f32 v[178:179], v[178:179], v[192:193]
	v_pk_mul_f32 v[156:157], v[156:157], v[186:187]
	v_pk_mul_f32 v[154:155], v[154:155], v[188:189]
	v_pk_mul_f32 v[54:55], v[54:55], v[184:185]
	v_pk_mul_f32 v[50:51], v[50:51], v[178:179]
	v_pk_mul_f32 v[56:57], v[56:57], v[156:157]
	v_pk_mul_f32 v[52:53], v[52:53], v[154:155]

; __device__ __forceinline__ float bf_lo(unsigned w) { return __uint_as_float(w << 16); }
; __device__ __forceinline__ float bf_hi(unsigned w) { return __uint_as_float(w & 0xffff0000u); }
;     __device__ __forceinline__ void operator()(f32x4 (&acc)[2][2][4][2], const Unit& u, int wr, int wc, int fr, int fq) const {
;     ...
;                     if (pn < 4) {
;                         const u32x4 gb = *(const u32x4*)(GB + ro + bj * HALF);
;                         const f32x4 b0 = {bf_lo(gb.x), bf_hi(gb.x), bf_lo(gb.y), bf_hi(gb.y)}, b1 = {bf_lo(gb.z), bf_hi(gb.z), bf_lo(gb.w), bf_hi(gb.w)};
; #pragma unroll
;                         for (int i = 0; i < 4; ++i) { acc[ai][bj][m][0][i] *= b0[i] * __builtin_amdgcn_rcpf(a0[i]); acc[ai][bj][m][1][i] *= b1[i] * __builtin_amdgcn_rcpf(a1[i]); }
.LBB0_634:
	s_andn2_b64 vcc, exec, s[38:39]
	s_cbranch_vccnz .LBB0_636
	v_rcp_f32_e32 v156, v156
	v_rcp_f32_e32 v154, v154
	v_rcp_f32_e32 v157, v157
	v_rcp_f32_e32 v155, v155
	v_rcp_f32_e32 v148, v148
	v_rcp_f32_e32 v146, v146
	v_rcp_f32_e32 v149, v149
	v_rcp_f32_e32 v147, v147
	s_waitcnt vmcnt(0)
	v_mov_b32_e32 v150, v230
	v_mov_b32_e32 v151, v231
	v_mov_b32_e32 v152, v232
	v_mov_b32_e32 v153, v233
	v_lshlrev_b32_e32 v178, 16, v150
	v_and_b32_e32 v179, 0xffff0000, v150
	v_lshlrev_b32_e32 v184, 16, v152
	v_and_b32_e32 v185, 0xffff0000, v152
	v_lshlrev_b32_e32 v150, 16, v151
	v_and_b32_e32 v151, 0xffff0000, v151
	v_lshlrev_b32_e32 v152, 16, v153
	v_and_b32_e32 v153, 0xffff0000, v153
	v_pk_mul_f32 v[156:157], v[156:157], v[178:179]
	v_pk_mul_f32 v[154:155], v[154:155], v[184:185]
	v_pk_mul_f32 v[148:149], v[148:149], v[150:151]
	v_pk_mul_f32 v[146:147], v[146:147], v[152:153]
	v_pk_mul_f32 v[22:23], v[22:23], v[156:157]
	v_pk_mul_f32 v[18:19], v[18:19], v[154:155]
	v_pk_mul_f32 v[24:25], v[24:25], v[148:149]
	v_pk_mul_f32 v[20:21], v[20:21], v[146:147]

; __device__ __forceinline__ float bf_lo(unsigned w) { return __uint_as_float(w << 16); }
; __device__ __forceinline__ float bf_hi(unsigned w) { return __uint_as_float(w & 0xffff0000u); }
;     __device__ __forceinline__ void operator()(f32x4 (&acc)[2][2][4][2], const Unit& u, int wr, int wc, int fr, int fq) const {
;     ...
;                     if (pn < 4) {
;                         const u32x4 gb = *(const u32x4*)(GB + ro + bj * HALF);
;                         const f32x4 b0 = {bf_lo(gb.x), bf_hi(gb.x), bf_lo(gb.y), bf_hi(gb.y)}, b1 = {bf_lo(gb.z), bf_hi(gb.z), bf_lo(gb.w), bf_hi(gb.w)};
; #pragma unroll
;                         for (int i = 0; i < 4; ++i) { acc[ai][bj][m][0][i] *= b0[i] * __builtin_amdgcn_rcpf(a0[i]); acc[ai][bj][m][1][i] *= b1[i] * __builtin_amdgcn_rcpf(a1[i]); }
.LBB0_638:
	s_andn2_b64 vcc, exec, s[38:39]
	v_lshl_add_u64 v[144:145], v[154:155], 1, s[16:17]
	s_cbranch_vccnz .LBB0_640
	v_rcp_f32_e32 v152, v152
	v_rcp_f32_e32 v150, v150
	v_rcp_f32_e32 v153, v153
	v_rcp_f32_e32 v151, v151
	v_rcp_f32_e32 v148, v148
	v_rcp_f32_e32 v146, v146
	v_rcp_f32_e32 v149, v149
	v_rcp_f32_e32 v147, v147
	s_waitcnt vmcnt(0)
	v_mov_b32_e32 v154, v234
	v_mov_b32_e32 v155, v235
	v_mov_b32_e32 v156, v236
	v_mov_b32_e32 v157, v237
	v_lshlrev_b32_e32 v178, 16, v154
	v_and_b32_e32 v179, 0xffff0000, v154
	v_lshlrev_b32_e32 v182, 16, v156
	v_and_b32_e32 v183, 0xffff0000, v156
	v_lshlrev_b32_e32 v154, 16, v155
	v_and_b32_e32 v155, 0xffff0000, v155
	v_lshlrev_b32_e32 v156, 16, v157
	v_and_b32_e32 v157, 0xffff0000, v157
	v_pk_mul_f32 v[152:153], v[152:153], v[178:179]
	v_pk_mul_f32 v[150:151], v[150:151], v[182:183]
	v_pk_mul_f32 v[148:149], v[148:149], v[154:155]
	v_pk_mul_f32 v[146:147], v[146:147], v[156:157]
	v_pk_mul_f32 v[46:47], v[46:47], v[152:153]
	v_pk_mul_f32 v[42:43], v[42:43], v[150:151]
	v_pk_mul_f32 v[48:49], v[48:49], v[148:149]
	v_pk_mul_f32 v[44:45], v[44:45], v[146:147]

; __device__ __forceinline__ float bf_lo(unsigned w) { return __uint_as_float(w << 16); }
; __device__ __forceinline__ float bf_hi(unsigned w) { return __uint_as_float(w & 0xffff0000u); }
;     __device__ __forceinline__ void operator()(f32x4 (&acc)[2][2][4][2], const Unit& u, int wr, int wc, int fr, int fq) const {
;     ...
;                     if (pn < 4) {
;                         const u32x4 gb = *(const u32x4*)(GB + ro + bj * HALF);
;                         const f32x4 b0 = {bf_lo(gb.x), bf_hi(gb.x), bf_lo(gb.y), bf_hi(gb.y)}, b1 = {bf_lo(gb.z), bf_hi(gb.z), bf_lo(gb.w), bf_hi(gb.w)};
; #pragma unroll
;                         for (int i = 0; i < 4; ++i) { acc[ai][bj][m][0][i] *= b0[i] * __builtin_amdgcn_rcpf(a0[i]); acc[ai][bj][m][1][i] *= b1[i] * __builtin_amdgcn_rcpf(a1[i]); }
.LBB0_642:
	s_andn2_b64 vcc, exec, s[38:39]
	s_cbranch_vccnz .LBB0_644
	v_rcp_f32_e32 v148, v148
	v_rcp_f32_e32 v146, v146
	v_rcp_f32_e32 v149, v149
	v_rcp_f32_e32 v147, v147
	v_rcp_f32_e32 v140, v140
	v_rcp_f32_e32 v138, v138
	v_rcp_f32_e32 v141, v141
	v_rcp_f32_e32 v139, v139
	s_waitcnt vmcnt(0)
	v_mov_b32_e32 v142, v238
	v_mov_b32_e32 v143, v239
	v_mov_b32_e32 v144, v240
	v_mov_b32_e32 v145, v241
	v_lshlrev_b32_e32 v150, 16, v142
	v_and_b32_e32 v151, 0xffff0000, v142
	v_lshlrev_b32_e32 v152, 16, v144
	v_and_b32_e32 v153, 0xffff0000, v144
	v_lshlrev_b32_e32 v142, 16, v143
	v_and_b32_e32 v143, 0xffff0000, v143
	v_lshlrev_b32_e32 v144, 16, v145
	v_and_b32_e32 v145, 0xffff0000, v145
	v_pk_mul_f32 v[148:149], v[148:149], v[150:151]
	v_pk_mul_f32 v[146:147], v[146:147], v[152:153]
	v_pk_mul_f32 v[140:141], v[140:141], v[142:143]
	v_pk_mul_f32 v[138:139], v[138:139], v[144:145]
	v_pk_mul_f32 v[14:15], v[14:15], v[148:149]
	v_pk_mul_f32 v[10:11], v[10:11], v[146:147]
	v_pk_mul_f32 v[16:17], v[16:17], v[140:141]
	v_pk_mul_f32 v[12:13], v[12:13], v[138:139]

; __device__ __forceinline__ float bf_lo(unsigned w) { return __uint_as_float(w << 16); }
; __device__ __forceinline__ float bf_hi(unsigned w) { return __uint_as_float(w & 0xffff0000u); }
;     __device__ __forceinline__ void operator()(f32x4 (&acc)[2][2][4][2], const Unit& u, int wr, int wc, int fr, int fq) const {
;     ...
;                     if (pn < 4) {
;                         const u32x4 gb = *(const u32x4*)(GB + ro + bj * HALF);
;                         const f32x4 b0 = {bf_lo(gb.x), bf_hi(gb.x), bf_lo(gb.y), bf_hi(gb.y)}, b1 = {bf_lo(gb.z), bf_hi(gb.z), bf_lo(gb.w), bf_hi(gb.w)};
; #pragma unroll
;                         for (int i = 0; i < 4; ++i) { acc[ai][bj][m][0][i] *= b0[i] * __builtin_amdgcn_rcpf(a0[i]); acc[ai][bj][m][1][i] *= b1[i] * __builtin_amdgcn_rcpf(a1[i]); }
.LBB0_646:
	s_andn2_b64 vcc, exec, s[38:39]
	v_lshl_add_u64 v[136:137], v[146:147], 1, s[16:17]
	s_cbranch_vccnz .LBB0_648
	v_rcp_f32_e32 v144, v144
	v_rcp_f32_e32 v142, v142
	v_rcp_f32_e32 v145, v145
	v_rcp_f32_e32 v143, v143
	v_rcp_f32_e32 v140, v140
	v_rcp_f32_e32 v138, v138
	v_rcp_f32_e32 v141, v141
	v_rcp_f32_e32 v139, v139
	s_waitcnt vmcnt(0)
	v_mov_b32_e32 v146, v242
	v_mov_b32_e32 v147, v243
	v_mov_b32_e32 v148, v244
	v_mov_b32_e32 v149, v245
	v_lshlrev_b32_e32 v150, 16, v146
	v_and_b32_e32 v151, 0xffff0000, v146
	v_lshlrev_b32_e32 v152, 16, v148
	v_and_b32_e32 v153, 0xffff0000, v148
	v_lshlrev_b32_e32 v146, 16, v147
	v_and_b32_e32 v147, 0xffff0000, v147
	v_lshlrev_b32_e32 v148, 16, v149
	v_and_b32_e32 v149, 0xffff0000, v149
	v_pk_mul_f32 v[144:145], v[144:145], v[150:151]
	v_pk_mul_f32 v[142:143], v[142:143], v[152:153]
	v_pk_mul_f32 v[140:141], v[140:141], v[146:147]
	v_pk_mul_f32 v[138:139], v[138:139], v[148:149]
	v_pk_mul_f32 v[38:39], v[38:39], v[144:145]
	v_pk_mul_f32 v[34:35], v[34:35], v[142:143]
	v_pk_mul_f32 v[40:41], v[40:41], v[140:141]
	v_pk_mul_f32 v[36:37], v[36:37], v[138:139]

; __device__ __forceinline__ float bf_lo(unsigned w) { return __uint_as_float(w << 16); }
; __device__ __forceinline__ float bf_hi(unsigned w) { return __uint_as_float(w & 0xffff0000u); }
;     __device__ __forceinline__ void operator()(f32x4 (&acc)[2][2][4][2], const Unit& u, int wr, int wc, int fr, int fq) const {
;     ...
;                     if (pn < 4) {
;                         const u32x4 gb = *(const u32x4*)(GB + ro + bj * HALF);
;                         const f32x4 b0 = {bf_lo(gb.x), bf_hi(gb.x), bf_lo(gb.y), bf_hi(gb.y)}, b1 = {bf_lo(gb.z), bf_hi(gb.z), bf_lo(gb.w), bf_hi(gb.w)};
; #pragma unroll
;                         for (int i = 0; i < 4; ++i) { acc[ai][bj][m][0][i] *= b0[i] * __builtin_amdgcn_rcpf(a0[i]); acc[ai][bj][m][1][i] *= b1[i] * __builtin_amdgcn_rcpf(a1[i]); }
.LBB0_652:
	v_rcp_f32_e32 v140, v140
	v_rcp_f32_e32 v138, v138
	v_rcp_f32_e32 v141, v141
	v_rcp_f32_e32 v139, v139
	v_rcp_f32_e32 v132, v132
	v_rcp_f32_e32 v130, v130
	v_rcp_f32_e32 v133, v133
	v_rcp_f32_e32 v131, v131
	s_waitcnt vmcnt(0)
	v_mov_b32_e32 v134, v248
	v_mov_b32_e32 v135, v249
	v_mov_b32_e32 v136, v250
	v_mov_b32_e32 v137, v251
	v_lshlrev_b32_e32 v142, 16, v134
	v_and_b32_e32 v143, 0xffff0000, v134
	v_lshlrev_b32_e32 v144, 16, v136
	v_and_b32_e32 v145, 0xffff0000, v136
	v_lshlrev_b32_e32 v134, 16, v135
	v_and_b32_e32 v135, 0xffff0000, v135
	v_lshlrev_b32_e32 v136, 16, v137
	v_and_b32_e32 v137, 0xffff0000, v137
	v_pk_mul_f32 v[140:141], v[140:141], v[142:143]
	v_pk_mul_f32 v[138:139], v[138:139], v[144:145]
	v_pk_mul_f32 v[132:133], v[132:133], v[134:135]
	v_pk_mul_f32 v[130:131], v[130:131], v[136:137]
	v_pk_mul_f32 v[6:7], v[6:7], v[140:141]
	v_pk_mul_f32 v[2:3], v[2:3], v[138:139]
	v_pk_mul_f32 v[8:9], v[8:9], v[132:133]
	v_pk_mul_f32 v[4:5], v[4:5], v[130:131]
	s_and_b64 vcc, exec, s[6:7]
	s_mov_b64 s[6:7], -1
	s_cbranch_vccnz .LBB0_575

; __device__ __forceinline__ float bf_lo(unsigned w) { return __uint_as_float(w << 16); }
; __device__ __forceinline__ float bf_hi(unsigned w) { return __uint_as_float(w & 0xffff0000u); }
;     __device__ __forceinline__ void fused(f32x4 (&acc)[2][2][4][2], const Unit& u, int wr, int wc, int fr, int fq, PG8_LAS unsigned char* lds, int wid, int lane) const {
;     ...
;         const int col0 = u.pn * BM + wc * 32 + 8 * fq, b = u.pm >> 4;
;         {
;             f32x4 gv[2][2];
; #pragma unroll
;             for (int bj = 0; bj < 2; ++bj)
; #pragma unroll
;                 for (int n = 0; n < 2; ++n) gv[bj][n] = *(const f32x4*)(g + (size_t)b * 6144 + col0 + bj * HALF + 4 * n);
; #pragma unroll
;             for (int ai = 0; ai < 2; ++ai)
; #pragma unroll
;                 for (int m = 0; m < 4; ++m) { const int r = ai * HALF + wr * 64 + m * 16 + fr; const size_t off = (size_t)(u.pm * BM + r) * 1024 + col0;
; #pragma unroll
;                     for (int bj = 0; bj < 2; ++bj) { f32x4 b0, b1;
;                         if (XIN_BF16) { const u32x4 w = *(const u32x4*)((const bf16_t*)xin + off + bj * HALF); b0 = (f32x4){bf_lo(w.x), bf_hi(w.x), bf_lo(w.y), bf_hi(w.y)}; b1 = (f32x4){bf_lo(w.z), bf_hi(w.z), bf_lo(w.w), bf_hi(w.w)}; }
;                         else { b0 = *(const f32x4*)((const float*)xin + off + bj * HALF); b1 = *(const f32x4*)((const float*)xin + off + bj * HALF + 4); }
;                         acc[ai][bj][m][0] = b0 + gv[bj][0] * acc[ai][bj][m][0]; acc[ai][bj][m][1] = b1 + gv[bj][1] * acc[ai][bj][m][1]; }
.LBB0_942:
	s_add_u32 s6, s12, 0xc800000
	s_addc_u32 s7, s13, 0
	s_lshl_b32 s8, s25, 5
	s_lshl_b32 s9, s18, 8
	v_lshrrev_b32_e32 v130, 1, v168
	s_or_b32 s8, s9, s8
	v_and_or_b32 v156, v130, 24, s8
	s_ashr_i32 s8, s5, 4
	s_mul_i32 s35, s8, 0x6000
	s_mul_hi_i32 s34, s8, 0x6000
	s_add_u32 s8, s12, s35
	s_addc_u32 s9, s13, s34
	s_lshl_b32 s30, s5, 8
	v_add_u32_e32 v164, s30, v166
	v_ashrrev_i32_e32 v165, 31, v164
	v_ashrrev_i32_e32 v157, 31, v156
	v_lshlrev_b64 v[150:151], 11, v[164:165]
	v_lshl_add_u64 v[130:131], s[6:7], 0, v[150:151]
	v_lshlrev_b64 v[146:147], 1, v[156:157]
	v_lshl_add_u64 v[130:131], v[130:131], 0, v[146:147]
	v_lshl_add_u64 v[132:133], v[156:157], 2, s[8:9]
	s_movk_i32 s10, 0x5000
	s_barrier
	s_mov_b64 s[98:99], 0x8000
	v_lshl_add_u64 v[198:199], v[130:131], 0, s[98:99]
	global_load_dwordx4 v[206:209], v[198:199], off
	global_load_dwordx4 v[210:213], v[198:199], off offset:256
	s_mov_b64 s[98:99], 0x10000
	v_lshl_add_u64 v[198:199], v[130:131], 0, s[98:99]
	global_load_dwordx4 v[214:217], v[198:199], off
	global_load_dwordx4 v[218:221], v[198:199], off offset:256
	s_mov_b64 s[98:99], 0x18000
	v_lshl_add_u64 v[198:199], v[130:131], 0, s[98:99]
	global_load_dwordx4 v[222:225], v[198:199], off
	global_load_dwordx4 v[226:229], v[198:199], off offset:256
	s_mov_b64 s[98:99], 0x40000
	v_lshl_add_u64 v[198:199], v[130:131], 0, s[98:99]
	global_load_dwordx4 v[230:233], v[198:199], off
	global_load_dwordx4 v[234:237], v[198:199], off offset:256
	s_mov_b64 s[98:99], 0x48000
	v_lshl_add_u64 v[198:199], v[130:131], 0, s[98:99]
	global_load_dwordx4 v[238:241], v[198:199], off
	global_load_dwordx4 v[242:245], v[198:199], off offset:256
	s_mov_b64 s[98:99], 0x50000
	v_lshl_add_u64 v[198:199], v[130:131], 0, s[98:99]
	global_load_dwordx4 v[248:251], v[198:199], off
	global_load_dwordx4 v[252:255], v[198:199], off offset:256
	global_load_dwordx4 v[152:155], v[130:131], off
	global_load_dwordx4 v[158:161], v[130:131], off offset:256
	v_add_co_u32_e32 v130, vcc, s10, v132
	s_mov_b64 s[8:9], 0x5000
	s_nop 0
	v_addc_co_u32_e32 v131, vcc, 0, v133, vcc
	global_load_dwordx4 v[138:141], v[130:131], off
	v_lshl_add_u64 v[130:131], v[132:133], 0, s[8:9]
	global_load_dwordx4 v[142:145], v[130:131], off offset:16
	global_load_dwordx4 v[134:137], v[130:131], off offset:512
	s_nop 0
	global_load_dwordx4 v[130:133], v[130:131], off offset:528
	v_add_u32_e32 v148, 16, v164
	v_ashrrev_i32_e32 v149, 31, v148
	v_lshlrev_b64 v[148:149], 11, v[148:149]
	v_lshl_add_u64 v[162:163], s[6:7], 0, v[148:149]
	v_lshl_add_u64 v[162:163], v[162:163], 0, v[146:147]
	v_mbcnt_hi_u32_b32 v173, -1, v1
	v_and_b32_e32 v169, 64, v173
	v_xor_b32_e32 v165, 16, v173
	v_add_u32_e32 v194, 64, v169
	v_cmp_lt_i32_e32 vcc, v165, v194
	s_waitcnt vmcnt(0)
	v_lshlrev_b32_e32 v170, 16, v152
	v_and_b32_e32 v171, 0xffff0000, v152
	v_lshlrev_b32_e32 v152, 16, v153
	v_and_b32_e32 v153, 0xffff0000, v153
	v_lshlrev_b32_e32 v174, 16, v154
	v_and_b32_e32 v175, 0xffff0000, v154
	v_lshlrev_b32_e32 v154, 16, v155
	v_and_b32_e32 v155, 0xffff0000, v155
	v_lshlrev_b32_e32 v176, 16, v158
	v_and_b32_e32 v177, 0xffff0000, v158
	v_lshlrev_b32_e32 v158, 16, v159
	v_and_b32_e32 v159, 0xffff0000, v159
	v_lshlrev_b32_e32 v178, 16, v160
	v_and_b32_e32 v179, 0xffff0000, v160
	v_lshlrev_b32_e32 v160, 16, v161
	v_and_b32_e32 v161, 0xffff0000, v161
	v_pk_fma_f32 v[58:59], v[58:59], v[138:139], v[170:171]
	v_pk_fma_f32 v[60:61], v[60:61], v[140:141], v[152:153]
	v_pk_fma_f32 v[64:65], v[64:65], v[144:145], v[154:155]
	v_pk_fma_f32 v[62:63], v[62:63], v[142:143], v[174:175]
	v_pk_fma_f32 v[56:57], v[56:57], v[136:137], v[158:159]
	v_pk_fma_f32 v[54:55], v[54:55], v[134:135], v[176:177]
	v_pk_fma_f32 v[48:49], v[48:49], v[132:133], v[160:161]
	v_pk_fma_f32 v[46:47], v[46:47], v[130:131], v[178:179]
	v_add_u32_e32 v152, 32, v164
	v_mov_b32_e32 v158, v206
	v_mov_b32_e32 v159, v207
	v_mov_b32_e32 v160, v208
	v_mov_b32_e32 v161, v209
	v_mov_b32_e32 v174, v210
	v_mov_b32_e32 v175, v211
	v_mov_b32_e32 v176, v212
	v_mov_b32_e32 v177, v213
	v_ashrrev_i32_e32 v153, 31, v152
	v_lshlrev_b64 v[152:153], 11, v[152:153]
	v_lshl_add_u64 v[154:155], s[6:7], 0, v[152:153]
	v_lshl_add_u64 v[154:155], v[154:155], 0, v[146:147]
	v_cndmask_b32_e32 v165, v173, v165, vcc
	v_lshlrev_b32_e32 v169, 2, v165
	s_waitcnt vmcnt(1)
	v_lshlrev_b32_e32 v162, 16, v158
	v_and_b32_e32 v163, 0xffff0000, v158
	v_lshlrev_b32_e32 v158, 16, v159
	v_and_b32_e32 v159, 0xffff0000, v159
	v_lshlrev_b32_e32 v170, 16, v160
	v_and_b32_e32 v171, 0xffff0000, v160
	v_lshlrev_b32_e32 v160, 16, v161
	v_and_b32_e32 v161, 0xffff0000, v161
	s_waitcnt vmcnt(0)
	v_lshlrev_b32_e32 v178, 16, v174
	v_and_b32_e32 v179, 0xffff0000, v174
	v_lshlrev_b32_e32 v174, 16, v175
	v_and_b32_e32 v175, 0xffff0000, v175
	v_lshlrev_b32_e32 v180, 16, v176
	v_and_b32_e32 v181, 0xffff0000, v176
	v_lshlrev_b32_e32 v176, 16, v177
	v_and_b32_e32 v177, 0xffff0000, v177
	v_pk_fma_f32 v[84:85], v[84:85], v[140:141], v[158:159]
	v_pk_fma_f32 v[82:83], v[82:83], v[138:139], v[162:163]
	v_pk_fma_f32 v[76:77], v[76:77], v[144:145], v[160:161]
	v_pk_fma_f32 v[74:75], v[74:75], v[142:143], v[170:171]
	v_pk_fma_f32 v[52:53], v[52:53], v[136:137], v[174:175]
	v_pk_fma_f32 v[50:51], v[50:51], v[134:135], v[178:179]
	v_pk_fma_f32 v[44:45], v[44:45], v[132:133], v[176:177]
	v_pk_fma_f32 v[42:43], v[42:43], v[130:131], v[180:181]
	s_nop 0
	v_mov_b32_e32 v158, v214
	v_mov_b32_e32 v159, v215
	v_mov_b32_e32 v160, v216
	v_mov_b32_e32 v161, v217
	v_mov_b32_e32 v174, v218
	v_mov_b32_e32 v175, v219
	v_mov_b32_e32 v176, v220
	v_mov_b32_e32 v177, v221
	v_add_u32_e32 v154, 48, v164
	v_ashrrev_i32_e32 v155, 31, v154
	v_lshlrev_b64 v[154:155], 11, v[154:155]
	v_lshl_add_u64 v[162:163], s[6:7], 0, v[154:155]
	v_lshl_add_u64 v[170:171], v[162:163], 0, v[146:147]
	s_waitcnt vmcnt(1)
; __device__ __forceinline__ float bf_lo(unsigned w) { return __uint_as_float(w << 16); }
; __device__ __forceinline__ float bf_hi(unsigned w) { return __uint_as_float(w & 0xffff0000u); }
;     __device__ __forceinline__ void fused(f32x4 (&acc)[2][2][4][2], const Unit& u, int wr, int wc, int fr, int fq, PG8_LAS unsigned char* lds, int wid, int lane) const {
;     ...
;             for (int ai = 0; ai < 2; ++ai)
; #pragma unroll
;                 for (int m = 0; m < 4; ++m) { const int r = ai * HALF + wr * 64 + m * 16 + fr; const size_t off = (size_t)(u.pm * BM + r) * 1024 + col0;
; #pragma unroll
;                     for (int bj = 0; bj < 2; ++bj) { f32x4 b0, b1;
;                         if (XIN_BF16) { const u32x4 w = *(const u32x4*)((const bf16_t*)xin + off + bj * HALF); b0 = (f32x4){bf_lo(w.x), bf_hi(w.x), bf_lo(w.y), bf_hi(w.y)}; b1 = (f32x4){bf_lo(w.z), bf_hi(w.z), bf_lo(w.w), bf_hi(w.w)}; }
;                         else { b0 = *(const f32x4*)((const float*)xin + off + bj * HALF); b1 = *(const f32x4*)((const float*)xin + off + bj * HALF + 4); }
;                         acc[ai][bj][m][0] = b0 + gv[bj][0] * acc[ai][bj][m][0]; acc[ai][bj][m][1] = b1 + gv[bj][1] * acc[ai][bj][m][1]; }
	v_lshlrev_b32_e32 v162, 16, v158
	v_and_b32_e32 v163, 0xffff0000, v158
	v_lshlrev_b32_e32 v158, 16, v159
	v_and_b32_e32 v159, 0xffff0000, v159
	v_lshlrev_b32_e32 v178, 16, v160
	v_and_b32_e32 v179, 0xffff0000, v160
	v_lshlrev_b32_e32 v160, 16, v161
	v_and_b32_e32 v161, 0xffff0000, v161
	s_waitcnt vmcnt(0)
	v_lshlrev_b32_e32 v180, 16, v174
	v_and_b32_e32 v181, 0xffff0000, v174
	v_lshlrev_b32_e32 v174, 16, v175
	v_and_b32_e32 v175, 0xffff0000, v175
	v_lshlrev_b32_e32 v182, 16, v176
	v_and_b32_e32 v183, 0xffff0000, v176
	v_lshlrev_b32_e32 v176, 16, v177
	v_and_b32_e32 v177, 0xffff0000, v177
	v_pk_fma_f32 v[100:101], v[100:101], v[140:141], v[158:159]
	v_pk_fma_f32 v[98:99], v[98:99], v[138:139], v[162:163]
	v_pk_fma_f32 v[92:93], v[92:93], v[144:145], v[160:161]
	v_pk_fma_f32 v[90:91], v[90:91], v[142:143], v[178:179]
	v_pk_fma_f32 v[80:81], v[80:81], v[136:137], v[174:175]
	v_pk_fma_f32 v[78:79], v[78:79], v[134:135], v[180:181]
	v_pk_fma_f32 v[72:73], v[72:73], v[132:133], v[176:177]
	v_pk_fma_f32 v[70:71], v[70:71], v[130:131], v[182:183]
	v_add_u32_e32 v158, 0x80, v164
	v_mov_b32_e32 v160, v222
	v_mov_b32_e32 v161, v223
	v_mov_b32_e32 v162, v224
	v_mov_b32_e32 v163, v225
	v_mov_b32_e32 v174, v226
	v_mov_b32_e32 v175, v227
	v_mov_b32_e32 v176, v228
	v_mov_b32_e32 v177, v229
	v_ashrrev_i32_e32 v159, 31, v158
	v_lshlrev_b64 v[158:159], 11, v[158:159]
	v_lshl_add_u64 v[170:171], s[6:7], 0, v[158:159]
	v_lshl_add_u64 v[170:171], v[170:171], 0, v[146:147]
	s_waitcnt vmcnt(1)
	v_lshlrev_b32_e32 v178, 16, v160
	v_and_b32_e32 v179, 0xffff0000, v160
	v_lshlrev_b32_e32 v160, 16, v161
	v_and_b32_e32 v161, 0xffff0000, v161
	v_lshlrev_b32_e32 v180, 16, v162
	v_and_b32_e32 v181, 0xffff0000, v162
	v_lshlrev_b32_e32 v162, 16, v163
	v_and_b32_e32 v163, 0xffff0000, v163
	s_waitcnt vmcnt(0)
	v_lshlrev_b32_e32 v182, 16, v174
	v_and_b32_e32 v183, 0xffff0000, v174
	v_lshlrev_b32_e32 v174, 16, v175
	v_and_b32_e32 v175, 0xffff0000, v175
	v_lshlrev_b32_e32 v184, 16, v176
	v_and_b32_e32 v185, 0xffff0000, v176
	v_lshlrev_b32_e32 v176, 16, v177
	v_and_b32_e32 v177, 0xffff0000, v177
	v_pk_fma_f32 v[116:117], v[116:117], v[140:141], v[160:161]
	v_pk_fma_f32 v[114:115], v[114:115], v[138:139], v[178:179]
	v_pk_fma_f32 v[112:113], v[112:113], v[144:145], v[162:163]
	v_pk_fma_f32 v[110:111], v[110:111], v[142:143], v[180:181]
	v_pk_fma_f32 v[104:105], v[104:105], v[136:137], v[174:175]
	v_pk_fma_f32 v[102:103], v[102:103], v[134:135], v[182:183]
	v_pk_fma_f32 v[96:97], v[96:97], v[132:133], v[176:177]
	v_pk_fma_f32 v[94:95], v[94:95], v[130:131], v[184:185]
	v_add_u32_e32 v160, 0x90, v164
	v_mov_b32_e32 v174, v230
	v_mov_b32_e32 v175, v231
	v_mov_b32_e32 v176, v232
	v_mov_b32_e32 v177, v233
	v_mov_b32_e32 v178, v234
	v_mov_b32_e32 v179, v235
	v_mov_b32_e32 v180, v236
	v_mov_b32_e32 v181, v237
	v_ashrrev_i32_e32 v161, 31, v160
	v_lshlrev_b64 v[160:161], 11, v[160:161]
	v_lshl_add_u64 v[162:163], s[6:7], 0, v[160:161]
	v_lshl_add_u64 v[162:163], v[162:163], 0, v[146:147]
	s_waitcnt vmcnt(1)
	v_lshlrev_b32_e32 v170, 16, v174
	v_and_b32_e32 v171, 0xffff0000, v174
	v_lshlrev_b32_e32 v174, 16, v175
	v_and_b32_e32 v175, 0xffff0000, v175
	v_lshlrev_b32_e32 v182, 16, v176
	v_and_b32_e32 v183, 0xffff0000, v176
	v_lshlrev_b32_e32 v176, 16, v177
	v_and_b32_e32 v177, 0xffff0000, v177
	s_waitcnt vmcnt(0)
	v_lshlrev_b32_e32 v184, 16, v178
	v_and_b32_e32 v185, 0xffff0000, v178
	v_lshlrev_b32_e32 v178, 16, v179
	v_and_b32_e32 v179, 0xffff0000, v179
	v_lshlrev_b32_e32 v186, 16, v180
	v_and_b32_e32 v187, 0xffff0000, v180
	v_lshlrev_b32_e32 v180, 16, v181
	v_and_b32_e32 v181, 0xffff0000, v181
	v_pk_fma_f32 v[128:129], v[128:129], v[140:141], v[174:175]
	v_pk_fma_f32 v[126:127], v[126:127], v[138:139], v[170:171]
	v_pk_fma_f32 v[124:125], v[124:125], v[144:145], v[176:177]
	v_pk_fma_f32 v[122:123], v[122:123], v[142:143], v[182:183]
	v_pk_fma_f32 v[120:121], v[120:121], v[136:137], v[178:179]
	v_pk_fma_f32 v[118:119], v[118:119], v[134:135], v[184:185]
	v_pk_fma_f32 v[108:109], v[108:109], v[132:133], v[180:181]
	v_pk_fma_f32 v[106:107], v[106:107], v[130:131], v[186:187]
	s_nop 0
	v_mov_b32_e32 v174, v238
	v_mov_b32_e32 v175, v239
	v_mov_b32_e32 v176, v240
	v_mov_b32_e32 v177, v241
	v_mov_b32_e32 v178, v242
	v_mov_b32_e32 v179, v243
	v_mov_b32_e32 v180, v244
	v_mov_b32_e32 v181, v245
	v_add_u32_e32 v162, 0xa0, v164
	v_ashrrev_i32_e32 v163, 31, v162
	v_lshlrev_b64 v[162:163], 11, v[162:163]
	v_lshl_add_u64 v[170:171], s[6:7], 0, v[162:163]
	v_lshl_add_u64 v[170:171], v[170:171], 0, v[146:147]
	v_add_u32_e32 v164, 0xb0, v164
	v_ashrrev_i32_e32 v165, 31, v164
	v_lshlrev_b64 v[164:165], 11, v[164:165]
	s_waitcnt vmcnt(1)
	v_lshlrev_b32_e32 v182, 16, v174
	v_and_b32_e32 v183, 0xffff0000, v174
	v_lshlrev_b32_e32 v174, 16, v175
	v_and_b32_e32 v175, 0xffff0000, v175
	v_lshlrev_b32_e32 v184, 16, v176
	v_and_b32_e32 v185, 0xffff0000, v176
	v_lshlrev_b32_e32 v176, 16, v177
	v_and_b32_e32 v177, 0xffff0000, v177
	s_waitcnt vmcnt(0)
	v_lshlrev_b32_e32 v186, 16, v178
	v_and_b32_e32 v187, 0xffff0000, v178
	v_lshlrev_b32_e32 v178, 16, v179
	v_and_b32_e32 v179, 0xffff0000, v179
	v_lshlrev_b32_e32 v188, 16, v180
	v_and_b32_e32 v189, 0xffff0000, v180
	v_lshlrev_b32_e32 v180, 16, v181
	v_and_b32_e32 v181, 0xffff0000, v181
	v_pk_fma_f32 v[88:89], v[88:89], v[140:141], v[174:175]
	v_pk_fma_f32 v[86:87], v[86:87], v[138:139], v[182:183]
	v_pk_fma_f32 v[68:69], v[68:69], v[144:145], v[176:177]
	v_pk_fma_f32 v[66:67], v[66:67], v[142:143], v[184:185]
	v_pk_fma_f32 v[40:41], v[40:41], v[136:137], v[178:179]
	v_pk_fma_f32 v[38:39], v[38:39], v[134:135], v[186:187]
	v_pk_fma_f32 v[36:37], v[36:37], v[132:133], v[180:181]
	v_pk_fma_f32 v[34:35], v[34:35], v[130:131], v[188:189]
	v_mov_b32_e32 v184, v59
	v_mov_b32_e32 v174, v248
	v_mov_b32_e32 v175, v249
	v_mov_b32_e32 v176, v250
	v_mov_b32_e32 v177, v251
	v_mov_b32_e32 v178, v252
	v_mov_b32_e32 v179, v253
	v_mov_b32_e32 v180, v254
	v_mov_b32_e32 v181, v255
	v_lshl_add_u64 v[170:171], s[6:7], 0, v[164:165]
	v_lshl_add_u64 v[170:171], v[170:171], 0, v[146:147]
	v_mov_b32_e32 v185, v60
	v_mov_b32_e32 v186, v58
	v_mov_b32_e32 v187, v61
	v_pk_add_f32 v[184:185], v[184:185], v[186:187]
	s_lshl_b32 s6, s25, 3
	s_add_i32 s8, s6, 0
	s_waitcnt vmcnt(1)
; __device__ __forceinline__ float bf_lo(unsigned w) { return __uint_as_float(w << 16); }
; __device__ __forceinline__ float bf_hi(unsigned w) { return __uint_as_float(w & 0xffff0000u); }
;     template <class Mid> __device__ __forceinline__ bool run(const f32x4 (&v)[2][2][4][2], const Unit& u, int wr, int wc, int fr, int fq, PG8_LAS unsigned char* lds, int wid, int lane, const Mid& mid) const {
;     ...
;                     for (int n = 0; n < 2; ++n) { const f32x4 x = v[ai][bj][m][n]; s += (x[0] + x[1]) + (x[2] + x[3]); }
;                 s += __shfl_xor(s, 16); s += __shfl_xor(s, 32);
;                 const float mw = s * (1.0f / 64.0f); float q = 0.f;
; #pragma unroll
;                 for (int bj = 0; bj < 2; ++bj)
; #pragma unroll
;                     for (int n = 0; n < 2; ++n) { const f32x4 d = v[ai][bj][m][n] - mw; q += (d[0] * d[0] + d[1] * d[1]) + (d[2] * d[2] + d[3] * d[3]); }
;                 q += __shfl_xor(q, 16); q += __shfl_xor(q, 32);
;                 if (fq == 0) P[(ai * HALF + wr * 64 + m * 16 + fr) * 4 + wc] = (f32x2v){mw, q};
;     __device__ __forceinline__ void fused(f32x4 (&acc)[2][2][4][2], const Unit& u, int wr, int wc, int fr, int fq, PG8_LAS unsigned char* lds, int wid, int lane) const {
;     ...
;                 for (int m = 0; m < 4; ++m) { const int r = ai * HALF + wr * 64 + m * 16 + fr; const size_t off = (size_t)(u.pm * BM + r) * 1024 + col0;
; #pragma unroll
;                     for (int bj = 0; bj < 2; ++bj) { f32x4 b0, b1;
;                         if (XIN_BF16) { const u32x4 w = *(const u32x4*)((const bf16_t*)xin + off + bj * HALF); b0 = (f32x4){bf_lo(w.x), bf_hi(w.x), bf_lo(w.y), bf_hi(w.y)}; b1 = (f32x4){bf_lo(w.z), bf_hi(w.z), bf_lo(w.w), bf_hi(w.w)}; }
;                         else { b0 = *(const f32x4*)((const float*)xin + off + bj * HALF); b1 = *(const f32x4*)((const float*)xin + off + bj * HALF + 4); }
;                         acc[ai][bj][m][0] = b0 + gv[bj][0] * acc[ai][bj][m][0]; acc[ai][bj][m][1] = b1 + gv[bj][1] * acc[ai][bj][m][1]; }
	v_lshlrev_b32_e32 v182, 16, v174
	v_and_b32_e32 v183, 0xffff0000, v174
	v_lshlrev_b32_e32 v174, 16, v175
	v_and_b32_e32 v175, 0xffff0000, v175
	v_lshlrev_b32_e32 v188, 16, v176
	v_and_b32_e32 v189, 0xffff0000, v176
	v_lshlrev_b32_e32 v176, 16, v177
	v_and_b32_e32 v177, 0xffff0000, v177
	s_waitcnt vmcnt(0)
	v_lshlrev_b32_e32 v190, 16, v178
	v_and_b32_e32 v191, 0xffff0000, v178
	v_lshlrev_b32_e32 v178, 16, v179
	v_and_b32_e32 v179, 0xffff0000, v179
	v_lshlrev_b32_e32 v192, 16, v180
	v_and_b32_e32 v193, 0xffff0000, v180
	v_lshlrev_b32_e32 v180, 16, v181
	v_and_b32_e32 v181, 0xffff0000, v181
	v_pk_fma_f32 v[32:33], v[32:33], v[140:141], v[174:175]
	v_pk_fma_f32 v[30:31], v[30:31], v[138:139], v[182:183]
	v_pk_fma_f32 v[28:29], v[28:29], v[144:145], v[176:177]
	v_pk_fma_f32 v[26:27], v[26:27], v[142:143], v[188:189]
	v_pk_fma_f32 v[24:25], v[24:25], v[136:137], v[178:179]
	v_pk_fma_f32 v[22:23], v[22:23], v[134:135], v[190:191]
	v_pk_fma_f32 v[20:21], v[20:21], v[132:133], v[180:181]
	v_pk_fma_f32 v[18:19], v[18:19], v[130:131], v[192:193]
	v_mov_b32_e32 v174, v63
	global_load_dwordx4 v[176:179], v[170:171], off
	global_load_dwordx4 v[180:183], v[170:171], off offset:256
	v_mov_b32_e32 v175, v64
	v_mov_b32_e32 v188, v62
	v_mov_b32_e32 v189, v65
	v_pk_add_f32 v[174:175], v[174:175], v[188:189]
	v_add_f32_e32 v171, v184, v185
	v_pk_add_f32 v[174:175], v[174:175], v[174:175] op_sel_hi:[0,1]
	v_add_f32_e32 v191, v54, v55
	v_add_f32_e32 v193, v56, v57
	v_mov_b32_e32 v190, v46
	v_mov_b32_e32 v192, v47
	v_mov_b32_e32 v170, v49
	v_add_f32_e32 v171, 0, v171
	v_mov_b32_e32 v174, v48
	v_pk_add_f32 v[186:187], v[190:191], v[192:193]
	v_pk_add_f32 v[170:171], v[174:175], v[170:171]
	s_nop 0
	v_pk_add_f32 v[170:171], v[186:187], v[170:171]
	s_nop 0
	v_add_f32_e32 v170, v170, v171
	ds_bpermute_b32 v174, v169, v170
	v_xor_b32_e32 v171, 32, v173
	v_cmp_lt_i32_e32 vcc, v171, v194
	s_waitcnt lgkmcnt(0)
	v_add_f32_e32 v170, v170, v174
	v_cndmask_b32_e32 v171, v173, v171, vcc
	v_lshlrev_b32_e32 v171, 2, v171
	ds_bpermute_b32 v173, v171, v170
	s_waitcnt lgkmcnt(0)
	v_add_f32_e32 v173, v170, v173
	v_fmamk_f32 v174, v173, 0xbc800000, v61
	v_fmamk_f32 v184, v173, 0xbc800000, v59
	v_fmamk_f32 v186, v173, 0xbc800000, v65
	v_fmamk_f32 v188, v173, 0xbc800000, v63
	v_fmamk_f32 v170, v173, 0xbc800000, v60
	v_fmamk_f32 v175, v173, 0xbc800000, v58
	v_fmamk_f32 v185, v173, 0xbc800000, v64
	v_fmamk_f32 v187, v173, 0xbc800000, v62
	v_fmamk_f32 v190, v173, 0xbc800000, v57
	v_fmamk_f32 v192, v173, 0xbc800000, v55
	v_mul_f32_e32 v184, v184, v184
	v_mul_f32_e32 v174, v174, v174
	v_mul_f32_e32 v188, v188, v188
	v_mul_f32_e32 v186, v186, v186
	v_fmamk_f32 v189, v173, 0xbc800000, v56
	v_fmamk_f32 v191, v173, 0xbc800000, v54
	v_fmamk_f32 v194, v173, 0xbc800000, v49
	v_fmamk_f32 v196, v173, 0xbc800000, v47
	v_mul_f32_e32 v192, v192, v192
	v_mul_f32_e32 v190, v190, v190
	v_fmac_f32_e32 v184, v175, v175
	v_fmac_f32_e32 v174, v170, v170
	v_fmac_f32_e32 v188, v187, v187
	v_fmac_f32_e32 v186, v185, v185
	v_fmamk_f32 v193, v173, 0xbc800000, v48
	v_fmamk_f32 v195, v173, 0xbc800000, v46
	v_mul_f32_e32 v196, v196, v196
	v_mul_f32_e32 v194, v194, v194
	v_fmac_f32_e32 v192, v191, v191
	v_fmac_f32_e32 v190, v189, v189
	v_add_f32_e32 v170, v184, v174
	v_add_f32_e32 v174, v188, v186
	v_fmac_f32_e32 v196, v195, v195
	v_fmac_f32_e32 v194, v193, v193
	v_add_f32_e32 v175, v192, v190
	v_add_f32_e32 v170, v170, v174
	v_add_f32_e32 v184, v196, v194
	v_add_f32_e32 v170, v175, v170
	v_add_f32_e32 v174, v184, v170
	ds_bpermute_b32 v175, v169, v174
	v_and_b32_e32 v170, 63, v168
	v_cmp_gt_u32_e32 vcc, 16, v170
	s_waitcnt lgkmcnt(0)
	v_add_f32_e32 v174, v174, v175
	ds_bpermute_b32 v175, v171, v174
	s_waitcnt vmcnt(1)
	v_lshlrev_b32_e32 v184, 16, v176
	v_and_b32_e32 v185, 0xffff0000, v176
	v_lshlrev_b32_e32 v176, 16, v177
	v_and_b32_e32 v177, 0xffff0000, v177
	v_lshlrev_b32_e32 v186, 16, v178
	v_and_b32_e32 v187, 0xffff0000, v178
	v_lshlrev_b32_e32 v178, 16, v179
	v_and_b32_e32 v179, 0xffff0000, v179
	s_waitcnt vmcnt(0)
	v_lshlrev_b32_e32 v188, 16, v180
	v_and_b32_e32 v189, 0xffff0000, v180
	v_lshlrev_b32_e32 v180, 16, v181
	v_and_b32_e32 v181, 0xffff0000, v181
	v_lshlrev_b32_e32 v190, 16, v182
	v_and_b32_e32 v191, 0xffff0000, v182
	v_lshlrev_b32_e32 v182, 16, v183
	v_and_b32_e32 v183, 0xffff0000, v183
	v_pk_fma_f32 v[16:17], v[16:17], v[140:141], v[176:177]
	v_pk_fma_f32 v[14:15], v[14:15], v[138:139], v[184:185]
	v_pk_fma_f32 v[12:13], v[12:13], v[144:145], v[178:179]
	v_pk_fma_f32 v[10:11], v[10:11], v[142:143], v[186:187]
	v_pk_fma_f32 v[8:9], v[8:9], v[136:137], v[180:181]
	v_pk_fma_f32 v[6:7], v[6:7], v[134:135], v[188:189]
	v_pk_fma_f32 v[4:5], v[4:5], v[132:133], v[182:183]
	v_pk_fma_f32 v[2:3], v[2:3], v[130:131], v[190:191]
	s_nop 0
	s_and_saveexec_b64 s[6:7], vcc
	s_cbranch_execz .LBB0_944
	s_lshl_b32 s9, s24, 11
	s_add_i32 s9, s8, s9
	v_mul_f32_e32 v130, 0x3c800000, v173
	s_waitcnt lgkmcnt(0)
	v_add_f32_e32 v131, v174, v175
	v_lshl_add_u32 v132, v167, 5, s9
	ds_write_b64 v132, v[130:131]

; __device__ __forceinline__ void attn_unit(LAS unsigned char* lds, bf16* Q, const bf16* Kg, const bf16* Vg, const float* snk, int unit, int tid) {
;     const int lane = tid & 63, wave = tid >> 6, fr = lane & 15, fq = lane >> 4;
;     const int b = unit >> 6, n = (unit >> 1) & 31, h = unit & 1, r0 = b * SEQ + n * 128, hq = 8 * h + wave;
;     const v4u zero4 = {0u, 0u, 0u, 0u};
;     bf16* qbase = Q + (size_t)(r0 + fr) * 1024 + hq * 64;
;     bf16x8_t qf[8][2];
; #pragma unroll
;     for (int mt = 0; mt < 8; ++mt) { qf[mt][0] = *(const bf16x8_t*)(qbase + (size_t)mt * 16 * 1024 + 8 * fq); qf[mt][1] = *(const bf16x8_t*)(qbase + (size_t)mt * 16 * 1024 + 32 + 8 * fq); }
; #pragma unroll
;     for (int i = 0; i < 4; ++i) { const int idx = tid + 512 * i, j = idx >> 3, c = idx & 7, p = n * 128 - 128 + j;
;         v4u w = zero4; if (p >= 0) w = *(const v4u*)(Kg + (size_t)(b * SEQ + p) * 128 + h * 64 + c * 8);
;         *(LAS v4u*)(lds + j * ATT_KP + c * 16) = w; }
; #pragma unroll
;     for (int i = 0; i < 2; ++i) { const int idx = tid + 512 * i, j = (idx >> 3) * 2, c = idx & 7, p = n * 128 - 128 + j;
;         v4u w0 = zero4, w1 = zero4;
;         if (p >= 0) { w0 = *(const v4u*)(Vg + (size_t)(b * SEQ + p) * 128 + h * 64 + c * 8); w1 = *(const v4u*)(Vg + (size_t)(b * SEQ + p + 1) * 128 + h * 64 + c * 8); }
;         const unsigned A0[4] = {w0.x, w0.y, w0.z, w0.w}, A1[4] = {w1.x, w1.y, w1.z, w1.w};
; #pragma unroll
;         for (int e = 0; e < 8; ++e) { const unsigned lo = (e & 1) ? (A0[e >> 1] >> 16) : (A0[e >> 1] & 0xffffu), hi = (e & 1) ? (A1[e >> 1] & 0xffff0000u) : (A1[e >> 1] << 16);
;             *(LAS unsigned*)(lds + ATT_VOFF + (8 * c + e) * ATT_VP + j * 2) = lo | hi; } }
;     __syncthreads();
;     const float sink = snk[hq] * 1.4426950408889634f;
;     bool lo_ok[4];
; #pragma unroll
;     for (int i = 0; i < 4; ++i) lo_ok[i] = (4 * fq + i - fr) > 0;
; __global__ void __launch_bounds__(512, 2) fwd_mega(Args a) {
;     ...
;         {
;             int tid_ = threadIdx.x; asm volatile("" : "+v"(tid_));
;             for (int it = bx; it < 512; it += G) {
;                 if (it < 256) attn_unit(lds, WSP(WS_Q), WSP(WS_K), WSP(WS_V), INF(7) + l * 16, it, tid_);
;                 else sgu_unit(lds, WSP(WS_U), WSP(WS_VS), (const float*)(a.ws + WS_SGS), INF(8) + l * 1024, INF(9) + l * 1024, (const v4u*)(a.ws + WS_WF), INF(11) + l * 8 * 128, it - 256, tid_);
.LBB0_1394:
	s_or_b64 exec, exec, s[6:7]
	v_readlane_b32 s4, v246, 18
	v_readlane_b32 s5, v246, 19
	v_mov_b32_e32 v161, v0
	s_andn2_b64 vcc, exec, s[4:5]
	s_waitcnt lgkmcnt(0)
	s_barrier
	s_cbranch_vccnz .LBB0_1415
	s_movk_i32 s4, 0x80
	v_cmp_gt_i32_e64 s[6:7], s4, v161
	v_ashrrev_i32_e32 v169, 6, v161
	s_movk_i32 s4, 0x4400
	v_mul_lo_u32 v5, v169, s4
	s_load_dwordx2 s[4:5], s[0:1], 0xb8
	s_load_dwordx4 s[28:31], s[0:1], 0x38
	s_load_dwordx2 s[16:17], s[0:1], 0x48
	s_load_dwordx2 s[18:19], s[0:1], 0x58
	v_and_b32_e32 v6, 7, v161
	v_add_u32_e32 v8, 0x200, v161
	v_lshlrev_b32_e32 v170, 3, v6
	s_waitcnt lgkmcnt(0)
	s_add_u32 s38, s4, 0x4b00000
	s_addc_u32 s39, s5, 0
	s_add_u32 s30, s30, 0x1000
	s_addc_u32 s31, s31, 0
	s_add_u32 s40, s16, 0x1000
	v_mul_u32_u24_e32 v10, 0x110, v6
	v_bfe_u32 v15, v161, 4, 2
	v_lshlrev_b32_e32 v4, 4, v6
	s_waitcnt vmcnt(1)
	v_mul_u32_u24_e32 v20, 0x1080, v6
	v_ashrrev_i32_e32 v6, 2, v8
	s_addc_u32 s41, s17, 0
	v_add_u32_e32 v9, 0x400, v161
	v_and_b32_e32 v176, -2, v6
	v_lshlrev_b32_e32 v6, 2, v15
	s_add_u32 s44, s18, 0x1000
	v_and_b32_e32 v3, 63, v161
	v_and_b32_e32 v163, 15, v161
	v_ashrrev_i32_e32 v172, 3, v8
	v_ashrrev_i32_e32 v173, 3, v9
	v_add_u32_e32 v9, 0x600, v161
	v_or_b32_e32 v8, 2, v6
	s_addc_u32 s45, s19, 0
	v_mov_b32_e32 v147, 0
	v_ashrrev_i32_e32 v174, 3, v9
	v_ashrrev_i32_e32 v9, 2, v161
	v_cmp_gt_u32_e64 s[12:13], v8, v163
	v_or_b32_e32 v8, 3, v6
	v_lshlrev_b32_e32 v146, 4, v3
	s_add_u32 s46, s4, 0xf400000
	v_add_u32_e32 v3, 0, v5
	v_lshrrev_b32_e32 v5, 1, v161
	v_bfe_u32 v2, v161, 3, 3
	v_and_b32_e32 v175, -2, v9
	v_cmp_gt_u32_e64 s[14:15], v8, v163
	v_lshl_add_u64 v[8:9], s[4:5], 0, v[146:147]
	s_mov_b64 s[16:17], 0x680000
	s_addc_u32 s47, s5, 0
	v_and_b32_e32 v146, 24, v5
	v_lshlrev_b32_e32 v167, 3, v161
	v_lshlrev_b32_e32 v7, 11, v2
	v_lshlrev_b32_e32 v11, 2, v2
	v_lshlrev_b32_e32 v12, 4, v2
	v_bfe_u32 v2, v161, 3, 1
	v_lshl_add_u64 v[148:149], v[8:9], 0, s[16:17]
	v_lshl_add_u64 v[8:9], s[4:5], 0, v[146:147]
	s_mov_b64 s[16:17], 0x9300000
	s_add_u32 s50, s4, 0x6b00000
	v_mov_b32_e32 v5, v147
	v_and_or_b32 v2, v167, 56, v2
	v_lshl_add_u64 v[150:151], v[8:9], 0, s[16:17]
	s_addc_u32 s51, s5, 0
	v_add_u32_e32 v8, 0, v4
	v_lshl_add_u64 v[4:5], s[4:5], 0, v[4:5]
	s_mov_b64 s[4:5], 0x8b00000
	v_mul_u32_u24_e32 v14, 0x110, v2
	v_lshlrev_b32_e32 v2, 3, v15
	v_lshl_add_u64 v[152:153], v[4:5], 0, s[4:5]
	s_mov_b64 s[4:5], 0x8f00000
	v_lshl_add_u32 v9, v15, 4, 0
	v_and_b32_e32 v13, 48, v161
	v_ashrrev_i32_e32 v171, 3, v161
	s_movk_i32 s20, 0x90
	v_add3_u32 v177, v3, v10, v11
	v_lshl_add_u64 v[154:155], v[4:5], 0, s[4:5]
	v_sub_u32_e32 v10, v9, v2
	s_movk_i32 s4, 0x210
	v_mul_lo_u32 v16, v171, s20
	v_mul_lo_u32 v17, v172, s20
	v_mul_lo_u32 v18, v173, s20
	v_mul_lo_u32 v19, v174, s20
	v_add_u32_e32 v3, v3, v13
	v_lshl_add_u32 v4, v175, 1, 0
	v_lshl_add_u32 v5, v176, 1, 0
	v_mad_u32_u24 v179, v163, s4, v10
	s_lshl_b32 s4, s2, 2
	v_ashrrev_i32_e32 v165, 7, v161
	v_and_b32_e32 v168, 64, v161
	v_cmp_gt_u32_e64 s[8:9], v6, v163
	v_cmp_lt_u32_e64 s[10:11], v6, v163
	s_mov_b32 s49, 0
	v_mad_u32_u24 v178, v163, s20, v9
	s_addk_i32 s4, 0xfc00
	s_lshl_b32 s5, s3, 2
	s_lshl_b32 s24, s2, 6
	s_lshl_b32 s25, s3, 6
	s_movk_i32 s34, 0x1000
	s_movk_i32 s35, 0x2000
	s_movk_i32 s36, 0x3000
	s_movk_i32 s37, 0x4000
	s_mov_b32 s52, 0x3a800000
	s_mov_b32 s42, 0x800000
	v_lshlrev_b32_e32 v180, 1, v7
	s_mov_b32 s43, 0x8000
	s_mov_b32 s53, 0x10000
	s_mov_b32 s54, 0x18000
	s_mov_b32 s55, 0x20000
	s_mov_b32 s56, 0x28000
	s_mov_b32 s57, 0x30000
	s_mov_b32 s58, 0x38000
	v_add_u32_e32 v181, 0, v12
	s_mov_b32 s59, 0xffff0000
	v_add_u32_e32 v182, v3, v14
	v_lshlrev_b32_e32 v146, 1, v2
	v_add_u32_e32 v183, v8, v16
	v_add_u32_e32 v184, v8, v17
	v_add_u32_e32 v185, v8, v18
	v_add_u32_e32 v186, v8, v19
	s_mov_b32 s60, 0xffff
	v_add_u32_e32 v187, v4, v20
	v_add_u32_e32 v188, v5, v20
	s_mov_b32 s61, 0x3fb8aa3b
	v_lshlrev_b32_e32 v156, 1, v6
	v_mbcnt_hi_u32_b32 v189, -1, v1
	v_mov_b32_e32 v190, 0xff800000
	s_mov_b32 s62, s2
	s_mov_b32 s98, 0x100
	s_mov_b32 s101, 0
	s_bitcmp1_b32 s2, 3
	s_cbranch_scc0 .Lmix_noswap1
	s_addk_i32 s62, 0x100
	s_addk_i32 s4, 0x400
	s_addk_i32 s24, 0x4000
	s_mov_b32 s98, 0xffffff00

; __global__ void __launch_bounds__(512, 2) fwd_mega(Args a) {
;     ...
;             for (int it = bx; it < 512; it += G) {
;                 if (it < 256) attn_unit(lds, WSP(WS_Q), WSP(WS_K), WSP(WS_V), INF(7) + l * 16, it, tid_);
;                 else sgu_unit(lds, WSP(WS_U), WSP(WS_VS), (const float*)(a.ws + WS_SGS), INF(8) + l * 1024, INF(9) + l * 1024, (const v4u*)(a.ws + WS_WF), INF(11) + l * 8 * 128, it - 256, tid_);
.LBB0_1397:
	s_add_i32 s62, s62, s98
	s_add_i32 s4, s4, s99
	s_add_i32 s24, s24, s100
	s_add_i32 s101, s101, 1
	s_cmp_gt_i32 s101, 1
	s_cbranch_scc1 .LBB0_1415

; __device__ __forceinline__ float bf_lo(unsigned w) { return __uint_as_float(w << 16); }
; __device__ __forceinline__ float bf_hi(unsigned w) { return __uint_as_float(w & 0xffff0000u); }
; __device__ __forceinline__ u32x4 pack8(f32x4 v0, f32x4 v1) { u32x4 w; w.x = cvt_pk_bf16(v0[0], v0[1]); w.y = cvt_pk_bf16(v0[2], v0[3]); w.z = cvt_pk_bf16(v1[0], v1[1]); w.w = cvt_pk_bf16(v1[2], v1[3]); return w; }
;     __device__ __forceinline__ void operator()(f32x4 (&acc)[2][2][4][2], const Unit& u, int wr, int wc, int fr, int fq) const {
;         const int pn = u.pn, row0 = u.pm * BM + wr * 64 + fr, co = (pn & 3) * 256 + wc * 32 + 8 * fq;
; #pragma unroll
;         for (int ai = 0; ai < 2; ++ai) {
;             u32x4 gaq[4][2];
; #pragma unroll
;             for (int m = 0; m < 4; ++m)
; #pragma unroll
;                 for (int bj = 0; bj < 2; ++bj) gaq[m][bj] = *(const u32x4*)(GA + (size_t)(row0 + ai * HALF + m * 16) * 1024 + co + bj * HALF);
; #pragma unroll
;             for (int m = 0; m < 4; ++m) {
;                 const size_t ro = (size_t)(row0 + ai * HALF + m * 16) * 1024 + co;
; #pragma unroll
;                 for (int bj = 0; bj < 2; ++bj) {
;                     const u32x4 ga = gaq[m][bj];
;                     f32x4 a0 = {bf_lo(ga.x), bf_hi(ga.x), bf_lo(ga.y), bf_hi(ga.y)}, a1 = {bf_lo(ga.z), bf_hi(ga.z), bf_lo(ga.w), bf_hi(ga.w)};
; #pragma unroll
;                     for (int i = 0; i < 4; ++i) { a0[i] = fmaxf(a0[i], 1e-20f); a1[i] = fmaxf(a1[i], 1e-20f); }
;                     if (pn < 4) {
;                         const u32x4 gb = *(const u32x4*)(GB + ro + bj * HALF);
;                         const f32x4 b0 = {bf_lo(gb.x), bf_hi(gb.x), bf_lo(gb.y), bf_hi(gb.y)}, b1 = {bf_lo(gb.z), bf_hi(gb.z), bf_lo(gb.w), bf_hi(gb.w)};
; #pragma unroll
;                         for (int i = 0; i < 4; ++i) { acc[ai][bj][m][0][i] *= b0[i] * __builtin_amdgcn_rcpf(a0[i]); acc[ai][bj][m][1][i] *= b1[i] * __builtin_amdgcn_rcpf(a1[i]); }
;                     } else {
;                         *(u32x4*)(MG + ro + bj * HALF) = pack8(acc[ai][bj][m][0] * a0, acc[ai][bj][m][1] * a1);
.LBB0_1491:
	s_lshl_b32 s8, s40, 8
	v_lshl_add_u32 v178, s44, 8, v198
	s_and_b32 s8, s8, 0x300
	v_or_b32_e32 v202, s8, v200
	v_or_b32_e32 v184, 16, v178
	v_or_b32_e32 v182, 32, v178
	v_lshlrev_b32_e32 v166, 1, v202
	v_ashrrev_i32_e32 v179, 31, v178
	v_or_b32_e32 v180, 48, v178
	v_ashrrev_i32_e32 v185, 31, v184
	v_ashrrev_i32_e32 v183, 31, v182
	v_lshl_add_u64 v[176:177], s[14:15], 0, v[166:167]
	v_lshlrev_b64 v[130:131], 11, v[178:179]
	v_ashrrev_i32_e32 v181, 31, v180
	v_lshlrev_b64 v[132:133], 11, v[184:185]
	v_lshlrev_b64 v[134:135], 11, v[182:183]
	v_lshl_add_u64 v[130:131], v[176:177], 0, v[130:131]
	v_lshlrev_b64 v[136:137], 11, v[180:181]
	v_lshl_add_u64 v[132:133], v[176:177], 0, v[132:133]
	v_lshl_add_u64 v[134:135], v[176:177], 0, v[134:135]
	global_load_dwordx4 v[190:193], v[130:131], off
	v_lshl_add_u64 v[186:187], v[176:177], 0, v[136:137]
	global_load_dwordx4 v[154:157], v[130:131], off offset:256
	global_load_dwordx4 v[150:153], v[132:133], off
	global_load_dwordx4 v[146:149], v[132:133], off offset:256
	global_load_dwordx4 v[142:145], v[134:135], off
	global_load_dwordx4 v[138:141], v[134:135], off offset:256
	s_cmp_gt_i32 s40, 3
	s_cbranch_scc1 .Lgbskip_1_0
	s_sub_u32 s98, s16, s14
	s_subb_u32 s99, s17, s15
	v_lshl_add_u64 v[244:245], v[130:131], 0, s[98:99]
	global_load_dwordx4 v[212:215], v[244:245], off
	global_load_dwordx4 v[216:219], v[244:245], off offset:256
	v_lshl_add_u64 v[244:245], v[132:133], 0, s[98:99]
	global_load_dwordx4 v[220:223], v[244:245], off
	global_load_dwordx4 v[224:227], v[244:245], off offset:256
	v_lshl_add_u64 v[244:245], v[134:135], 0, s[98:99]
	global_load_dwordx4 v[228:231], v[244:245], off
	global_load_dwordx4 v[232:235], v[244:245], off offset:256
	v_lshl_add_u64 v[244:245], v[186:187], 0, s[98:99]
	global_load_dwordx4 v[236:239], v[244:245], off
	global_load_dwordx4 v[240:243], v[244:245], off offset:256
.Lgbskip_1_0:
	s_nop 0
	global_load_dwordx4 v[134:137], v[186:187], off
	global_load_dwordx4 v[130:133], v[186:187], off offset:256
	s_cmp_gt_i32 s40, 3
	v_lshlrev_b64 v[188:189], 10, v[178:179]
	s_cselect_b64 s[40:41], -1, 0
	v_or_b32_e32 v188, v188, v202
	s_mov_b64 s[8:9], -1
	s_and_b64 vcc, exec, s[40:41]
	v_lshl_add_u64 v[186:187], v[188:189], 1, s[12:13]
	s_waitcnt vmcnt(0)
	v_lshlrev_b32_e32 v166, 16, v190
	v_and_b32_e32 v179, 0xffff0000, v190
	v_lshlrev_b32_e32 v190, 16, v191
	v_and_b32_e32 v191, 0xffff0000, v191
	v_lshlrev_b32_e32 v194, 16, v192
	v_and_b32_e32 v192, 0xffff0000, v192
	v_lshlrev_b32_e32 v195, 16, v193
	v_and_b32_e32 v193, 0xffff0000, v193
	v_max_f32_e32 v166, v166, v166
	v_max_f32_e32 v194, v194, v194
	v_max_f32_e32 v179, v179, v179
	v_max_f32_e32 v192, v192, v192
	v_max_f32_e32 v190, v190, v190
	v_max_f32_e32 v203, v195, v195
	v_max_f32_e32 v191, v191, v191
	v_max_f32_e32 v204, v193, v193
	v_max_f32_e32 v196, 0x1e3ce508, v166
	v_max_f32_e32 v194, 0x1e3ce508, v194
	v_max_f32_e32 v197, 0x1e3ce508, v179
	v_max_f32_e32 v195, 0x1e3ce508, v192
	v_max_f32_e32 v192, 0x1e3ce508, v190
	v_max_f32_e32 v190, 0x1e3ce508, v203
	v_max_f32_e32 v193, 0x1e3ce508, v191
	v_max_f32_e32 v191, 0x1e3ce508, v204
	s_cbranch_vccz .LBB0_1493
	v_pk_mul_f32 v[206:207], v[128:129], v[192:193]
	v_pk_mul_f32 v[204:205], v[126:127], v[196:197]
	v_pk_mul_f32 v[208:209], v[124:125], v[190:191]
	v_pk_mul_f32 v[210:211], v[122:123], v[194:195]
	v_cvt_pk_bf16_f32 v204, v204, v205
	v_cvt_pk_bf16_f32 v205, v206, v207
	s_mov_b64 s[8:9], 0
	v_cvt_pk_bf16_f32 v206, v210, v211
	v_cvt_pk_bf16_f32 v207, v208, v209
	global_store_dwordx4 v[186:187], v[204:207], off
.LBB0_1493:
	s_andn2_b64 vcc, exec, s[8:9]
	v_lshl_add_u64 v[188:189], v[188:189], 1, s[16:17]
	s_cbranch_vccnz .LBB0_1495
	v_rcp_f32_e32 v196, v196
	v_rcp_f32_e32 v194, v194
	v_rcp_f32_e32 v197, v197
	v_rcp_f32_e32 v195, v195
	v_rcp_f32_e32 v192, v192
	v_rcp_f32_e32 v190, v190
	v_rcp_f32_e32 v193, v193
	v_rcp_f32_e32 v191, v191
	s_waitcnt vmcnt(0)
	v_mov_b32_e32 v204, v212
	v_mov_b32_e32 v205, v213
	v_mov_b32_e32 v206, v214
	v_mov_b32_e32 v207, v215
	v_lshlrev_b32_e32 v208, 16, v204
	v_and_b32_e32 v209, 0xffff0000, v204
	v_lshlrev_b32_e32 v210, 16, v206
	v_and_b32_e32 v211, 0xffff0000, v206
	v_lshlrev_b32_e32 v204, 16, v205
	v_and_b32_e32 v205, 0xffff0000, v205
	v_lshlrev_b32_e32 v206, 16, v207
	v_and_b32_e32 v207, 0xffff0000, v207
	v_pk_mul_f32 v[196:197], v[196:197], v[208:209]
	v_pk_mul_f32 v[194:195], v[194:195], v[210:211]
	v_pk_mul_f32 v[192:193], v[192:193], v[204:205]
	v_pk_mul_f32 v[190:191], v[190:191], v[206:207]
	v_pk_mul_f32 v[126:127], v[126:127], v[196:197]
	v_pk_mul_f32 v[122:123], v[122:123], v[194:195]
	v_pk_mul_f32 v[128:129], v[128:129], v[192:193]
	v_pk_mul_f32 v[124:125], v[124:125], v[190:191]

; __device__ __forceinline__ float bf_lo(unsigned w) { return __uint_as_float(w << 16); }
; __device__ __forceinline__ float bf_hi(unsigned w) { return __uint_as_float(w & 0xffff0000u); }
;     __device__ __forceinline__ void operator()(f32x4 (&acc)[2][2][4][2], const Unit& u, int wr, int wc, int fr, int fq) const {
;     ...
;                     if (pn < 4) {
;                         const u32x4 gb = *(const u32x4*)(GB + ro + bj * HALF);
;                         const f32x4 b0 = {bf_lo(gb.x), bf_hi(gb.x), bf_lo(gb.y), bf_hi(gb.y)}, b1 = {bf_lo(gb.z), bf_hi(gb.z), bf_lo(gb.w), bf_hi(gb.w)};
; #pragma unroll
;                         for (int i = 0; i < 4; ++i) { acc[ai][bj][m][0][i] *= b0[i] * __builtin_amdgcn_rcpf(a0[i]); acc[ai][bj][m][1][i] *= b1[i] * __builtin_amdgcn_rcpf(a1[i]); }
.LBB0_1497:
	s_andn2_b64 vcc, exec, s[40:41]
	s_cbranch_vccnz .LBB0_1499
	v_rcp_f32_e32 v192, v192
	v_rcp_f32_e32 v190, v190
	v_rcp_f32_e32 v193, v193
	v_rcp_f32_e32 v191, v191
	v_rcp_f32_e32 v156, v156
	v_rcp_f32_e32 v154, v154
	v_rcp_f32_e32 v157, v157
	v_rcp_f32_e32 v155, v155
	s_waitcnt vmcnt(0)
	v_mov_b32_e32 v186, v216
	v_mov_b32_e32 v187, v217
	v_mov_b32_e32 v188, v218
	v_mov_b32_e32 v189, v219
	v_lshlrev_b32_e32 v194, 16, v186
	v_and_b32_e32 v195, 0xffff0000, v186
	v_lshlrev_b32_e32 v196, 16, v188
	v_and_b32_e32 v197, 0xffff0000, v188
	v_lshlrev_b32_e32 v186, 16, v187
	v_and_b32_e32 v187, 0xffff0000, v187
	v_lshlrev_b32_e32 v188, 16, v189
	v_and_b32_e32 v189, 0xffff0000, v189
	v_pk_mul_f32 v[192:193], v[192:193], v[194:195]
	v_pk_mul_f32 v[190:191], v[190:191], v[196:197]
	v_pk_mul_f32 v[156:157], v[156:157], v[186:187]
	v_pk_mul_f32 v[154:155], v[154:155], v[188:189]
	v_pk_mul_f32 v[94:95], v[94:95], v[192:193]
	v_pk_mul_f32 v[90:91], v[90:91], v[190:191]
	v_pk_mul_f32 v[96:97], v[96:97], v[156:157]
	v_pk_mul_f32 v[92:93], v[92:93], v[154:155]

; __device__ __forceinline__ float bf_lo(unsigned w) { return __uint_as_float(w << 16); }
; __device__ __forceinline__ float bf_hi(unsigned w) { return __uint_as_float(w & 0xffff0000u); }
;     __device__ __forceinline__ void operator()(f32x4 (&acc)[2][2][4][2], const Unit& u, int wr, int wc, int fr, int fq) const {
;     ...
;                     if (pn < 4) {
;                         const u32x4 gb = *(const u32x4*)(GB + ro + bj * HALF);
;                         const f32x4 b0 = {bf_lo(gb.x), bf_hi(gb.x), bf_lo(gb.y), bf_hi(gb.y)}, b1 = {bf_lo(gb.z), bf_hi(gb.z), bf_lo(gb.w), bf_hi(gb.w)};
; #pragma unroll
;                         for (int i = 0; i < 4; ++i) { acc[ai][bj][m][0][i] *= b0[i] * __builtin_amdgcn_rcpf(a0[i]); acc[ai][bj][m][1][i] *= b1[i] * __builtin_amdgcn_rcpf(a1[i]); }
.LBB0_1501:
	s_andn2_b64 vcc, exec, s[40:41]
	v_lshl_add_u64 v[152:153], v[188:189], 1, s[16:17]
	s_cbranch_vccnz .LBB0_1503
	v_rcp_f32_e32 v186, v186
	v_rcp_f32_e32 v184, v184
	v_rcp_f32_e32 v187, v187
	v_rcp_f32_e32 v185, v185
	v_rcp_f32_e32 v156, v156
	v_rcp_f32_e32 v154, v154
	v_rcp_f32_e32 v157, v157
	v_rcp_f32_e32 v155, v155
	s_waitcnt vmcnt(0)
	v_mov_b32_e32 v188, v220
	v_mov_b32_e32 v189, v221
	v_mov_b32_e32 v190, v222
	v_mov_b32_e32 v191, v223
	v_lshlrev_b32_e32 v192, 16, v188
	v_and_b32_e32 v193, 0xffff0000, v188
	v_lshlrev_b32_e32 v194, 16, v190
	v_and_b32_e32 v195, 0xffff0000, v190
	v_lshlrev_b32_e32 v188, 16, v189
	v_and_b32_e32 v189, 0xffff0000, v189
	v_lshlrev_b32_e32 v190, 16, v191
	v_and_b32_e32 v191, 0xffff0000, v191
	v_pk_mul_f32 v[186:187], v[186:187], v[192:193]
	v_pk_mul_f32 v[184:185], v[184:185], v[194:195]
	v_pk_mul_f32 v[156:157], v[156:157], v[188:189]
	v_pk_mul_f32 v[154:155], v[154:155], v[190:191]
	v_pk_mul_f32 v[118:119], v[118:119], v[186:187]
	v_pk_mul_f32 v[114:115], v[114:115], v[184:185]
	v_pk_mul_f32 v[120:121], v[120:121], v[156:157]
	v_pk_mul_f32 v[116:117], v[116:117], v[154:155]

; __device__ __forceinline__ float bf_lo(unsigned w) { return __uint_as_float(w << 16); }
; __device__ __forceinline__ float bf_hi(unsigned w) { return __uint_as_float(w & 0xffff0000u); }
;     __device__ __forceinline__ void operator()(f32x4 (&acc)[2][2][4][2], const Unit& u, int wr, int wc, int fr, int fq) const {
;     ...
;                     if (pn < 4) {
;                         const u32x4 gb = *(const u32x4*)(GB + ro + bj * HALF);
;                         const f32x4 b0 = {bf_lo(gb.x), bf_hi(gb.x), bf_lo(gb.y), bf_hi(gb.y)}, b1 = {bf_lo(gb.z), bf_hi(gb.z), bf_lo(gb.w), bf_hi(gb.w)};
; #pragma unroll
;                         for (int i = 0; i < 4; ++i) { acc[ai][bj][m][0][i] *= b0[i] * __builtin_amdgcn_rcpf(a0[i]); acc[ai][bj][m][1][i] *= b1[i] * __builtin_amdgcn_rcpf(a1[i]); }
.LBB0_1505:
	s_andn2_b64 vcc, exec, s[40:41]
	s_cbranch_vccnz .LBB0_1507
	v_rcp_f32_e32 v156, v156
	v_rcp_f32_e32 v154, v154
	v_rcp_f32_e32 v157, v157
	v_rcp_f32_e32 v155, v155
	v_rcp_f32_e32 v148, v148
	v_rcp_f32_e32 v146, v146
	v_rcp_f32_e32 v149, v149
	v_rcp_f32_e32 v147, v147
	s_waitcnt vmcnt(0)
	v_mov_b32_e32 v150, v224
	v_mov_b32_e32 v151, v225
	v_mov_b32_e32 v152, v226
	v_mov_b32_e32 v153, v227
	v_lshlrev_b32_e32 v184, 16, v150
	v_and_b32_e32 v185, 0xffff0000, v150
	v_lshlrev_b32_e32 v186, 16, v152
	v_and_b32_e32 v187, 0xffff0000, v152
	v_lshlrev_b32_e32 v150, 16, v151
	v_and_b32_e32 v151, 0xffff0000, v151
	v_lshlrev_b32_e32 v152, 16, v153
	v_and_b32_e32 v153, 0xffff0000, v153
	v_pk_mul_f32 v[156:157], v[156:157], v[184:185]
	v_pk_mul_f32 v[154:155], v[154:155], v[186:187]
	v_pk_mul_f32 v[148:149], v[148:149], v[150:151]
	v_pk_mul_f32 v[146:147], v[146:147], v[152:153]
	v_pk_mul_f32 v[86:87], v[86:87], v[156:157]
	v_pk_mul_f32 v[82:83], v[82:83], v[154:155]
	v_pk_mul_f32 v[88:89], v[88:89], v[148:149]
	v_pk_mul_f32 v[84:85], v[84:85], v[146:147]

; __device__ __forceinline__ float bf_lo(unsigned w) { return __uint_as_float(w << 16); }
; __device__ __forceinline__ float bf_hi(unsigned w) { return __uint_as_float(w & 0xffff0000u); }
;     __device__ __forceinline__ void operator()(f32x4 (&acc)[2][2][4][2], const Unit& u, int wr, int wc, int fr, int fq) const {
;     ...
;                     if (pn < 4) {
;                         const u32x4 gb = *(const u32x4*)(GB + ro + bj * HALF);
;                         const f32x4 b0 = {bf_lo(gb.x), bf_hi(gb.x), bf_lo(gb.y), bf_hi(gb.y)}, b1 = {bf_lo(gb.z), bf_hi(gb.z), bf_lo(gb.w), bf_hi(gb.w)};
; #pragma unroll
;                         for (int i = 0; i < 4; ++i) { acc[ai][bj][m][0][i] *= b0[i] * __builtin_amdgcn_rcpf(a0[i]); acc[ai][bj][m][1][i] *= b1[i] * __builtin_amdgcn_rcpf(a1[i]); }
.LBB0_1509:
	s_andn2_b64 vcc, exec, s[40:41]
	v_lshl_add_u64 v[144:145], v[154:155], 1, s[16:17]
	s_cbranch_vccnz .LBB0_1511
	v_rcp_f32_e32 v152, v152
	v_rcp_f32_e32 v150, v150
	v_rcp_f32_e32 v153, v153
	v_rcp_f32_e32 v151, v151
	v_rcp_f32_e32 v148, v148
	v_rcp_f32_e32 v146, v146
	v_rcp_f32_e32 v149, v149
	v_rcp_f32_e32 v147, v147
	s_waitcnt vmcnt(0)
	v_mov_b32_e32 v154, v228
	v_mov_b32_e32 v155, v229
	v_mov_b32_e32 v156, v230
	v_mov_b32_e32 v157, v231
	v_lshlrev_b32_e32 v182, 16, v154
	v_and_b32_e32 v183, 0xffff0000, v154
	v_lshlrev_b32_e32 v184, 16, v156
	v_and_b32_e32 v185, 0xffff0000, v156
	v_lshlrev_b32_e32 v154, 16, v155
	v_and_b32_e32 v155, 0xffff0000, v155
	v_lshlrev_b32_e32 v156, 16, v157
	v_and_b32_e32 v157, 0xffff0000, v157
	v_pk_mul_f32 v[152:153], v[152:153], v[182:183]
	v_pk_mul_f32 v[150:151], v[150:151], v[184:185]
	v_pk_mul_f32 v[148:149], v[148:149], v[154:155]
	v_pk_mul_f32 v[146:147], v[146:147], v[156:157]
	v_pk_mul_f32 v[110:111], v[110:111], v[152:153]
	v_pk_mul_f32 v[106:107], v[106:107], v[150:151]
	v_pk_mul_f32 v[112:113], v[112:113], v[148:149]
	v_pk_mul_f32 v[108:109], v[108:109], v[146:147]

; __device__ __forceinline__ float bf_lo(unsigned w) { return __uint_as_float(w << 16); }
; __device__ __forceinline__ float bf_hi(unsigned w) { return __uint_as_float(w & 0xffff0000u); }
;     __device__ __forceinline__ void operator()(f32x4 (&acc)[2][2][4][2], const Unit& u, int wr, int wc, int fr, int fq) const {
;     ...
;                     if (pn < 4) {
;                         const u32x4 gb = *(const u32x4*)(GB + ro + bj * HALF);
;                         const f32x4 b0 = {bf_lo(gb.x), bf_hi(gb.x), bf_lo(gb.y), bf_hi(gb.y)}, b1 = {bf_lo(gb.z), bf_hi(gb.z), bf_lo(gb.w), bf_hi(gb.w)};
; #pragma unroll
;                         for (int i = 0; i < 4; ++i) { acc[ai][bj][m][0][i] *= b0[i] * __builtin_amdgcn_rcpf(a0[i]); acc[ai][bj][m][1][i] *= b1[i] * __builtin_amdgcn_rcpf(a1[i]); }
.LBB0_1513:
	s_andn2_b64 vcc, exec, s[40:41]
	s_cbranch_vccnz .LBB0_1515
	v_rcp_f32_e32 v148, v148
	v_rcp_f32_e32 v146, v146
	v_rcp_f32_e32 v149, v149
	v_rcp_f32_e32 v147, v147
	v_rcp_f32_e32 v140, v140
	v_rcp_f32_e32 v138, v138
	v_rcp_f32_e32 v141, v141
	v_rcp_f32_e32 v139, v139
	s_waitcnt vmcnt(0)
	v_mov_b32_e32 v142, v232
	v_mov_b32_e32 v143, v233
	v_mov_b32_e32 v144, v234
	v_mov_b32_e32 v145, v235
	v_lshlrev_b32_e32 v150, 16, v142
	v_and_b32_e32 v151, 0xffff0000, v142
	v_lshlrev_b32_e32 v152, 16, v144
	v_and_b32_e32 v153, 0xffff0000, v144
	v_lshlrev_b32_e32 v142, 16, v143
	v_and_b32_e32 v143, 0xffff0000, v143
	v_lshlrev_b32_e32 v144, 16, v145
	v_and_b32_e32 v145, 0xffff0000, v145
	v_pk_mul_f32 v[148:149], v[148:149], v[150:151]
	v_pk_mul_f32 v[146:147], v[146:147], v[152:153]
	v_pk_mul_f32 v[140:141], v[140:141], v[142:143]
	v_pk_mul_f32 v[138:139], v[138:139], v[144:145]
	v_pk_mul_f32 v[78:79], v[78:79], v[148:149]
	v_pk_mul_f32 v[74:75], v[74:75], v[146:147]
	v_pk_mul_f32 v[80:81], v[80:81], v[140:141]
	v_pk_mul_f32 v[76:77], v[76:77], v[138:139]

; __device__ __forceinline__ float bf_lo(unsigned w) { return __uint_as_float(w << 16); }
; __device__ __forceinline__ float bf_hi(unsigned w) { return __uint_as_float(w & 0xffff0000u); }
;     __device__ __forceinline__ void operator()(f32x4 (&acc)[2][2][4][2], const Unit& u, int wr, int wc, int fr, int fq) const {
;     ...
;                     if (pn < 4) {
;                         const u32x4 gb = *(const u32x4*)(GB + ro + bj * HALF);
;                         const f32x4 b0 = {bf_lo(gb.x), bf_hi(gb.x), bf_lo(gb.y), bf_hi(gb.y)}, b1 = {bf_lo(gb.z), bf_hi(gb.z), bf_lo(gb.w), bf_hi(gb.w)};
; #pragma unroll
;                         for (int i = 0; i < 4; ++i) { acc[ai][bj][m][0][i] *= b0[i] * __builtin_amdgcn_rcpf(a0[i]); acc[ai][bj][m][1][i] *= b1[i] * __builtin_amdgcn_rcpf(a1[i]); }
.LBB0_1517:
	s_andn2_b64 vcc, exec, s[40:41]
	v_lshl_add_u64 v[136:137], v[146:147], 1, s[16:17]
	s_cbranch_vccnz .LBB0_1519
	v_rcp_f32_e32 v144, v144
	v_rcp_f32_e32 v142, v142
	v_rcp_f32_e32 v145, v145
	v_rcp_f32_e32 v143, v143
	v_rcp_f32_e32 v140, v140
	v_rcp_f32_e32 v138, v138
	v_rcp_f32_e32 v141, v141
	v_rcp_f32_e32 v139, v139
	s_waitcnt vmcnt(0)
	v_mov_b32_e32 v146, v236
	v_mov_b32_e32 v147, v237
	v_mov_b32_e32 v148, v238
	v_mov_b32_e32 v149, v239
	v_lshlrev_b32_e32 v150, 16, v146
	v_and_b32_e32 v151, 0xffff0000, v146
	v_lshlrev_b32_e32 v152, 16, v148
	v_and_b32_e32 v153, 0xffff0000, v148
	v_lshlrev_b32_e32 v146, 16, v147
	v_and_b32_e32 v147, 0xffff0000, v147
	v_lshlrev_b32_e32 v148, 16, v149
	v_and_b32_e32 v149, 0xffff0000, v149
	v_pk_mul_f32 v[144:145], v[144:145], v[150:151]
	v_pk_mul_f32 v[142:143], v[142:143], v[152:153]
	v_pk_mul_f32 v[140:141], v[140:141], v[146:147]
	v_pk_mul_f32 v[138:139], v[138:139], v[148:149]
	v_pk_mul_f32 v[102:103], v[102:103], v[144:145]
	v_pk_mul_f32 v[98:99], v[98:99], v[142:143]
	v_pk_mul_f32 v[104:105], v[104:105], v[140:141]
	v_pk_mul_f32 v[100:101], v[100:101], v[138:139]

; __device__ __forceinline__ float bf_lo(unsigned w) { return __uint_as_float(w << 16); }
; __device__ __forceinline__ float bf_hi(unsigned w) { return __uint_as_float(w & 0xffff0000u); }
; __device__ __forceinline__ u32x4 pack8(f32x4 v0, f32x4 v1) { u32x4 w; w.x = cvt_pk_bf16(v0[0], v0[1]); w.y = cvt_pk_bf16(v0[2], v0[3]); w.z = cvt_pk_bf16(v1[0], v1[1]); w.w = cvt_pk_bf16(v1[2], v1[3]); return w; }
;     __device__ __forceinline__ void operator()(f32x4 (&acc)[2][2][4][2], const Unit& u, int wr, int wc, int fr, int fq) const {
;     ...
;         for (int ai = 0; ai < 2; ++ai) {
;             u32x4 gaq[4][2];
; #pragma unroll
;             for (int m = 0; m < 4; ++m)
; #pragma unroll
;                 for (int bj = 0; bj < 2; ++bj) gaq[m][bj] = *(const u32x4*)(GA + (size_t)(row0 + ai * HALF + m * 16) * 1024 + co + bj * HALF);
; #pragma unroll
;             for (int m = 0; m < 4; ++m) {
;                 const size_t ro = (size_t)(row0 + ai * HALF + m * 16) * 1024 + co;
; #pragma unroll
;                 for (int bj = 0; bj < 2; ++bj) {
;                     const u32x4 ga = gaq[m][bj];
;                     f32x4 a0 = {bf_lo(ga.x), bf_hi(ga.x), bf_lo(ga.y), bf_hi(ga.y)}, a1 = {bf_lo(ga.z), bf_hi(ga.z), bf_lo(ga.w), bf_hi(ga.w)};
; #pragma unroll
;                     for (int i = 0; i < 4; ++i) { a0[i] = fmaxf(a0[i], 1e-20f); a1[i] = fmaxf(a1[i], 1e-20f); }
;                     if (pn < 4) {
;                         const u32x4 gb = *(const u32x4*)(GB + ro + bj * HALF);
;                         const f32x4 b0 = {bf_lo(gb.x), bf_hi(gb.x), bf_lo(gb.y), bf_hi(gb.y)}, b1 = {bf_lo(gb.z), bf_hi(gb.z), bf_lo(gb.w), bf_hi(gb.w)};
; #pragma unroll
;                         for (int i = 0; i < 4; ++i) { acc[ai][bj][m][0][i] *= b0[i] * __builtin_amdgcn_rcpf(a0[i]); acc[ai][bj][m][1][i] *= b1[i] * __builtin_amdgcn_rcpf(a1[i]); }
;                     } else {
;                         *(u32x4*)(MG + ro + bj * HALF) = pack8(acc[ai][bj][m][0] * a0, acc[ai][bj][m][1] * a1);
.LBB0_1521:
	s_andn2_b64 vcc, exec, s[40:41]
	s_cbranch_vccnz .LBB0_1523
	v_rcp_f32_e32 v140, v140
	v_rcp_f32_e32 v138, v138
	v_rcp_f32_e32 v141, v141
	v_rcp_f32_e32 v139, v139
	v_rcp_f32_e32 v132, v132
	v_rcp_f32_e32 v130, v130
	v_rcp_f32_e32 v133, v133
	v_rcp_f32_e32 v131, v131
	s_waitcnt vmcnt(0)
	v_mov_b32_e32 v134, v240
	v_mov_b32_e32 v135, v241
	v_mov_b32_e32 v136, v242
	v_mov_b32_e32 v137, v243
	v_lshlrev_b32_e32 v142, 16, v134
	v_and_b32_e32 v143, 0xffff0000, v134
	v_lshlrev_b32_e32 v144, 16, v136
	v_and_b32_e32 v145, 0xffff0000, v136
	v_lshlrev_b32_e32 v134, 16, v135
	v_and_b32_e32 v135, 0xffff0000, v135
	v_lshlrev_b32_e32 v136, 16, v137
	v_and_b32_e32 v137, 0xffff0000, v137
	v_pk_mul_f32 v[140:141], v[140:141], v[142:143]
	v_pk_mul_f32 v[138:139], v[138:139], v[144:145]
	v_pk_mul_f32 v[132:133], v[132:133], v[134:135]
	v_pk_mul_f32 v[130:131], v[130:131], v[136:137]
	v_pk_mul_f32 v[70:71], v[70:71], v[140:141]
	v_pk_mul_f32 v[66:67], v[66:67], v[138:139]
	v_pk_mul_f32 v[72:73], v[72:73], v[132:133]
	v_pk_mul_f32 v[68:69], v[68:69], v[130:131]
.LBB0_1523:
	v_add_u32_e32 v184, 0x80, v178
	v_add_u32_e32 v182, 0x90, v178
	v_add_u32_e32 v180, 0xa0, v178
	v_ashrrev_i32_e32 v185, 31, v184
	v_add_u32_e32 v178, 0xb0, v178
	v_ashrrev_i32_e32 v183, 31, v182
	v_ashrrev_i32_e32 v181, 31, v180
	v_lshlrev_b64 v[130:131], 11, v[184:185]
	v_ashrrev_i32_e32 v179, 31, v178
	v_lshlrev_b64 v[132:133], 11, v[182:183]
	v_lshlrev_b64 v[134:135], 11, v[180:181]
	v_lshl_add_u64 v[130:131], v[176:177], 0, v[130:131]
	v_lshlrev_b64 v[136:137], 11, v[178:179]
	v_lshl_add_u64 v[132:133], v[176:177], 0, v[132:133]
	v_lshl_add_u64 v[134:135], v[176:177], 0, v[134:135]
	global_load_dwordx4 v[186:189], v[130:131], off
	v_lshl_add_u64 v[176:177], v[176:177], 0, v[136:137]
	global_load_dwordx4 v[154:157], v[130:131], off offset:256
	global_load_dwordx4 v[150:153], v[132:133], off
	global_load_dwordx4 v[146:149], v[132:133], off offset:256
	global_load_dwordx4 v[142:145], v[134:135], off
	global_load_dwordx4 v[138:141], v[134:135], off offset:256
	s_cmp_gt_i32 s40, 3
	s_cbranch_scc1 .Lgbskip_1_1
	s_sub_u32 s98, s16, s14
	s_subb_u32 s99, s17, s15
	v_lshl_add_u64 v[244:245], v[130:131], 0, s[98:99]
	global_load_dwordx4 v[212:215], v[244:245], off
	global_load_dwordx4 v[216:219], v[244:245], off offset:256
	v_lshl_add_u64 v[244:245], v[132:133], 0, s[98:99]
	global_load_dwordx4 v[220:223], v[244:245], off
	global_load_dwordx4 v[224:227], v[244:245], off offset:256
	v_lshl_add_u64 v[244:245], v[134:135], 0, s[98:99]
	global_load_dwordx4 v[228:231], v[244:245], off
	global_load_dwordx4 v[232:235], v[244:245], off offset:256
	v_lshl_add_u64 v[244:245], v[176:177], 0, s[98:99]
	global_load_dwordx4 v[236:239], v[244:245], off
	global_load_dwordx4 v[240:243], v[244:245], off offset:256
.Lgbskip_1_1:
	s_nop 0
	global_load_dwordx4 v[134:137], v[176:177], off
	global_load_dwordx4 v[130:133], v[176:177], off offset:256
	v_lshlrev_b64 v[184:185], 10, v[184:185]
	v_or_b32_e32 v184, v184, v202
	s_mov_b64 s[40:41], -1
	s_and_b64 vcc, exec, s[8:9]
	s_waitcnt vmcnt(7)
	v_lshlrev_b32_e32 v166, 16, v186
	v_and_b32_e32 v176, 0xffff0000, v186
	v_lshlrev_b32_e32 v177, 16, v187
	v_and_b32_e32 v186, 0xffff0000, v187
	v_lshlrev_b32_e32 v187, 16, v188
	v_and_b32_e32 v188, 0xffff0000, v188
	v_lshlrev_b32_e32 v190, 16, v189
	v_and_b32_e32 v189, 0xffff0000, v189
	v_max_f32_e32 v166, v166, v166
	v_max_f32_e32 v187, v187, v187
	v_max_f32_e32 v176, v176, v176
	v_max_f32_e32 v188, v188, v188
	v_max_f32_e32 v177, v177, v177
	v_max_f32_e32 v194, v190, v190
	v_max_f32_e32 v195, v186, v186
	v_max_f32_e32 v196, v189, v189
	v_max_f32_e32 v192, 0x1e3ce508, v166
	v_max_f32_e32 v190, 0x1e3ce508, v187
	v_max_f32_e32 v193, 0x1e3ce508, v176
	v_max_f32_e32 v191, 0x1e3ce508, v188
	v_max_f32_e32 v188, 0x1e3ce508, v177
	v_max_f32_e32 v186, 0x1e3ce508, v194
	v_max_f32_e32 v189, 0x1e3ce508, v195
	v_max_f32_e32 v187, 0x1e3ce508, v196
	v_lshl_add_u64 v[176:177], v[184:185], 1, s[12:13]
	s_cbranch_vccnz .LBB0_1525
	v_pk_mul_f32 v[196:197], v[64:65], v[188:189]
	v_pk_mul_f32 v[194:195], v[62:63], v[192:193]
	s_mov_b64 s[40:41], 0
	v_pk_mul_f32 v[204:205], v[60:61], v[186:187]
	v_pk_mul_f32 v[206:207], v[58:59], v[190:191]
	v_cvt_pk_bf16_f32 v194, v194, v195
	v_cvt_pk_bf16_f32 v195, v196, v197
	s_nop 0
	v_cvt_pk_bf16_f32 v196, v206, v207
	v_cvt_pk_bf16_f32 v197, v204, v205
	global_store_dwordx4 v[176:177], v[194:197], off
.LBB0_1525:
	s_andn2_b64 vcc, exec, s[40:41]
	v_lshl_add_u64 v[184:185], v[184:185], 1, s[16:17]
	s_cbranch_vccnz .LBB0_1527
	v_rcp_f32_e32 v192, v192
	v_rcp_f32_e32 v190, v190
	v_rcp_f32_e32 v193, v193
	v_rcp_f32_e32 v191, v191
	v_rcp_f32_e32 v188, v188
	v_rcp_f32_e32 v186, v186
	v_rcp_f32_e32 v189, v189
	v_rcp_f32_e32 v187, v187
	s_waitcnt vmcnt(0)
	v_mov_b32_e32 v194, v212
	v_mov_b32_e32 v195, v213
	v_mov_b32_e32 v196, v214
	v_mov_b32_e32 v197, v215
	v_lshlrev_b32_e32 v204, 16, v194
	v_and_b32_e32 v205, 0xffff0000, v194
	v_lshlrev_b32_e32 v206, 16, v196
	v_and_b32_e32 v207, 0xffff0000, v196
	v_lshlrev_b32_e32 v194, 16, v195
	v_and_b32_e32 v195, 0xffff0000, v195
	v_lshlrev_b32_e32 v196, 16, v197
	v_and_b32_e32 v197, 0xffff0000, v197
	v_pk_mul_f32 v[192:193], v[192:193], v[204:205]
	v_pk_mul_f32 v[190:191], v[190:191], v[206:207]
	v_pk_mul_f32 v[188:189], v[188:189], v[194:195]
	v_pk_mul_f32 v[186:187], v[186:187], v[196:197]
	v_pk_mul_f32 v[62:63], v[62:63], v[192:193]
	v_pk_mul_f32 v[58:59], v[58:59], v[190:191]
	v_pk_mul_f32 v[64:65], v[64:65], v[188:189]
	v_pk_mul_f32 v[60:61], v[60:61], v[186:187]

; __device__ __forceinline__ float bf_lo(unsigned w) { return __uint_as_float(w << 16); }
; __device__ __forceinline__ float bf_hi(unsigned w) { return __uint_as_float(w & 0xffff0000u); }
;     __device__ __forceinline__ void operator()(f32x4 (&acc)[2][2][4][2], const Unit& u, int wr, int wc, int fr, int fq) const {
;     ...
;                     if (pn < 4) {
;                         const u32x4 gb = *(const u32x4*)(GB + ro + bj * HALF);
;                         const f32x4 b0 = {bf_lo(gb.x), bf_hi(gb.x), bf_lo(gb.y), bf_hi(gb.y)}, b1 = {bf_lo(gb.z), bf_hi(gb.z), bf_lo(gb.w), bf_hi(gb.w)};
; #pragma unroll
;                         for (int i = 0; i < 4; ++i) { acc[ai][bj][m][0][i] *= b0[i] * __builtin_amdgcn_rcpf(a0[i]); acc[ai][bj][m][1][i] *= b1[i] * __builtin_amdgcn_rcpf(a1[i]); }
.LBB0_1529:
	s_andn2_b64 vcc, exec, s[40:41]
	s_cbranch_vccnz .LBB0_1531
	v_rcp_f32_e32 v176, v188
	v_rcp_f32_e32 v184, v186
	v_rcp_f32_e32 v177, v189
	v_rcp_f32_e32 v185, v187
	v_rcp_f32_e32 v156, v156
	v_rcp_f32_e32 v154, v154
	v_rcp_f32_e32 v157, v157
	v_rcp_f32_e32 v155, v155
	s_waitcnt vmcnt(0)
	v_mov_b32_e32 v190, v216
	v_mov_b32_e32 v191, v217
	v_mov_b32_e32 v192, v218
	v_mov_b32_e32 v193, v219
	v_lshlrev_b32_e32 v186, 16, v190
	v_and_b32_e32 v187, 0xffff0000, v190
	v_lshlrev_b32_e32 v188, 16, v192
	v_and_b32_e32 v189, 0xffff0000, v192
	v_lshlrev_b32_e32 v190, 16, v191
	v_and_b32_e32 v191, 0xffff0000, v191
	v_lshlrev_b32_e32 v192, 16, v193
	v_and_b32_e32 v193, 0xffff0000, v193
	v_pk_mul_f32 v[176:177], v[176:177], v[186:187]
	v_pk_mul_f32 v[184:185], v[184:185], v[188:189]
	v_pk_mul_f32 v[156:157], v[156:157], v[190:191]
	v_pk_mul_f32 v[154:155], v[154:155], v[192:193]
	v_pk_mul_f32 v[30:31], v[30:31], v[176:177]
	v_pk_mul_f32 v[26:27], v[26:27], v[184:185]
	v_pk_mul_f32 v[32:33], v[32:33], v[156:157]
	v_pk_mul_f32 v[28:29], v[28:29], v[154:155]

; __device__ __forceinline__ float bf_lo(unsigned w) { return __uint_as_float(w << 16); }
; __device__ __forceinline__ float bf_hi(unsigned w) { return __uint_as_float(w & 0xffff0000u); }
;     __device__ __forceinline__ void operator()(f32x4 (&acc)[2][2][4][2], const Unit& u, int wr, int wc, int fr, int fq) const {
;     ...
;                     if (pn < 4) {
;                         const u32x4 gb = *(const u32x4*)(GB + ro + bj * HALF);
;                         const f32x4 b0 = {bf_lo(gb.x), bf_hi(gb.x), bf_lo(gb.y), bf_hi(gb.y)}, b1 = {bf_lo(gb.z), bf_hi(gb.z), bf_lo(gb.w), bf_hi(gb.w)};
; #pragma unroll
;                         for (int i = 0; i < 4; ++i) { acc[ai][bj][m][0][i] *= b0[i] * __builtin_amdgcn_rcpf(a0[i]); acc[ai][bj][m][1][i] *= b1[i] * __builtin_amdgcn_rcpf(a1[i]); }
.LBB0_1533:
	s_andn2_b64 vcc, exec, s[40:41]
	v_lshl_add_u64 v[152:153], v[184:185], 1, s[16:17]
	s_cbranch_vccnz .LBB0_1535
	v_rcp_f32_e32 v182, v182
	v_rcp_f32_e32 v176, v176
	v_rcp_f32_e32 v183, v183
	v_rcp_f32_e32 v177, v177
	v_rcp_f32_e32 v156, v156
	v_rcp_f32_e32 v154, v154
	v_rcp_f32_e32 v157, v157
	v_rcp_f32_e32 v155, v155
	s_waitcnt vmcnt(0)
	v_mov_b32_e32 v184, v220
	v_mov_b32_e32 v185, v221
	v_mov_b32_e32 v186, v222
	v_mov_b32_e32 v187, v223
	v_lshlrev_b32_e32 v188, 16, v184
	v_and_b32_e32 v189, 0xffff0000, v184
	v_lshlrev_b32_e32 v190, 16, v186
	v_and_b32_e32 v191, 0xffff0000, v186
	v_lshlrev_b32_e32 v184, 16, v185
	v_and_b32_e32 v185, 0xffff0000, v185
	v_lshlrev_b32_e32 v186, 16, v187
	v_and_b32_e32 v187, 0xffff0000, v187
	v_pk_mul_f32 v[182:183], v[182:183], v[188:189]
	v_pk_mul_f32 v[176:177], v[176:177], v[190:191]
	v_pk_mul_f32 v[156:157], v[156:157], v[184:185]
	v_pk_mul_f32 v[154:155], v[154:155], v[186:187]
	v_pk_mul_f32 v[54:55], v[54:55], v[182:183]
	v_pk_mul_f32 v[50:51], v[50:51], v[176:177]
	v_pk_mul_f32 v[56:57], v[56:57], v[156:157]
	v_pk_mul_f32 v[52:53], v[52:53], v[154:155]

; __device__ __forceinline__ float bf_lo(unsigned w) { return __uint_as_float(w << 16); }
; __device__ __forceinline__ float bf_hi(unsigned w) { return __uint_as_float(w & 0xffff0000u); }
;     __device__ __forceinline__ void operator()(f32x4 (&acc)[2][2][4][2], const Unit& u, int wr, int wc, int fr, int fq) const {
;     ...
;                     if (pn < 4) {
;                         const u32x4 gb = *(const u32x4*)(GB + ro + bj * HALF);
;                         const f32x4 b0 = {bf_lo(gb.x), bf_hi(gb.x), bf_lo(gb.y), bf_hi(gb.y)}, b1 = {bf_lo(gb.z), bf_hi(gb.z), bf_lo(gb.w), bf_hi(gb.w)};
; #pragma unroll
;                         for (int i = 0; i < 4; ++i) { acc[ai][bj][m][0][i] *= b0[i] * __builtin_amdgcn_rcpf(a0[i]); acc[ai][bj][m][1][i] *= b1[i] * __builtin_amdgcn_rcpf(a1[i]); }
.LBB0_1537:
	s_andn2_b64 vcc, exec, s[40:41]
	s_cbranch_vccnz .LBB0_1539
	v_rcp_f32_e32 v156, v156
	v_rcp_f32_e32 v154, v154
	v_rcp_f32_e32 v157, v157
	v_rcp_f32_e32 v155, v155
	v_rcp_f32_e32 v148, v148
	v_rcp_f32_e32 v146, v146
	v_rcp_f32_e32 v149, v149
	v_rcp_f32_e32 v147, v147
	s_waitcnt vmcnt(0)
	v_mov_b32_e32 v150, v224
	v_mov_b32_e32 v151, v225
	v_mov_b32_e32 v152, v226
	v_mov_b32_e32 v153, v227
	v_lshlrev_b32_e32 v176, 16, v150
	v_and_b32_e32 v177, 0xffff0000, v150
	v_lshlrev_b32_e32 v182, 16, v152
	v_and_b32_e32 v183, 0xffff0000, v152
	v_lshlrev_b32_e32 v150, 16, v151
	v_and_b32_e32 v151, 0xffff0000, v151
	v_lshlrev_b32_e32 v152, 16, v153
	v_and_b32_e32 v153, 0xffff0000, v153
	v_pk_mul_f32 v[156:157], v[156:157], v[176:177]
	v_pk_mul_f32 v[154:155], v[154:155], v[182:183]
	v_pk_mul_f32 v[148:149], v[148:149], v[150:151]
	v_pk_mul_f32 v[146:147], v[146:147], v[152:153]
	v_pk_mul_f32 v[22:23], v[22:23], v[156:157]
	v_pk_mul_f32 v[18:19], v[18:19], v[154:155]
	v_pk_mul_f32 v[24:25], v[24:25], v[148:149]
	v_pk_mul_f32 v[20:21], v[20:21], v[146:147]

; __device__ __forceinline__ float bf_lo(unsigned w) { return __uint_as_float(w << 16); }
; __device__ __forceinline__ float bf_hi(unsigned w) { return __uint_as_float(w & 0xffff0000u); }
;     __device__ __forceinline__ void operator()(f32x4 (&acc)[2][2][4][2], const Unit& u, int wr, int wc, int fr, int fq) const {
;     ...
;                     if (pn < 4) {
;                         const u32x4 gb = *(const u32x4*)(GB + ro + bj * HALF);
;                         const f32x4 b0 = {bf_lo(gb.x), bf_hi(gb.x), bf_lo(gb.y), bf_hi(gb.y)}, b1 = {bf_lo(gb.z), bf_hi(gb.z), bf_lo(gb.w), bf_hi(gb.w)};
; #pragma unroll
;                         for (int i = 0; i < 4; ++i) { acc[ai][bj][m][0][i] *= b0[i] * __builtin_amdgcn_rcpf(a0[i]); acc[ai][bj][m][1][i] *= b1[i] * __builtin_amdgcn_rcpf(a1[i]); }
.LBB0_1541:
	s_andn2_b64 vcc, exec, s[40:41]
	v_lshl_add_u64 v[144:145], v[154:155], 1, s[16:17]
	s_cbranch_vccnz .LBB0_1543
	v_rcp_f32_e32 v152, v152
	v_rcp_f32_e32 v150, v150
	v_rcp_f32_e32 v153, v153
	v_rcp_f32_e32 v151, v151
	v_rcp_f32_e32 v148, v148
	v_rcp_f32_e32 v146, v146
	v_rcp_f32_e32 v149, v149
	v_rcp_f32_e32 v147, v147
	s_waitcnt vmcnt(0)
	v_mov_b32_e32 v154, v228
	v_mov_b32_e32 v155, v229
	v_mov_b32_e32 v156, v230
	v_mov_b32_e32 v157, v231
	v_lshlrev_b32_e32 v176, 16, v154
	v_and_b32_e32 v177, 0xffff0000, v154
	v_lshlrev_b32_e32 v180, 16, v156
	v_and_b32_e32 v181, 0xffff0000, v156
	v_lshlrev_b32_e32 v154, 16, v155
	v_and_b32_e32 v155, 0xffff0000, v155
	v_lshlrev_b32_e32 v156, 16, v157
	v_and_b32_e32 v157, 0xffff0000, v157
	v_pk_mul_f32 v[152:153], v[152:153], v[176:177]
	v_pk_mul_f32 v[150:151], v[150:151], v[180:181]
	v_pk_mul_f32 v[148:149], v[148:149], v[154:155]
	v_pk_mul_f32 v[146:147], v[146:147], v[156:157]
	v_pk_mul_f32 v[46:47], v[46:47], v[152:153]
	v_pk_mul_f32 v[42:43], v[42:43], v[150:151]
	v_pk_mul_f32 v[48:49], v[48:49], v[148:149]
	v_pk_mul_f32 v[44:45], v[44:45], v[146:147]

; __device__ __forceinline__ float bf_lo(unsigned w) { return __uint_as_float(w << 16); }
; __device__ __forceinline__ float bf_hi(unsigned w) { return __uint_as_float(w & 0xffff0000u); }
;     __device__ __forceinline__ void operator()(f32x4 (&acc)[2][2][4][2], const Unit& u, int wr, int wc, int fr, int fq) const {
;     ...
;                     if (pn < 4) {
;                         const u32x4 gb = *(const u32x4*)(GB + ro + bj * HALF);
;                         const f32x4 b0 = {bf_lo(gb.x), bf_hi(gb.x), bf_lo(gb.y), bf_hi(gb.y)}, b1 = {bf_lo(gb.z), bf_hi(gb.z), bf_lo(gb.w), bf_hi(gb.w)};
; #pragma unroll
;                         for (int i = 0; i < 4; ++i) { acc[ai][bj][m][0][i] *= b0[i] * __builtin_amdgcn_rcpf(a0[i]); acc[ai][bj][m][1][i] *= b1[i] * __builtin_amdgcn_rcpf(a1[i]); }
.LBB0_1545:
	s_andn2_b64 vcc, exec, s[40:41]
	s_cbranch_vccnz .LBB0_1547
	v_rcp_f32_e32 v148, v148
	v_rcp_f32_e32 v146, v146
	v_rcp_f32_e32 v149, v149
	v_rcp_f32_e32 v147, v147
	v_rcp_f32_e32 v140, v140
	v_rcp_f32_e32 v138, v138
	v_rcp_f32_e32 v141, v141
	v_rcp_f32_e32 v139, v139
	s_waitcnt vmcnt(0)
	v_mov_b32_e32 v142, v232
	v_mov_b32_e32 v143, v233
	v_mov_b32_e32 v144, v234
	v_mov_b32_e32 v145, v235
	v_lshlrev_b32_e32 v150, 16, v142
	v_and_b32_e32 v151, 0xffff0000, v142
	v_lshlrev_b32_e32 v152, 16, v144
	v_and_b32_e32 v153, 0xffff0000, v144
	v_lshlrev_b32_e32 v142, 16, v143
	v_and_b32_e32 v143, 0xffff0000, v143
	v_lshlrev_b32_e32 v144, 16, v145
	v_and_b32_e32 v145, 0xffff0000, v145
	v_pk_mul_f32 v[148:149], v[148:149], v[150:151]
	v_pk_mul_f32 v[146:147], v[146:147], v[152:153]
	v_pk_mul_f32 v[140:141], v[140:141], v[142:143]
	v_pk_mul_f32 v[138:139], v[138:139], v[144:145]
	v_pk_mul_f32 v[14:15], v[14:15], v[148:149]
	v_pk_mul_f32 v[10:11], v[10:11], v[146:147]
	v_pk_mul_f32 v[16:17], v[16:17], v[140:141]
	v_pk_mul_f32 v[12:13], v[12:13], v[138:139]

; __device__ __forceinline__ float bf_lo(unsigned w) { return __uint_as_float(w << 16); }
; __device__ __forceinline__ float bf_hi(unsigned w) { return __uint_as_float(w & 0xffff0000u); }
;     __device__ __forceinline__ void operator()(f32x4 (&acc)[2][2][4][2], const Unit& u, int wr, int wc, int fr, int fq) const {
;     ...
;                     if (pn < 4) {
;                         const u32x4 gb = *(const u32x4*)(GB + ro + bj * HALF);
;                         const f32x4 b0 = {bf_lo(gb.x), bf_hi(gb.x), bf_lo(gb.y), bf_hi(gb.y)}, b1 = {bf_lo(gb.z), bf_hi(gb.z), bf_lo(gb.w), bf_hi(gb.w)};
; #pragma unroll
;                         for (int i = 0; i < 4; ++i) { acc[ai][bj][m][0][i] *= b0[i] * __builtin_amdgcn_rcpf(a0[i]); acc[ai][bj][m][1][i] *= b1[i] * __builtin_amdgcn_rcpf(a1[i]); }
.LBB0_1549:
	s_andn2_b64 vcc, exec, s[40:41]
	v_lshl_add_u64 v[136:137], v[146:147], 1, s[16:17]
	s_cbranch_vccnz .LBB0_1551
	v_rcp_f32_e32 v144, v144
	v_rcp_f32_e32 v142, v142
	v_rcp_f32_e32 v145, v145
	v_rcp_f32_e32 v143, v143
	v_rcp_f32_e32 v140, v140
	v_rcp_f32_e32 v138, v138
	v_rcp_f32_e32 v141, v141
	v_rcp_f32_e32 v139, v139
	s_waitcnt vmcnt(0)
	v_mov_b32_e32 v146, v236
	v_mov_b32_e32 v147, v237
	v_mov_b32_e32 v148, v238
	v_mov_b32_e32 v149, v239
	v_lshlrev_b32_e32 v150, 16, v146
	v_and_b32_e32 v151, 0xffff0000, v146
	v_lshlrev_b32_e32 v152, 16, v148
	v_and_b32_e32 v153, 0xffff0000, v148
	v_lshlrev_b32_e32 v146, 16, v147
	v_and_b32_e32 v147, 0xffff0000, v147
	v_lshlrev_b32_e32 v148, 16, v149
	v_and_b32_e32 v149, 0xffff0000, v149
	v_pk_mul_f32 v[144:145], v[144:145], v[150:151]
	v_pk_mul_f32 v[142:143], v[142:143], v[152:153]
	v_pk_mul_f32 v[140:141], v[140:141], v[146:147]
	v_pk_mul_f32 v[138:139], v[138:139], v[148:149]
	v_pk_mul_f32 v[38:39], v[38:39], v[144:145]
	v_pk_mul_f32 v[34:35], v[34:35], v[142:143]
	v_pk_mul_f32 v[40:41], v[40:41], v[140:141]
	v_pk_mul_f32 v[36:37], v[36:37], v[138:139]

; __device__ __forceinline__ float bf_lo(unsigned w) { return __uint_as_float(w << 16); }
; __device__ __forceinline__ float bf_hi(unsigned w) { return __uint_as_float(w & 0xffff0000u); }
;     __device__ __forceinline__ void operator()(f32x4 (&acc)[2][2][4][2], const Unit& u, int wr, int wc, int fr, int fq) const {
;     ...
;                     if (pn < 4) {
;                         const u32x4 gb = *(const u32x4*)(GB + ro + bj * HALF);
;                         const f32x4 b0 = {bf_lo(gb.x), bf_hi(gb.x), bf_lo(gb.y), bf_hi(gb.y)}, b1 = {bf_lo(gb.z), bf_hi(gb.z), bf_lo(gb.w), bf_hi(gb.w)};
; #pragma unroll
;                         for (int i = 0; i < 4; ++i) { acc[ai][bj][m][0][i] *= b0[i] * __builtin_amdgcn_rcpf(a0[i]); acc[ai][bj][m][1][i] *= b1[i] * __builtin_amdgcn_rcpf(a1[i]); }
.LBB0_1555:
	v_rcp_f32_e32 v140, v140
	v_rcp_f32_e32 v138, v138
	v_rcp_f32_e32 v141, v141
	v_rcp_f32_e32 v139, v139
	v_rcp_f32_e32 v132, v132
	v_rcp_f32_e32 v130, v130
	v_rcp_f32_e32 v133, v133
	v_rcp_f32_e32 v131, v131
	s_waitcnt vmcnt(0)
	v_mov_b32_e32 v134, v240
	v_mov_b32_e32 v135, v241
	v_mov_b32_e32 v136, v242
	v_mov_b32_e32 v137, v243
	v_lshlrev_b32_e32 v142, 16, v134
	v_and_b32_e32 v143, 0xffff0000, v134
	v_lshlrev_b32_e32 v144, 16, v136
	v_and_b32_e32 v145, 0xffff0000, v136
	v_lshlrev_b32_e32 v134, 16, v135
	v_and_b32_e32 v135, 0xffff0000, v135
	v_lshlrev_b32_e32 v136, 16, v137
	v_and_b32_e32 v137, 0xffff0000, v137
	v_pk_mul_f32 v[140:141], v[140:141], v[142:143]
	v_pk_mul_f32 v[138:139], v[138:139], v[144:145]
	v_pk_mul_f32 v[132:133], v[132:133], v[134:135]
	v_pk_mul_f32 v[130:131], v[130:131], v[136:137]
	v_pk_mul_f32 v[6:7], v[6:7], v[140:141]
	v_pk_mul_f32 v[2:3], v[2:3], v[138:139]
	v_pk_mul_f32 v[8:9], v[8:9], v[132:133]
	v_pk_mul_f32 v[4:5], v[4:5], v[130:131]
	s_and_b64 vcc, exec, s[6:7]
	s_mov_b64 s[6:7], -1
	s_cbranch_vccnz .LBB0_1478

; __device__ __forceinline__ float bf_lo(unsigned w) { return __uint_as_float(w << 16); }
; __device__ __forceinline__ float bf_hi(unsigned w) { return __uint_as_float(w & 0xffff0000u); }
;     __device__ __forceinline__ void fused(f32x4 (&acc)[2][2][4][2], const Unit& u, int wr, int wc, int fr, int fq, PG8_LAS unsigned char* lds, int wid, int lane) const {
;     ...
;         const int col0 = u.pn * BM + wc * 32 + 8 * fq, b = u.pm >> 4;
;         {
;             f32x4 gv[2][2];
; #pragma unroll
;             for (int bj = 0; bj < 2; ++bj)
; #pragma unroll
;                 for (int n = 0; n < 2; ++n) gv[bj][n] = *(const f32x4*)(g + (size_t)b * 6144 + col0 + bj * HALF + 4 * n);
; #pragma unroll
;             for (int ai = 0; ai < 2; ++ai)
; #pragma unroll
;                 for (int m = 0; m < 4; ++m) { const int r = ai * HALF + wr * 64 + m * 16 + fr; const size_t off = (size_t)(u.pm * BM + r) * 1024 + col0;
; #pragma unroll
;                     for (int bj = 0; bj < 2; ++bj) { f32x4 b0, b1;
;                         if (XIN_BF16) { const u32x4 w = *(const u32x4*)((const bf16_t*)xin + off + bj * HALF); b0 = (f32x4){bf_lo(w.x), bf_hi(w.x), bf_lo(w.y), bf_hi(w.y)}; b1 = (f32x4){bf_lo(w.z), bf_hi(w.z), bf_lo(w.w), bf_hi(w.w)}; }
;                         else { b0 = *(const f32x4*)((const float*)xin + off + bj * HALF); b1 = *(const f32x4*)((const float*)xin + off + bj * HALF + 4); }
;                         acc[ai][bj][m][0] = b0 + gv[bj][0] * acc[ai][bj][m][0]; acc[ai][bj][m][1] = b1 + gv[bj][1] * acc[ai][bj][m][1]; }
.LBB0_1635:
	s_lshl_b32 s6, s19, 5
	s_lshl_b32 s7, s10, 8
	v_lshrrev_b32_e32 v130, 1, v168
	s_or_b32 s6, s7, s6
	v_and_or_b32 v156, v130, 24, s6
	s_ashr_i32 s6, s18, 4
	s_mul_i32 s34, s6, 0x6000
	s_mul_hi_i32 s25, s6, 0x6000
	s_add_u32 s6, s14, s34
	s_addc_u32 s7, s15, s25
	s_lshl_b32 s28, s18, 8
	v_add_u32_e32 v164, s28, v166
	v_ashrrev_i32_e32 v165, 31, v164
	v_ashrrev_i32_e32 v157, 31, v156
	v_lshlrev_b64 v[150:151], 11, v[164:165]
	v_lshl_add_u64 v[130:131], s[12:13], 0, v[150:151]
	v_lshlrev_b64 v[146:147], 1, v[156:157]
	v_lshl_add_u64 v[130:131], v[130:131], 0, v[146:147]
	v_lshl_add_u64 v[132:133], v[156:157], 2, s[6:7]
	s_mov_b32 s8, 0x1a000
	s_barrier
	s_mov_b64 s[98:99], 0x8000
	v_lshl_add_u64 v[244:245], v[130:131], 0, s[98:99]
	global_load_dwordx4 v[196:199], v[244:245], off
	global_load_dwordx4 v[200:203], v[244:245], off offset:256
	s_mov_b64 s[98:99], 0x10000
	v_lshl_add_u64 v[244:245], v[130:131], 0, s[98:99]
	global_load_dwordx4 v[204:207], v[244:245], off
	global_load_dwordx4 v[208:211], v[244:245], off offset:256
	s_mov_b64 s[98:99], 0x18000
	v_lshl_add_u64 v[244:245], v[130:131], 0, s[98:99]
	global_load_dwordx4 v[212:215], v[244:245], off
	global_load_dwordx4 v[216:219], v[244:245], off offset:256
	s_mov_b64 s[98:99], 0x40000
	v_lshl_add_u64 v[244:245], v[130:131], 0, s[98:99]
	global_load_dwordx4 v[220:223], v[244:245], off
	global_load_dwordx4 v[224:227], v[244:245], off offset:256
	s_mov_b64 s[98:99], 0x48000
	v_lshl_add_u64 v[244:245], v[130:131], 0, s[98:99]
	global_load_dwordx4 v[228:231], v[244:245], off
	global_load_dwordx4 v[232:235], v[244:245], off offset:256
	s_mov_b64 s[98:99], 0x50000
	v_lshl_add_u64 v[244:245], v[130:131], 0, s[98:99]
	global_load_dwordx4 v[236:239], v[244:245], off
	global_load_dwordx4 v[240:243], v[244:245], off offset:256
	s_mov_b64 s[98:99], 0x58000
	v_lshl_add_u64 v[244:245], v[130:131], 0, s[98:99]
	global_load_dwordx4 v[248:251], v[244:245], off
	global_load_dwordx4 v[252:255], v[244:245], off offset:256
	global_load_dwordx4 v[152:155], v[130:131], off
	global_load_dwordx4 v[158:161], v[130:131], off offset:256
	v_add_co_u32_e32 v130, vcc, s8, v132
	s_mov_b64 s[6:7], 0x1a000
	s_nop 0
	v_addc_co_u32_e32 v131, vcc, 0, v133, vcc
	global_load_dwordx4 v[138:141], v[130:131], off
	v_lshl_add_u64 v[130:131], v[132:133], 0, s[6:7]
	global_load_dwordx4 v[142:145], v[130:131], off offset:16
	global_load_dwordx4 v[134:137], v[130:131], off offset:512
	s_nop 0
	global_load_dwordx4 v[130:133], v[130:131], off offset:528
	v_add_u32_e32 v148, 16, v164
	v_ashrrev_i32_e32 v149, 31, v148
	v_lshlrev_b64 v[148:149], 11, v[148:149]
	v_lshl_add_u64 v[162:163], s[12:13], 0, v[148:149]
	v_lshl_add_u64 v[162:163], v[162:163], 0, v[146:147]
	v_mbcnt_hi_u32_b32 v192, -1, v1
	v_and_b32_e32 v169, 64, v192
	v_xor_b32_e32 v165, 16, v192
	v_add_u32_e32 v193, 64, v169
	v_cmp_lt_i32_e32 vcc, v165, v193
	s_lshl_b32 s6, s19, 3
	s_add_i32 s8, s6, 0
	v_cndmask_b32_e32 v165, v192, v165, vcc
	v_lshlrev_b32_e32 v169, 2, v165
	s_waitcnt vmcnt(0)
	v_lshlrev_b32_e32 v170, 16, v152
	v_and_b32_e32 v171, 0xffff0000, v152
	v_lshlrev_b32_e32 v152, 16, v153
	v_and_b32_e32 v153, 0xffff0000, v153
	v_lshlrev_b32_e32 v172, 16, v154
	v_and_b32_e32 v173, 0xffff0000, v154
	v_lshlrev_b32_e32 v154, 16, v155
	v_and_b32_e32 v155, 0xffff0000, v155
	v_lshlrev_b32_e32 v174, 16, v158
	v_and_b32_e32 v175, 0xffff0000, v158
	v_lshlrev_b32_e32 v158, 16, v159
	v_and_b32_e32 v159, 0xffff0000, v159
	v_lshlrev_b32_e32 v176, 16, v160
	v_and_b32_e32 v177, 0xffff0000, v160
	v_lshlrev_b32_e32 v160, 16, v161
	v_and_b32_e32 v161, 0xffff0000, v161
	v_pk_fma_f32 v[58:59], v[58:59], v[138:139], v[170:171]
	v_pk_fma_f32 v[60:61], v[60:61], v[140:141], v[152:153]
	v_pk_fma_f32 v[64:65], v[64:65], v[144:145], v[154:155]
	v_pk_fma_f32 v[62:63], v[62:63], v[142:143], v[172:173]
	v_pk_fma_f32 v[56:57], v[56:57], v[136:137], v[158:159]
	v_pk_fma_f32 v[54:55], v[54:55], v[134:135], v[174:175]
	v_pk_fma_f32 v[48:49], v[48:49], v[132:133], v[160:161]
	v_pk_fma_f32 v[46:47], v[46:47], v[130:131], v[176:177]
	v_add_u32_e32 v152, 32, v164
	v_mov_b32_e32 v158, v196
	v_mov_b32_e32 v159, v197
	v_mov_b32_e32 v160, v198
	v_mov_b32_e32 v161, v199
	v_mov_b32_e32 v170, v200
	v_mov_b32_e32 v171, v201
	v_mov_b32_e32 v172, v202
	v_mov_b32_e32 v173, v203
	v_ashrrev_i32_e32 v153, 31, v152
	v_lshlrev_b64 v[152:153], 11, v[152:153]
	v_lshl_add_u64 v[154:155], s[12:13], 0, v[152:153]
	v_lshl_add_u64 v[154:155], v[154:155], 0, v[146:147]
	s_waitcnt vmcnt(1)
	v_lshlrev_b32_e32 v162, 16, v158
	v_and_b32_e32 v163, 0xffff0000, v158
	v_lshlrev_b32_e32 v158, 16, v159
	v_and_b32_e32 v159, 0xffff0000, v159
	v_lshlrev_b32_e32 v174, 16, v160
	v_and_b32_e32 v175, 0xffff0000, v160
	v_lshlrev_b32_e32 v160, 16, v161
	v_and_b32_e32 v161, 0xffff0000, v161
	s_waitcnt vmcnt(0)
	v_lshlrev_b32_e32 v176, 16, v170
	v_and_b32_e32 v177, 0xffff0000, v170
	v_lshlrev_b32_e32 v170, 16, v171
	v_and_b32_e32 v171, 0xffff0000, v171
	v_lshlrev_b32_e32 v178, 16, v172
	v_and_b32_e32 v179, 0xffff0000, v172
	v_lshlrev_b32_e32 v172, 16, v173
	v_and_b32_e32 v173, 0xffff0000, v173
	v_pk_fma_f32 v[80:81], v[80:81], v[140:141], v[158:159]
	v_pk_fma_f32 v[78:79], v[78:79], v[138:139], v[162:163]
	v_pk_fma_f32 v[72:73], v[72:73], v[144:145], v[160:161]
	v_pk_fma_f32 v[70:71], v[70:71], v[142:143], v[174:175]
	v_pk_fma_f32 v[52:53], v[52:53], v[136:137], v[170:171]
	v_pk_fma_f32 v[50:51], v[50:51], v[134:135], v[176:177]
	v_pk_fma_f32 v[44:45], v[44:45], v[132:133], v[172:173]
	v_pk_fma_f32 v[42:43], v[42:43], v[130:131], v[178:179]
	s_nop 0
	v_mov_b32_e32 v158, v204
	v_mov_b32_e32 v159, v205
	v_mov_b32_e32 v160, v206
	v_mov_b32_e32 v161, v207
	v_mov_b32_e32 v170, v208
	v_mov_b32_e32 v171, v209
	v_mov_b32_e32 v172, v210
	v_mov_b32_e32 v173, v211
	v_add_u32_e32 v154, 48, v164
	v_ashrrev_i32_e32 v155, 31, v154
	v_lshlrev_b64 v[154:155], 11, v[154:155]
	v_lshl_add_u64 v[162:163], s[12:13], 0, v[154:155]
	v_lshl_add_u64 v[174:175], v[162:163], 0, v[146:147]
	s_waitcnt vmcnt(1)
; __device__ __forceinline__ float bf_lo(unsigned w) { return __uint_as_float(w << 16); }
; __device__ __forceinline__ float bf_hi(unsigned w) { return __uint_as_float(w & 0xffff0000u); }
;     __device__ __forceinline__ void fused(f32x4 (&acc)[2][2][4][2], const Unit& u, int wr, int wc, int fr, int fq, PG8_LAS unsigned char* lds, int wid, int lane) const {
;     ...
;             for (int ai = 0; ai < 2; ++ai)
; #pragma unroll
;                 for (int m = 0; m < 4; ++m) { const int r = ai * HALF + wr * 64 + m * 16 + fr; const size_t off = (size_t)(u.pm * BM + r) * 1024 + col0;
; #pragma unroll
;                     for (int bj = 0; bj < 2; ++bj) { f32x4 b0, b1;
;                         if (XIN_BF16) { const u32x4 w = *(const u32x4*)((const bf16_t*)xin + off + bj * HALF); b0 = (f32x4){bf_lo(w.x), bf_hi(w.x), bf_lo(w.y), bf_hi(w.y)}; b1 = (f32x4){bf_lo(w.z), bf_hi(w.z), bf_lo(w.w), bf_hi(w.w)}; }
;                         else { b0 = *(const f32x4*)((const float*)xin + off + bj * HALF); b1 = *(const f32x4*)((const float*)xin + off + bj * HALF + 4); }
;                         acc[ai][bj][m][0] = b0 + gv[bj][0] * acc[ai][bj][m][0]; acc[ai][bj][m][1] = b1 + gv[bj][1] * acc[ai][bj][m][1]; }
	v_lshlrev_b32_e32 v162, 16, v158
	v_and_b32_e32 v163, 0xffff0000, v158
	v_lshlrev_b32_e32 v158, 16, v159
	v_and_b32_e32 v159, 0xffff0000, v159
	v_lshlrev_b32_e32 v176, 16, v160
	v_and_b32_e32 v177, 0xffff0000, v160
	v_lshlrev_b32_e32 v160, 16, v161
	v_and_b32_e32 v161, 0xffff0000, v161
	s_waitcnt vmcnt(0)
	v_lshlrev_b32_e32 v178, 16, v170
	v_and_b32_e32 v179, 0xffff0000, v170
	v_lshlrev_b32_e32 v170, 16, v171
	v_and_b32_e32 v171, 0xffff0000, v171
	v_lshlrev_b32_e32 v180, 16, v172
	v_and_b32_e32 v181, 0xffff0000, v172
	v_lshlrev_b32_e32 v172, 16, v173
	v_and_b32_e32 v173, 0xffff0000, v173
	v_pk_fma_f32 v[100:101], v[100:101], v[140:141], v[158:159]
	v_pk_fma_f32 v[98:99], v[98:99], v[138:139], v[162:163]
	v_pk_fma_f32 v[92:93], v[92:93], v[144:145], v[160:161]
	v_pk_fma_f32 v[90:91], v[90:91], v[142:143], v[176:177]
	v_pk_fma_f32 v[76:77], v[76:77], v[136:137], v[170:171]
	v_pk_fma_f32 v[74:75], v[74:75], v[134:135], v[178:179]
	v_pk_fma_f32 v[68:69], v[68:69], v[132:133], v[172:173]
	v_pk_fma_f32 v[66:67], v[66:67], v[130:131], v[180:181]
	v_add_u32_e32 v158, 0x80, v164
	v_mov_b32_e32 v160, v212
	v_mov_b32_e32 v161, v213
	v_mov_b32_e32 v162, v214
	v_mov_b32_e32 v163, v215
	v_mov_b32_e32 v170, v216
	v_mov_b32_e32 v171, v217
	v_mov_b32_e32 v172, v218
	v_mov_b32_e32 v173, v219
	v_ashrrev_i32_e32 v159, 31, v158
	v_lshlrev_b64 v[158:159], 11, v[158:159]
	v_lshl_add_u64 v[174:175], s[12:13], 0, v[158:159]
	v_lshl_add_u64 v[174:175], v[174:175], 0, v[146:147]
	s_waitcnt vmcnt(1)
	v_lshlrev_b32_e32 v176, 16, v160
	v_and_b32_e32 v177, 0xffff0000, v160
	v_lshlrev_b32_e32 v160, 16, v161
	v_and_b32_e32 v161, 0xffff0000, v161
	v_lshlrev_b32_e32 v178, 16, v162
	v_and_b32_e32 v179, 0xffff0000, v162
	v_lshlrev_b32_e32 v162, 16, v163
	v_and_b32_e32 v163, 0xffff0000, v163
	s_waitcnt vmcnt(0)
	v_lshlrev_b32_e32 v180, 16, v170
	v_and_b32_e32 v181, 0xffff0000, v170
	v_lshlrev_b32_e32 v170, 16, v171
	v_and_b32_e32 v171, 0xffff0000, v171
	v_lshlrev_b32_e32 v182, 16, v172
	v_and_b32_e32 v183, 0xffff0000, v172
	v_lshlrev_b32_e32 v172, 16, v173
	v_and_b32_e32 v173, 0xffff0000, v173
	v_pk_fma_f32 v[116:117], v[116:117], v[140:141], v[160:161]
	v_pk_fma_f32 v[114:115], v[114:115], v[138:139], v[176:177]
	v_pk_fma_f32 v[108:109], v[108:109], v[144:145], v[162:163]
	v_pk_fma_f32 v[106:107], v[106:107], v[142:143], v[178:179]
	v_pk_fma_f32 v[104:105], v[104:105], v[136:137], v[170:171]
	v_pk_fma_f32 v[102:103], v[102:103], v[134:135], v[180:181]
	v_pk_fma_f32 v[96:97], v[96:97], v[132:133], v[172:173]
	v_pk_fma_f32 v[94:95], v[94:95], v[130:131], v[182:183]
	v_add_u32_e32 v160, 0x90, v164
	v_mov_b32_e32 v170, v220
	v_mov_b32_e32 v171, v221
	v_mov_b32_e32 v172, v222
	v_mov_b32_e32 v173, v223
	s_nop 0
	v_mov_b32_e32 v174, v224
	v_mov_b32_e32 v175, v225
	v_mov_b32_e32 v176, v226
	v_mov_b32_e32 v177, v227
	v_ashrrev_i32_e32 v161, 31, v160
	v_lshlrev_b64 v[160:161], 11, v[160:161]
	v_lshl_add_u64 v[162:163], s[12:13], 0, v[160:161]
	v_lshl_add_u64 v[162:163], v[162:163], 0, v[146:147]
	s_waitcnt vmcnt(1)
	v_lshlrev_b32_e32 v178, 16, v170
	v_and_b32_e32 v179, 0xffff0000, v170
	v_lshlrev_b32_e32 v170, 16, v171
	v_and_b32_e32 v171, 0xffff0000, v171
	v_lshlrev_b32_e32 v180, 16, v172
	v_and_b32_e32 v181, 0xffff0000, v172
	v_lshlrev_b32_e32 v172, 16, v173
	v_and_b32_e32 v173, 0xffff0000, v173
	s_waitcnt vmcnt(0)
	v_lshlrev_b32_e32 v182, 16, v174
	v_and_b32_e32 v183, 0xffff0000, v174
	v_lshlrev_b32_e32 v174, 16, v175
	v_and_b32_e32 v175, 0xffff0000, v175
	v_lshlrev_b32_e32 v184, 16, v176
	v_and_b32_e32 v185, 0xffff0000, v176
	v_lshlrev_b32_e32 v176, 16, v177
	v_and_b32_e32 v177, 0xffff0000, v177
	v_pk_fma_f32 v[128:129], v[128:129], v[140:141], v[170:171]
	v_pk_fma_f32 v[126:127], v[126:127], v[138:139], v[178:179]
	v_pk_fma_f32 v[124:125], v[124:125], v[144:145], v[172:173]
	v_pk_fma_f32 v[122:123], v[122:123], v[142:143], v[180:181]
	v_pk_fma_f32 v[120:121], v[120:121], v[136:137], v[174:175]
	v_pk_fma_f32 v[118:119], v[118:119], v[134:135], v[182:183]
	v_pk_fma_f32 v[112:113], v[112:113], v[132:133], v[176:177]
	v_pk_fma_f32 v[110:111], v[110:111], v[130:131], v[184:185]
	s_nop 0
	v_mov_b32_e32 v170, v228
	v_mov_b32_e32 v171, v229
	v_mov_b32_e32 v172, v230
	v_mov_b32_e32 v173, v231
	v_mov_b32_e32 v174, v232
	v_mov_b32_e32 v175, v233
	v_mov_b32_e32 v176, v234
	v_mov_b32_e32 v177, v235
	v_add_u32_e32 v162, 0xa0, v164
	v_ashrrev_i32_e32 v163, 31, v162
	v_lshlrev_b64 v[162:163], 11, v[162:163]
	v_lshl_add_u64 v[178:179], s[12:13], 0, v[162:163]
	v_lshl_add_u64 v[178:179], v[178:179], 0, v[146:147]
	v_add_u32_e32 v164, 0xb0, v164
	v_ashrrev_i32_e32 v165, 31, v164
	v_lshlrev_b64 v[164:165], 11, v[164:165]
	s_waitcnt vmcnt(1)
	v_lshlrev_b32_e32 v180, 16, v170
	v_and_b32_e32 v181, 0xffff0000, v170
	v_lshlrev_b32_e32 v170, 16, v171
	v_and_b32_e32 v171, 0xffff0000, v171
	v_lshlrev_b32_e32 v182, 16, v172
	v_and_b32_e32 v183, 0xffff0000, v172
	v_lshlrev_b32_e32 v172, 16, v173
	v_and_b32_e32 v173, 0xffff0000, v173
	s_waitcnt vmcnt(0)
	v_lshlrev_b32_e32 v184, 16, v174
	v_and_b32_e32 v185, 0xffff0000, v174
	v_lshlrev_b32_e32 v174, 16, v175
	v_and_b32_e32 v175, 0xffff0000, v175
	v_lshlrev_b32_e32 v186, 16, v176
	v_and_b32_e32 v187, 0xffff0000, v176
	v_lshlrev_b32_e32 v176, 16, v177
	v_and_b32_e32 v177, 0xffff0000, v177
	v_pk_fma_f32 v[88:89], v[88:89], v[140:141], v[170:171]
	v_pk_fma_f32 v[86:87], v[86:87], v[138:139], v[180:181]
	v_pk_fma_f32 v[84:85], v[84:85], v[144:145], v[172:173]
	v_pk_fma_f32 v[82:83], v[82:83], v[142:143], v[182:183]
	v_pk_fma_f32 v[40:41], v[40:41], v[136:137], v[174:175]
	v_pk_fma_f32 v[38:39], v[38:39], v[134:135], v[184:185]
	v_pk_fma_f32 v[36:37], v[36:37], v[132:133], v[176:177]
	v_pk_fma_f32 v[34:35], v[34:35], v[130:131], v[186:187]
	v_mov_b32_e32 v184, v59
	v_mov_b32_e32 v170, v236
	v_mov_b32_e32 v171, v237
	v_mov_b32_e32 v172, v238
	v_mov_b32_e32 v173, v239
	v_mov_b32_e32 v174, v240
	v_mov_b32_e32 v175, v241
	v_mov_b32_e32 v176, v242
	v_mov_b32_e32 v177, v243
	v_lshl_add_u64 v[178:179], s[12:13], 0, v[164:165]
	v_lshl_add_u64 v[180:181], v[178:179], 0, v[146:147]
	v_mov_b32_e32 v185, v60
	v_mov_b32_e32 v186, v58
	v_mov_b32_e32 v187, v61
	v_pk_add_f32 v[184:185], v[184:185], v[186:187]
	s_waitcnt vmcnt(1)
; __device__ __forceinline__ float bf_lo(unsigned w) { return __uint_as_float(w << 16); }
; __device__ __forceinline__ float bf_hi(unsigned w) { return __uint_as_float(w & 0xffff0000u); }
;     template <class Mid> __device__ __forceinline__ bool run(const f32x4 (&v)[2][2][4][2], const Unit& u, int wr, int wc, int fr, int fq, PG8_LAS unsigned char* lds, int wid, int lane, const Mid& mid) const {
;     ...
;                     for (int n = 0; n < 2; ++n) { const f32x4 x = v[ai][bj][m][n]; s += (x[0] + x[1]) + (x[2] + x[3]); }
;                 s += __shfl_xor(s, 16); s += __shfl_xor(s, 32);
;                 const float mw = s * (1.0f / 64.0f); float q = 0.f;
; #pragma unroll
;                 for (int bj = 0; bj < 2; ++bj)
; #pragma unroll
;                     for (int n = 0; n < 2; ++n) { const f32x4 d = v[ai][bj][m][n] - mw; q += (d[0] * d[0] + d[1] * d[1]) + (d[2] * d[2] + d[3] * d[3]); }
;                 q += __shfl_xor(q, 16); q += __shfl_xor(q, 32);
;                 if (fq == 0) P[(ai * HALF + wr * 64 + m * 16 + fr) * 4 + wc] = (f32x2v){mw, q};
;     __device__ __forceinline__ void fused(f32x4 (&acc)[2][2][4][2], const Unit& u, int wr, int wc, int fr, int fq, PG8_LAS unsigned char* lds, int wid, int lane) const {
;     ...
;                 for (int m = 0; m < 4; ++m) { const int r = ai * HALF + wr * 64 + m * 16 + fr; const size_t off = (size_t)(u.pm * BM + r) * 1024 + col0;
; #pragma unroll
;                     for (int bj = 0; bj < 2; ++bj) { f32x4 b0, b1;
;                         if (XIN_BF16) { const u32x4 w = *(const u32x4*)((const bf16_t*)xin + off + bj * HALF); b0 = (f32x4){bf_lo(w.x), bf_hi(w.x), bf_lo(w.y), bf_hi(w.y)}; b1 = (f32x4){bf_lo(w.z), bf_hi(w.z), bf_lo(w.w), bf_hi(w.w)}; }
;                         else { b0 = *(const f32x4*)((const float*)xin + off + bj * HALF); b1 = *(const f32x4*)((const float*)xin + off + bj * HALF + 4); }
;                         acc[ai][bj][m][0] = b0 + gv[bj][0] * acc[ai][bj][m][0]; acc[ai][bj][m][1] = b1 + gv[bj][1] * acc[ai][bj][m][1]; }
	v_lshlrev_b32_e32 v178, 16, v170
	v_and_b32_e32 v179, 0xffff0000, v170
	v_lshlrev_b32_e32 v170, 16, v171
	v_and_b32_e32 v171, 0xffff0000, v171
	v_lshlrev_b32_e32 v182, 16, v172
	v_and_b32_e32 v183, 0xffff0000, v172
	v_lshlrev_b32_e32 v172, 16, v173
	v_and_b32_e32 v173, 0xffff0000, v173
	s_waitcnt vmcnt(0)
	v_lshlrev_b32_e32 v188, 16, v174
	v_and_b32_e32 v189, 0xffff0000, v174
	v_lshlrev_b32_e32 v174, 16, v175
	v_and_b32_e32 v175, 0xffff0000, v175
	v_lshlrev_b32_e32 v190, 16, v176
	v_and_b32_e32 v191, 0xffff0000, v176
	v_lshlrev_b32_e32 v176, 16, v177
	v_and_b32_e32 v177, 0xffff0000, v177
	v_pk_fma_f32 v[32:33], v[32:33], v[140:141], v[170:171]
	v_pk_fma_f32 v[30:31], v[30:31], v[138:139], v[178:179]
	v_pk_fma_f32 v[28:29], v[28:29], v[144:145], v[172:173]
	v_pk_fma_f32 v[26:27], v[26:27], v[142:143], v[182:183]
	v_pk_fma_f32 v[24:25], v[24:25], v[136:137], v[174:175]
	v_pk_fma_f32 v[22:23], v[22:23], v[134:135], v[188:189]
	v_pk_fma_f32 v[20:21], v[20:21], v[132:133], v[176:177]
	v_pk_fma_f32 v[18:19], v[18:19], v[130:131], v[190:191]
	v_mov_b32_e32 v170, v63
	v_mov_b32_e32 v176, v248
	v_mov_b32_e32 v177, v249
	v_mov_b32_e32 v178, v250
	v_mov_b32_e32 v179, v251
	v_mov_b32_e32 v171, v64
	v_mov_b32_e32 v180, v252
	v_mov_b32_e32 v181, v253
	v_mov_b32_e32 v182, v254
	v_mov_b32_e32 v183, v255
	v_mov_b32_e32 v172, v62
	v_mov_b32_e32 v173, v65
	v_add_f32_e32 v175, v54, v55
	v_add_f32_e32 v189, v56, v57
	v_mov_b32_e32 v174, v46
	v_mov_b32_e32 v188, v47
	v_pk_add_f32 v[170:171], v[170:171], v[172:173]
	v_pk_add_f32 v[172:173], v[174:175], v[188:189]
	v_add_f32_e32 v174, v184, v185
	v_pk_add_f32 v[170:171], v[170:171], v[170:171] op_sel_hi:[0,1]
	v_mov_b32_e32 v190, v49
	v_add_f32_e32 v191, 0, v174
	v_mov_b32_e32 v170, v48
	v_pk_add_f32 v[170:171], v[170:171], v[190:191]
	s_nop 0
	v_pk_add_f32 v[170:171], v[172:173], v[170:171]
	s_nop 0
	v_add_f32_e32 v170, v170, v171
	ds_bpermute_b32 v172, v169, v170
	v_xor_b32_e32 v171, 32, v192
	v_cmp_lt_i32_e32 vcc, v171, v193
	s_waitcnt lgkmcnt(0)
	v_add_f32_e32 v170, v170, v172
	v_cndmask_b32_e32 v171, v192, v171, vcc
	v_lshlrev_b32_e32 v171, 2, v171
	ds_bpermute_b32 v172, v171, v170
	s_waitcnt lgkmcnt(0)
	v_add_f32_e32 v172, v170, v172
	v_fmamk_f32 v173, v172, 0xbc800000, v61
	v_fmamk_f32 v175, v172, 0xbc800000, v59
	v_fmamk_f32 v185, v172, 0xbc800000, v65
	v_fmamk_f32 v187, v172, 0xbc800000, v63
	v_fmamk_f32 v170, v172, 0xbc800000, v60
	v_fmamk_f32 v174, v172, 0xbc800000, v58
	v_fmamk_f32 v184, v172, 0xbc800000, v64
	v_fmamk_f32 v186, v172, 0xbc800000, v62
	v_fmamk_f32 v189, v172, 0xbc800000, v57
	v_fmamk_f32 v191, v172, 0xbc800000, v55
	v_mul_f32_e32 v175, v175, v175
	v_mul_f32_e32 v173, v173, v173
	v_mul_f32_e32 v187, v187, v187
	v_mul_f32_e32 v185, v185, v185
	v_fmamk_f32 v188, v172, 0xbc800000, v56
	v_fmamk_f32 v190, v172, 0xbc800000, v54
	v_fmamk_f32 v193, v172, 0xbc800000, v49
	v_fmamk_f32 v195, v172, 0xbc800000, v47
	v_mul_f32_e32 v191, v191, v191
	v_mul_f32_e32 v189, v189, v189
	v_fmac_f32_e32 v175, v174, v174
	v_fmac_f32_e32 v173, v170, v170
	v_fmac_f32_e32 v187, v186, v186
	v_fmac_f32_e32 v185, v184, v184
	v_fmamk_f32 v192, v172, 0xbc800000, v48
	v_fmamk_f32 v194, v172, 0xbc800000, v46
	v_mul_f32_e32 v195, v195, v195
	v_mul_f32_e32 v193, v193, v193
	v_fmac_f32_e32 v191, v190, v190
	v_fmac_f32_e32 v189, v188, v188
	v_add_f32_e32 v170, v175, v173
	v_add_f32_e32 v173, v187, v185
	v_fmac_f32_e32 v195, v194, v194
	v_fmac_f32_e32 v193, v192, v192
	v_add_f32_e32 v174, v191, v189
	v_add_f32_e32 v170, v170, v173
	v_add_f32_e32 v175, v195, v193
	v_add_f32_e32 v170, v174, v170
	v_add_f32_e32 v173, v175, v170
	ds_bpermute_b32 v174, v169, v173
	v_and_b32_e32 v170, 63, v168
	v_cmp_gt_u32_e32 vcc, 16, v170
	s_waitcnt lgkmcnt(0)
	v_add_f32_e32 v173, v173, v174
	ds_bpermute_b32 v174, v171, v173
	s_waitcnt vmcnt(1)
	v_lshlrev_b32_e32 v184, 16, v176
	v_and_b32_e32 v185, 0xffff0000, v176
	v_lshlrev_b32_e32 v176, 16, v177
	v_and_b32_e32 v177, 0xffff0000, v177
	v_lshlrev_b32_e32 v186, 16, v178
	v_and_b32_e32 v187, 0xffff0000, v178
	v_lshlrev_b32_e32 v178, 16, v179
	v_and_b32_e32 v179, 0xffff0000, v179
	s_waitcnt vmcnt(0)
	v_lshlrev_b32_e32 v188, 16, v180
	v_and_b32_e32 v189, 0xffff0000, v180
	v_lshlrev_b32_e32 v180, 16, v181
	v_and_b32_e32 v181, 0xffff0000, v181
	v_lshlrev_b32_e32 v190, 16, v182
	v_and_b32_e32 v191, 0xffff0000, v182
	v_lshlrev_b32_e32 v182, 16, v183
	v_and_b32_e32 v183, 0xffff0000, v183
	v_pk_fma_f32 v[16:17], v[16:17], v[140:141], v[176:177]
	v_pk_fma_f32 v[14:15], v[14:15], v[138:139], v[184:185]
	v_pk_fma_f32 v[12:13], v[12:13], v[144:145], v[178:179]
	v_pk_fma_f32 v[10:11], v[10:11], v[142:143], v[186:187]
	v_pk_fma_f32 v[8:9], v[8:9], v[136:137], v[180:181]
	v_pk_fma_f32 v[6:7], v[6:7], v[134:135], v[188:189]
	v_pk_fma_f32 v[4:5], v[4:5], v[132:133], v[182:183]
	v_pk_fma_f32 v[2:3], v[2:3], v[130:131], v[190:191]
	s_nop 0
	s_and_saveexec_b64 s[6:7], vcc
	s_cbranch_execz .LBB0_1637
	s_lshl_b32 s9, s24, 11
	s_add_i32 s9, s8, s9
	v_mul_f32_e32 v130, 0x3c800000, v172
	s_waitcnt lgkmcnt(0)
	v_add_f32_e32 v131, v173, v174
	v_lshl_add_u32 v132, v167, 5, s9
	ds_write_b64 v132, v[130:131]

; __device__ __forceinline__ float bf_lo(unsigned w) { return __uint_as_float(w << 16); }
; __device__ __forceinline__ float bf_hi(unsigned w) { return __uint_as_float(w & 0xffff0000u); }
;     __device__ __forceinline__ void fused(f32x4 (&acc)[2][2][4][2], const Unit& u, int wr, int wc, int fr, int fq, PG8_LAS unsigned char* lds, int wid, int lane) const {
;     ...
;         const int col0 = u.pn * BM + wc * 32 + 8 * fq, b = u.pm >> 4;
;         {
;             f32x4 gv[2][2];
; #pragma unroll
;             for (int bj = 0; bj < 2; ++bj)
; #pragma unroll
;                 for (int n = 0; n < 2; ++n) gv[bj][n] = *(const f32x4*)(g + (size_t)b * 6144 + col0 + bj * HALF + 4 * n);
; #pragma unroll
;             for (int ai = 0; ai < 2; ++ai)
; #pragma unroll
;                 for (int m = 0; m < 4; ++m) { const int r = ai * HALF + wr * 64 + m * 16 + fr; const size_t off = (size_t)(u.pm * BM + r) * 1024 + col0;
; #pragma unroll
;                     for (int bj = 0; bj < 2; ++bj) { f32x4 b0, b1;
;                         if (XIN_BF16) { const u32x4 w = *(const u32x4*)((const bf16_t*)xin + off + bj * HALF); b0 = (f32x4){bf_lo(w.x), bf_hi(w.x), bf_lo(w.y), bf_hi(w.y)}; b1 = (f32x4){bf_lo(w.z), bf_hi(w.z), bf_lo(w.w), bf_hi(w.w)}; }
;                         else { b0 = *(const f32x4*)((const float*)xin + off + bj * HALF); b1 = *(const f32x4*)((const float*)xin + off + bj * HALF + 4); }
;                         acc[ai][bj][m][0] = b0 + gv[bj][0] * acc[ai][bj][m][0]; acc[ai][bj][m][1] = b1 + gv[bj][1] * acc[ai][bj][m][1]; }
.LBB0_1845:
	s_add_u32 s0, s12, 0xc800000
	s_addc_u32 s1, s13, 0
	s_lshl_b32 s2, s34, 5
	s_lshl_b32 s3, s14, 8
	v_lshrrev_b32_e32 v130, 1, v0
	s_or_b32 s2, s3, s2
	v_and_or_b32 v152, v130, 24, s2
	s_ashr_i32 s2, s31, 4
	s_mul_hi_i32 s3, s2, 0x6000
	s_mulk_i32 s2, 0x6000
	s_add_u32 s4, s12, s2
	s_addc_u32 s5, s13, s3
	s_lshl_b32 s2, s31, 8
	v_add_u32_e32 v146, s2, v166
	v_ashrrev_i32_e32 v147, 31, v146
	v_ashrrev_i32_e32 v153, 31, v152
	v_lshlrev_b64 v[130:131], 11, v[146:147]
	v_lshl_add_u64 v[130:131], s[0:1], 0, v[130:131]
	v_lshlrev_b64 v[164:165], 1, v[152:153]
	v_lshl_add_u64 v[130:131], v[130:131], 0, v[164:165]
	v_lshl_add_u64 v[132:133], v[152:153], 2, s[4:5]
	s_mov_b32 s3, 0x1d000
	s_barrier
	s_mov_b64 s[98:99], 0x8000
	v_lshl_add_u64 v[244:245], v[130:131], 0, s[98:99]
	global_load_dwordx4 v[192:195], v[244:245], off
	global_load_dwordx4 v[196:199], v[244:245], off offset:256
	s_mov_b64 s[98:99], 0x10000
	v_lshl_add_u64 v[244:245], v[130:131], 0, s[98:99]
	global_load_dwordx4 v[200:203], v[244:245], off
	global_load_dwordx4 v[204:207], v[244:245], off offset:256
	s_mov_b64 s[98:99], 0x18000
	v_lshl_add_u64 v[244:245], v[130:131], 0, s[98:99]
	global_load_dwordx4 v[208:211], v[244:245], off
	global_load_dwordx4 v[212:215], v[244:245], off offset:256
	s_mov_b64 s[98:99], 0x40000
	v_lshl_add_u64 v[244:245], v[130:131], 0, s[98:99]
	global_load_dwordx4 v[216:219], v[244:245], off
	global_load_dwordx4 v[220:223], v[244:245], off offset:256
	s_mov_b64 s[98:99], 0x48000
	v_lshl_add_u64 v[244:245], v[130:131], 0, s[98:99]
	global_load_dwordx4 v[224:227], v[244:245], off
	global_load_dwordx4 v[228:231], v[244:245], off offset:256
	s_mov_b64 s[98:99], 0x50000
	v_lshl_add_u64 v[244:245], v[130:131], 0, s[98:99]
	global_load_dwordx4 v[232:235], v[244:245], off
	global_load_dwordx4 v[236:239], v[244:245], off offset:256
	s_mov_b64 s[98:99], 0x58000
	v_lshl_add_u64 v[244:245], v[130:131], 0, s[98:99]
	global_load_dwordx4 v[240:243], v[244:245], off
	global_load_dwordx4 v[248:251], v[244:245], off offset:256
	global_load_dwordx4 v[154:157], v[130:131], off
	global_load_dwordx4 v[158:161], v[130:131], off offset:256
	v_add_co_u32_e32 v130, vcc, s3, v132
	s_mov_b64 s[4:5], 0x1d000
	s_nop 0
	v_addc_co_u32_e32 v131, vcc, 0, v133, vcc
	global_load_dwordx4 v[138:141], v[130:131], off
	v_lshl_add_u64 v[130:131], v[132:133], 0, s[4:5]
	global_load_dwordx4 v[142:145], v[130:131], off offset:16
	global_load_dwordx4 v[134:137], v[130:131], off offset:512
	s_nop 0
	global_load_dwordx4 v[130:133], v[130:131], off offset:528
	v_add_u32_e32 v148, 16, v146
	v_ashrrev_i32_e32 v149, 31, v148
	v_lshlrev_b64 v[150:151], 11, v[148:149]
	v_lshl_add_u64 v[150:151], s[0:1], 0, v[150:151]
	v_lshl_add_u64 v[150:151], v[150:151], 0, v[164:165]
	v_mbcnt_hi_u32_b32 v188, -1, v1
	v_xor_b32_e32 v1, 16, v188
	s_waitcnt vmcnt(0)
	v_lshlrev_b32_e32 v162, 16, v154
	v_and_b32_e32 v163, 0xffff0000, v154
	v_lshlrev_b32_e32 v154, 16, v155
	v_and_b32_e32 v155, 0xffff0000, v155
	v_lshlrev_b32_e32 v168, 16, v156
	v_and_b32_e32 v169, 0xffff0000, v156
	v_lshlrev_b32_e32 v156, 16, v157
	v_and_b32_e32 v157, 0xffff0000, v157
	v_lshlrev_b32_e32 v170, 16, v158
	v_and_b32_e32 v171, 0xffff0000, v158
	v_lshlrev_b32_e32 v158, 16, v159
	v_and_b32_e32 v159, 0xffff0000, v159
	v_lshlrev_b32_e32 v172, 16, v160
	v_and_b32_e32 v173, 0xffff0000, v160
	v_lshlrev_b32_e32 v160, 16, v161
	v_and_b32_e32 v161, 0xffff0000, v161
	v_pk_fma_f32 v[102:103], v[102:103], v[138:139], v[162:163]
	v_pk_fma_f32 v[104:105], v[104:105], v[140:141], v[154:155]
	v_pk_fma_f32 v[108:109], v[108:109], v[144:145], v[156:157]
	v_pk_fma_f32 v[106:107], v[106:107], v[142:143], v[168:169]
	v_pk_fma_f32 v[88:89], v[88:89], v[136:137], v[158:159]
	v_pk_fma_f32 v[86:87], v[86:87], v[134:135], v[170:171]
	v_pk_fma_f32 v[84:85], v[84:85], v[132:133], v[160:161]
	v_pk_fma_f32 v[82:83], v[82:83], v[130:131], v[172:173]
	s_nop 0
	v_mov_b32_e32 v154, v192
	v_mov_b32_e32 v155, v193
	v_mov_b32_e32 v156, v194
	v_mov_b32_e32 v157, v195
	v_mov_b32_e32 v158, v196
	v_mov_b32_e32 v159, v197
	v_mov_b32_e32 v160, v198
	v_mov_b32_e32 v161, v199
	v_add_u32_e32 v150, 32, v146
	v_ashrrev_i32_e32 v151, 31, v150
	v_lshlrev_b64 v[162:163], 11, v[150:151]
	v_lshl_add_u64 v[162:163], s[0:1], 0, v[162:163]
	v_lshl_add_u64 v[162:163], v[162:163], 0, v[164:165]
	s_waitcnt vmcnt(1)
	v_lshlrev_b32_e32 v168, 16, v154
	v_and_b32_e32 v169, 0xffff0000, v154
	v_lshlrev_b32_e32 v154, 16, v155
	v_and_b32_e32 v155, 0xffff0000, v155
	v_lshlrev_b32_e32 v170, 16, v156
	v_and_b32_e32 v171, 0xffff0000, v156
	v_lshlrev_b32_e32 v156, 16, v157
	v_and_b32_e32 v157, 0xffff0000, v157
	s_waitcnt vmcnt(0)
	v_lshlrev_b32_e32 v172, 16, v158
	v_and_b32_e32 v173, 0xffff0000, v158
	v_lshlrev_b32_e32 v158, 16, v159
	v_and_b32_e32 v159, 0xffff0000, v159
	v_lshlrev_b32_e32 v174, 16, v160
	v_and_b32_e32 v175, 0xffff0000, v160
	v_lshlrev_b32_e32 v160, 16, v161
	v_and_b32_e32 v161, 0xffff0000, v161
	v_pk_fma_f32 v[116:117], v[116:117], v[140:141], v[154:155]
	v_pk_fma_f32 v[114:115], v[114:115], v[138:139], v[168:169]
	v_pk_fma_f32 v[120:121], v[120:121], v[144:145], v[156:157]
	v_pk_fma_f32 v[118:119], v[118:119], v[142:143], v[170:171]
	v_pk_fma_f32 v[96:97], v[96:97], v[136:137], v[158:159]
	v_pk_fma_f32 v[94:95], v[94:95], v[134:135], v[172:173]
	v_pk_fma_f32 v[92:93], v[92:93], v[132:133], v[160:161]
	v_pk_fma_f32 v[90:91], v[90:91], v[130:131], v[174:175]
	v_add_u32_e32 v154, 48, v146
	v_mov_b32_e32 v156, v200
	v_mov_b32_e32 v157, v201
	v_mov_b32_e32 v158, v202
	v_mov_b32_e32 v159, v203
	s_nop 0
	v_mov_b32_e32 v160, v204
	v_mov_b32_e32 v161, v205
	v_mov_b32_e32 v162, v206
	v_mov_b32_e32 v163, v207
	v_ashrrev_i32_e32 v155, 31, v154
	v_lshlrev_b64 v[168:169], 11, v[154:155]
	v_lshl_add_u64 v[168:169], s[0:1], 0, v[168:169]
	v_lshl_add_u64 v[168:169], v[168:169], 0, v[164:165]
	s_waitcnt vmcnt(1)
; __device__ __forceinline__ float bf_lo(unsigned w) { return __uint_as_float(w << 16); }
; __device__ __forceinline__ float bf_hi(unsigned w) { return __uint_as_float(w & 0xffff0000u); }
;     __device__ __forceinline__ void fused(f32x4 (&acc)[2][2][4][2], const Unit& u, int wr, int wc, int fr, int fq, PG8_LAS unsigned char* lds, int wid, int lane) const {
;     ...
;             for (int ai = 0; ai < 2; ++ai)
; #pragma unroll
;                 for (int m = 0; m < 4; ++m) { const int r = ai * HALF + wr * 64 + m * 16 + fr; const size_t off = (size_t)(u.pm * BM + r) * 1024 + col0;
; #pragma unroll
;                     for (int bj = 0; bj < 2; ++bj) { f32x4 b0, b1;
;                         if (XIN_BF16) { const u32x4 w = *(const u32x4*)((const bf16_t*)xin + off + bj * HALF); b0 = (f32x4){bf_lo(w.x), bf_hi(w.x), bf_lo(w.y), bf_hi(w.y)}; b1 = (f32x4){bf_lo(w.z), bf_hi(w.z), bf_lo(w.w), bf_hi(w.w)}; }
;                         else { b0 = *(const f32x4*)((const float*)xin + off + bj * HALF); b1 = *(const f32x4*)((const float*)xin + off + bj * HALF + 4); }
;                         acc[ai][bj][m][0] = b0 + gv[bj][0] * acc[ai][bj][m][0]; acc[ai][bj][m][1] = b1 + gv[bj][1] * acc[ai][bj][m][1]; }
	v_lshlrev_b32_e32 v170, 16, v156
	v_and_b32_e32 v171, 0xffff0000, v156
	v_lshlrev_b32_e32 v156, 16, v157
	v_and_b32_e32 v157, 0xffff0000, v157
	v_lshlrev_b32_e32 v172, 16, v158
	v_and_b32_e32 v173, 0xffff0000, v158
	v_lshlrev_b32_e32 v158, 16, v159
	v_and_b32_e32 v159, 0xffff0000, v159
	s_waitcnt vmcnt(0)
	v_lshlrev_b32_e32 v174, 16, v160
	v_and_b32_e32 v175, 0xffff0000, v160
	v_lshlrev_b32_e32 v160, 16, v161
	v_and_b32_e32 v161, 0xffff0000, v161
	v_lshlrev_b32_e32 v176, 16, v162
	v_and_b32_e32 v177, 0xffff0000, v162
	v_lshlrev_b32_e32 v162, 16, v163
	v_and_b32_e32 v163, 0xffff0000, v163
	v_pk_fma_f32 v[128:129], v[128:129], v[140:141], v[156:157]
	v_pk_fma_f32 v[126:127], v[126:127], v[138:139], v[170:171]
	v_pk_fma_f32 v[124:125], v[124:125], v[144:145], v[158:159]
	v_pk_fma_f32 v[122:123], v[122:123], v[142:143], v[172:173]
	v_pk_fma_f32 v[112:113], v[112:113], v[136:137], v[160:161]
	v_pk_fma_f32 v[110:111], v[110:111], v[134:135], v[174:175]
	v_pk_fma_f32 v[100:101], v[100:101], v[132:133], v[162:163]
	v_pk_fma_f32 v[98:99], v[98:99], v[130:131], v[176:177]
	v_add_u32_e32 v156, 0x80, v146
	v_mov_b32_e32 v158, v208
	v_mov_b32_e32 v159, v209
	v_mov_b32_e32 v160, v210
	v_mov_b32_e32 v161, v211
	s_nop 0
	v_mov_b32_e32 v168, v212
	v_mov_b32_e32 v169, v213
	v_mov_b32_e32 v170, v214
	v_mov_b32_e32 v171, v215
	v_ashrrev_i32_e32 v157, 31, v156
	v_lshlrev_b64 v[162:163], 11, v[156:157]
	v_lshl_add_u64 v[162:163], s[0:1], 0, v[162:163]
	v_lshl_add_u64 v[172:173], v[162:163], 0, v[164:165]
	s_waitcnt vmcnt(1)
	v_lshlrev_b32_e32 v162, 16, v158
	v_and_b32_e32 v163, 0xffff0000, v158
	v_lshlrev_b32_e32 v158, 16, v159
	v_and_b32_e32 v159, 0xffff0000, v159
	v_lshlrev_b32_e32 v174, 16, v160
	v_and_b32_e32 v175, 0xffff0000, v160
	v_lshlrev_b32_e32 v160, 16, v161
	v_and_b32_e32 v161, 0xffff0000, v161
	s_waitcnt vmcnt(0)
	v_lshlrev_b32_e32 v176, 16, v168
	v_and_b32_e32 v177, 0xffff0000, v168
	v_lshlrev_b32_e32 v168, 16, v169
	v_and_b32_e32 v169, 0xffff0000, v169
	v_lshlrev_b32_e32 v178, 16, v170
	v_and_b32_e32 v179, 0xffff0000, v170
	v_lshlrev_b32_e32 v170, 16, v171
	v_and_b32_e32 v171, 0xffff0000, v171
	v_pk_fma_f32 v[80:81], v[80:81], v[140:141], v[158:159]
	v_pk_fma_f32 v[78:79], v[78:79], v[138:139], v[162:163]
	v_pk_fma_f32 v[76:77], v[76:77], v[144:145], v[160:161]
	v_pk_fma_f32 v[74:75], v[74:75], v[142:143], v[174:175]
	v_pk_fma_f32 v[72:73], v[72:73], v[136:137], v[168:169]
	v_pk_fma_f32 v[70:71], v[70:71], v[134:135], v[176:177]
	v_pk_fma_f32 v[68:69], v[68:69], v[132:133], v[170:171]
	v_pk_fma_f32 v[66:67], v[66:67], v[130:131], v[178:179]
	v_add_u32_e32 v158, 0x90, v146
	v_mov_b32_e32 v160, v216
	v_mov_b32_e32 v161, v217
	v_mov_b32_e32 v162, v218
	v_mov_b32_e32 v163, v219
	v_mov_b32_e32 v168, v220
	v_mov_b32_e32 v169, v221
	v_mov_b32_e32 v170, v222
	v_mov_b32_e32 v171, v223
	v_ashrrev_i32_e32 v159, 31, v158
	v_lshlrev_b64 v[172:173], 11, v[158:159]
	v_lshl_add_u64 v[172:173], s[0:1], 0, v[172:173]
	v_lshl_add_u64 v[172:173], v[172:173], 0, v[164:165]
	s_waitcnt vmcnt(1)
	v_lshlrev_b32_e32 v174, 16, v160
	v_and_b32_e32 v175, 0xffff0000, v160
	v_lshlrev_b32_e32 v160, 16, v161
	v_and_b32_e32 v161, 0xffff0000, v161
	v_lshlrev_b32_e32 v176, 16, v162
	v_and_b32_e32 v177, 0xffff0000, v162
	v_lshlrev_b32_e32 v162, 16, v163
	v_and_b32_e32 v163, 0xffff0000, v163
	s_waitcnt vmcnt(0)
	v_lshlrev_b32_e32 v178, 16, v168
	v_and_b32_e32 v179, 0xffff0000, v168
	v_lshlrev_b32_e32 v168, 16, v169
	v_and_b32_e32 v169, 0xffff0000, v169
	v_lshlrev_b32_e32 v180, 16, v170
	v_and_b32_e32 v181, 0xffff0000, v170
	v_lshlrev_b32_e32 v170, 16, v171
	v_and_b32_e32 v171, 0xffff0000, v171
	v_pk_fma_f32 v[64:65], v[64:65], v[140:141], v[160:161]
	v_pk_fma_f32 v[62:63], v[62:63], v[138:139], v[174:175]
	v_pk_fma_f32 v[60:61], v[60:61], v[144:145], v[162:163]
	v_pk_fma_f32 v[58:59], v[58:59], v[142:143], v[176:177]
	v_pk_fma_f32 v[56:57], v[56:57], v[136:137], v[168:169]
	v_pk_fma_f32 v[54:55], v[54:55], v[134:135], v[178:179]
	v_pk_fma_f32 v[52:53], v[52:53], v[132:133], v[170:171]
	v_pk_fma_f32 v[50:51], v[50:51], v[130:131], v[180:181]
	v_add_u32_e32 v160, 0xa0, v146
	v_mov_b32_e32 v168, v224
	v_mov_b32_e32 v169, v225
	v_mov_b32_e32 v170, v226
	v_mov_b32_e32 v171, v227
	s_nop 0
	v_mov_b32_e32 v172, v228
	v_mov_b32_e32 v173, v229
	v_mov_b32_e32 v174, v230
	v_mov_b32_e32 v175, v231
	v_ashrrev_i32_e32 v161, 31, v160
	v_lshlrev_b64 v[162:163], 11, v[160:161]
	v_lshl_add_u64 v[162:163], s[0:1], 0, v[162:163]
	v_lshl_add_u64 v[162:163], v[162:163], 0, v[164:165]
	s_waitcnt vmcnt(1)
	v_lshlrev_b32_e32 v176, 16, v168
	v_and_b32_e32 v177, 0xffff0000, v168
	v_lshlrev_b32_e32 v168, 16, v169
	v_and_b32_e32 v169, 0xffff0000, v169
	v_lshlrev_b32_e32 v178, 16, v170
	v_and_b32_e32 v179, 0xffff0000, v170
	v_lshlrev_b32_e32 v170, 16, v171
	v_and_b32_e32 v171, 0xffff0000, v171
	s_waitcnt vmcnt(0)
	v_lshlrev_b32_e32 v180, 16, v172
	v_and_b32_e32 v181, 0xffff0000, v172
	v_lshlrev_b32_e32 v172, 16, v173
	v_and_b32_e32 v173, 0xffff0000, v173
	v_lshlrev_b32_e32 v182, 16, v174
	v_and_b32_e32 v183, 0xffff0000, v174
	v_lshlrev_b32_e32 v174, 16, v175
	v_and_b32_e32 v175, 0xffff0000, v175
	v_pk_fma_f32 v[48:49], v[48:49], v[140:141], v[168:169]
	v_pk_fma_f32 v[46:47], v[46:47], v[138:139], v[176:177]
	v_pk_fma_f32 v[44:45], v[44:45], v[144:145], v[170:171]
	v_pk_fma_f32 v[42:43], v[42:43], v[142:143], v[178:179]
	v_pk_fma_f32 v[40:41], v[40:41], v[136:137], v[172:173]
	v_pk_fma_f32 v[38:39], v[38:39], v[134:135], v[180:181]
	v_pk_fma_f32 v[36:37], v[36:37], v[132:133], v[174:175]
	v_pk_fma_f32 v[34:35], v[34:35], v[130:131], v[182:183]
	v_mov_b32_e32 v180, v103
	v_mov_b32_e32 v168, v232
	v_mov_b32_e32 v169, v233
	v_mov_b32_e32 v170, v234
	v_mov_b32_e32 v171, v235
	v_mov_b32_e32 v172, v236
	v_mov_b32_e32 v173, v237
	v_mov_b32_e32 v174, v238
	v_mov_b32_e32 v175, v239
	v_and_b32_e32 v162, 64, v188
	v_add_u32_e32 v189, 64, v162
	v_add_u32_e32 v162, 0xb0, v146
	v_ashrrev_i32_e32 v163, 31, v162
	v_lshlrev_b64 v[176:177], 11, v[162:163]
	v_lshl_add_u64 v[176:177], s[0:1], 0, v[176:177]
	v_lshl_add_u64 v[164:165], v[176:177], 0, v[164:165]
	v_mov_b32_e32 v181, v104
	v_mov_b32_e32 v182, v102
	v_mov_b32_e32 v183, v105
	v_pk_add_f32 v[180:181], v[180:181], v[182:183]
	v_cmp_lt_i32_e32 vcc, v1, v189
	s_lshl_b32 s0, s34, 3
	s_add_i32 s3, s0, 0
	v_cndmask_b32_e32 v1, v188, v1, vcc
	v_lshlrev_b32_e32 v1, 2, v1
	s_waitcnt vmcnt(1)
; __device__ __forceinline__ float bf_lo(unsigned w) { return __uint_as_float(w << 16); }
; __device__ __forceinline__ float bf_hi(unsigned w) { return __uint_as_float(w & 0xffff0000u); }
;     template <class Mid> __device__ __forceinline__ bool run(const f32x4 (&v)[2][2][4][2], const Unit& u, int wr, int wc, int fr, int fq, PG8_LAS unsigned char* lds, int wid, int lane, const Mid& mid) const {
;     ...
;                     for (int n = 0; n < 2; ++n) { const f32x4 x = v[ai][bj][m][n]; s += (x[0] + x[1]) + (x[2] + x[3]); }
;                 s += __shfl_xor(s, 16); s += __shfl_xor(s, 32);
;                 const float mw = s * (1.0f / 64.0f); float q = 0.f;
; #pragma unroll
;                 for (int bj = 0; bj < 2; ++bj)
; #pragma unroll
;                     for (int n = 0; n < 2; ++n) { const f32x4 d = v[ai][bj][m][n] - mw; q += (d[0] * d[0] + d[1] * d[1]) + (d[2] * d[2] + d[3] * d[3]); }
;                 q += __shfl_xor(q, 16); q += __shfl_xor(q, 32);
;                 if (fq == 0) P[(ai * HALF + wr * 64 + m * 16 + fr) * 4 + wc] = (f32x2v){mw, q};
;     __device__ __forceinline__ void fused(f32x4 (&acc)[2][2][4][2], const Unit& u, int wr, int wc, int fr, int fq, PG8_LAS unsigned char* lds, int wid, int lane) const {
;     ...
;                 for (int m = 0; m < 4; ++m) { const int r = ai * HALF + wr * 64 + m * 16 + fr; const size_t off = (size_t)(u.pm * BM + r) * 1024 + col0;
; #pragma unroll
;                     for (int bj = 0; bj < 2; ++bj) { f32x4 b0, b1;
;                         if (XIN_BF16) { const u32x4 w = *(const u32x4*)((const bf16_t*)xin + off + bj * HALF); b0 = (f32x4){bf_lo(w.x), bf_hi(w.x), bf_lo(w.y), bf_hi(w.y)}; b1 = (f32x4){bf_lo(w.z), bf_hi(w.z), bf_lo(w.w), bf_hi(w.w)}; }
;                         else { b0 = *(const f32x4*)((const float*)xin + off + bj * HALF); b1 = *(const f32x4*)((const float*)xin + off + bj * HALF + 4); }
;                         acc[ai][bj][m][0] = b0 + gv[bj][0] * acc[ai][bj][m][0]; acc[ai][bj][m][1] = b1 + gv[bj][1] * acc[ai][bj][m][1]; }
	v_lshlrev_b32_e32 v176, 16, v168
	v_and_b32_e32 v177, 0xffff0000, v168
	v_lshlrev_b32_e32 v168, 16, v169
	v_and_b32_e32 v169, 0xffff0000, v169
	v_lshlrev_b32_e32 v178, 16, v170
	v_and_b32_e32 v179, 0xffff0000, v170
	v_lshlrev_b32_e32 v170, 16, v171
	v_and_b32_e32 v171, 0xffff0000, v171
	s_waitcnt vmcnt(0)
	v_lshlrev_b32_e32 v184, 16, v172
	v_and_b32_e32 v185, 0xffff0000, v172
	v_lshlrev_b32_e32 v172, 16, v173
	v_and_b32_e32 v173, 0xffff0000, v173
	v_lshlrev_b32_e32 v186, 16, v174
	v_and_b32_e32 v187, 0xffff0000, v174
	v_lshlrev_b32_e32 v174, 16, v175
	v_and_b32_e32 v175, 0xffff0000, v175
	v_pk_fma_f32 v[32:33], v[32:33], v[140:141], v[168:169]
	v_pk_fma_f32 v[30:31], v[30:31], v[138:139], v[176:177]
	v_pk_fma_f32 v[28:29], v[28:29], v[144:145], v[170:171]
	v_pk_fma_f32 v[26:27], v[26:27], v[142:143], v[178:179]
	v_pk_fma_f32 v[24:25], v[24:25], v[136:137], v[172:173]
	v_pk_fma_f32 v[22:23], v[22:23], v[134:135], v[184:185]
	v_pk_fma_f32 v[20:21], v[20:21], v[132:133], v[174:175]
	v_pk_fma_f32 v[18:19], v[18:19], v[130:131], v[186:187]
	v_mov_b32_e32 v168, v107
	v_mov_b32_e32 v172, v240
	v_mov_b32_e32 v173, v241
	v_mov_b32_e32 v174, v242
	v_mov_b32_e32 v175, v243
	v_mov_b32_e32 v176, v248
	v_mov_b32_e32 v177, v249
	v_mov_b32_e32 v178, v250
	v_mov_b32_e32 v179, v251
	v_mov_b32_e32 v169, v108
	v_mov_b32_e32 v170, v106
	v_mov_b32_e32 v171, v109
	v_pk_add_f32 v[168:169], v[168:169], v[170:171]
	v_add_f32_e32 v165, v180, v181
	v_pk_add_f32 v[168:169], v[168:169], v[168:169] op_sel_hi:[0,1]
	v_add_f32_e32 v185, v86, v87
	v_add_f32_e32 v187, v88, v89
	v_mov_b32_e32 v184, v82
	v_mov_b32_e32 v186, v83
	v_mov_b32_e32 v164, v85
	v_add_f32_e32 v165, 0, v165
	v_mov_b32_e32 v168, v84
	v_pk_add_f32 v[170:171], v[184:185], v[186:187]
	v_pk_add_f32 v[164:165], v[168:169], v[164:165]
	s_nop 0
	v_pk_add_f32 v[164:165], v[170:171], v[164:165]
	s_nop 0
	v_add_f32_e32 v164, v164, v165
	ds_bpermute_b32 v168, v1, v164
	v_xor_b32_e32 v165, 32, v188
	v_cmp_lt_i32_e32 vcc, v165, v189
	s_waitcnt lgkmcnt(0)
	v_add_f32_e32 v164, v164, v168
	v_cndmask_b32_e32 v165, v188, v165, vcc
	v_lshlrev_b32_e32 v165, 2, v165
	ds_bpermute_b32 v168, v165, v164
	s_waitcnt lgkmcnt(0)
	v_add_f32_e32 v168, v164, v168
	v_fmamk_f32 v169, v168, 0xbc800000, v105
	v_fmamk_f32 v171, v168, 0xbc800000, v103
	v_fmamk_f32 v181, v168, 0xbc800000, v109
	v_fmamk_f32 v183, v168, 0xbc800000, v107
	v_fmamk_f32 v164, v168, 0xbc800000, v104
	v_fmamk_f32 v170, v168, 0xbc800000, v102
	v_fmamk_f32 v180, v168, 0xbc800000, v108
	v_fmamk_f32 v182, v168, 0xbc800000, v106
	v_fmamk_f32 v185, v168, 0xbc800000, v89
	v_fmamk_f32 v187, v168, 0xbc800000, v87
	v_mul_f32_e32 v171, v171, v171
	v_mul_f32_e32 v169, v169, v169
	v_mul_f32_e32 v183, v183, v183
	v_mul_f32_e32 v181, v181, v181
	v_fmamk_f32 v184, v168, 0xbc800000, v88
	v_fmamk_f32 v186, v168, 0xbc800000, v86
	v_fmamk_f32 v189, v168, 0xbc800000, v85
	v_fmamk_f32 v191, v168, 0xbc800000, v83
	v_mul_f32_e32 v187, v187, v187
	v_mul_f32_e32 v185, v185, v185
	v_fmac_f32_e32 v171, v170, v170
	v_fmac_f32_e32 v169, v164, v164
	v_fmac_f32_e32 v183, v182, v182
	v_fmac_f32_e32 v181, v180, v180
	v_fmamk_f32 v188, v168, 0xbc800000, v84
	v_fmamk_f32 v190, v168, 0xbc800000, v82
	v_mul_f32_e32 v191, v191, v191
	v_mul_f32_e32 v189, v189, v189
	v_fmac_f32_e32 v187, v186, v186
	v_fmac_f32_e32 v185, v184, v184
	v_add_f32_e32 v164, v171, v169
	v_add_f32_e32 v169, v183, v181
	v_fmac_f32_e32 v191, v190, v190
	v_fmac_f32_e32 v189, v188, v188
	v_add_f32_e32 v170, v187, v185
	v_add_f32_e32 v164, v164, v169
	v_add_f32_e32 v171, v191, v189
	v_add_f32_e32 v164, v170, v164
	v_add_f32_e32 v169, v171, v164
	ds_bpermute_b32 v170, v1, v169
	v_and_b32_e32 v164, 63, v0
	v_cmp_gt_u32_e32 vcc, 16, v164
	s_waitcnt lgkmcnt(0)
	v_add_f32_e32 v169, v169, v170
	ds_bpermute_b32 v170, v165, v169
	s_waitcnt vmcnt(1)
	v_lshlrev_b32_e32 v180, 16, v172
	v_and_b32_e32 v181, 0xffff0000, v172
	v_lshlrev_b32_e32 v172, 16, v173
	v_and_b32_e32 v173, 0xffff0000, v173
	v_lshlrev_b32_e32 v182, 16, v174
	v_and_b32_e32 v183, 0xffff0000, v174
	v_lshlrev_b32_e32 v174, 16, v175
	v_and_b32_e32 v175, 0xffff0000, v175
	s_waitcnt vmcnt(0)
	v_lshlrev_b32_e32 v184, 16, v176
	v_and_b32_e32 v185, 0xffff0000, v176
	v_lshlrev_b32_e32 v176, 16, v177
	v_and_b32_e32 v177, 0xffff0000, v177
	v_lshlrev_b32_e32 v186, 16, v178
	v_and_b32_e32 v187, 0xffff0000, v178
	v_lshlrev_b32_e32 v178, 16, v179
	v_and_b32_e32 v179, 0xffff0000, v179
	v_pk_fma_f32 v[16:17], v[16:17], v[140:141], v[172:173]
	v_pk_fma_f32 v[14:15], v[14:15], v[138:139], v[180:181]
	v_pk_fma_f32 v[12:13], v[12:13], v[144:145], v[174:175]
	v_pk_fma_f32 v[10:11], v[10:11], v[142:143], v[182:183]
	v_pk_fma_f32 v[8:9], v[8:9], v[136:137], v[176:177]
	v_pk_fma_f32 v[6:7], v[6:7], v[134:135], v[184:185]
	v_pk_fma_f32 v[4:5], v[4:5], v[132:133], v[178:179]
	v_pk_fma_f32 v[2:3], v[2:3], v[130:131], v[186:187]
	s_nop 0
	s_and_saveexec_b64 s[0:1], vcc
	s_cbranch_execz .LBB0_1847
	s_lshl_b32 s4, s33, 11
	s_add_i32 s4, s3, s4
	v_mul_f32_e32 v130, 0x3c800000, v168
	s_waitcnt lgkmcnt(0)
	v_add_f32_e32 v131, v169, v170
	v_lshl_add_u32 v132, v167, 5, s4
	ds_write_b64 v132, v[130:131]

; __global__ void __launch_bounds__(512, 2) fwd_mega(Args a) {
	.amdhsa_kernel _Z8fwd_mega4Args
		.amdhsa_group_segment_fixed_size 0
		.amdhsa_private_segment_fixed_size 0
		.amdhsa_kernarg_size 480
		.amdhsa_user_sgpr_count 2
		.amdhsa_user_sgpr_dispatch_ptr 0
		.amdhsa_user_sgpr_queue_ptr 0
		.amdhsa_user_sgpr_kernarg_segment_ptr 1
		.amdhsa_user_sgpr_dispatch_id 0
		.amdhsa_user_sgpr_kernarg_preload_length 0
		.amdhsa_user_sgpr_kernarg_preload_offset 0
		.amdhsa_user_sgpr_private_segment_size 0
		.amdhsa_uses_dynamic_stack 0
		.amdhsa_enable_private_segment 0
		.amdhsa_system_sgpr_workgroup_id_x 1
		.amdhsa_system_sgpr_workgroup_id_y 0
		.amdhsa_system_sgpr_workgroup_id_z 0
		.amdhsa_system_sgpr_workgroup_info 0
		.amdhsa_system_vgpr_workitem_id 0
		.amdhsa_next_free_vgpr 256
		.amdhsa_next_free_sgpr 102
		.amdhsa_accum_offset 256
		.amdhsa_reserve_vcc 1
		.amdhsa_float_round_mode_32 0
		.amdhsa_float_round_mode_16_64 0
		.amdhsa_float_denorm_mode_32 3
		.amdhsa_float_denorm_mode_16_64 3
		.amdhsa_dx10_clamp 1
		.amdhsa_ieee_mode 1
		.amdhsa_fp16_overflow 0
		.amdhsa_tg_split 0
		.amdhsa_exception_fp_ieee_invalid_op 0
		.amdhsa_exception_fp_denorm_src 0
		.amdhsa_exception_fp_ieee_div_zero 0
		.amdhsa_exception_fp_ieee_overflow 0
		.amdhsa_exception_fp_ieee_underflow 0
		.amdhsa_exception_fp_ieee_inexact 0
		.amdhsa_exception_int_div_zero 0
	.end_amdhsa_kernel

; __global__ void __launch_bounds__(512, 2) fwd_mega(Args a) {
amdhsa.kernels:
  - .agpr_count:     0
    .args:
      - .offset:         0
        .size:           224
        .value_kind:     by_value
      - .offset:         224
        .size:           4
        .value_kind:     hidden_block_count_x
      - .offset:         228
        .size:           4
        .value_kind:     hidden_block_count_y
      - .offset:         232
        .size:           4
        .value_kind:     hidden_block_count_z
      - .offset:         236
        .size:           2
        .value_kind:     hidden_group_size_x
      - .offset:         238
        .size:           2
        .value_kind:     hidden_group_size_y
      - .offset:         240
        .size:           2
        .value_kind:     hidden_group_size_z
      - .offset:         242
        .size:           2
        .value_kind:     hidden_remainder_x
      - .offset:         244
        .size:           2
        .value_kind:     hidden_remainder_y
      - .offset:         246
        .size:           2
        .value_kind:     hidden_remainder_z
      - .offset:         264
        .size:           8
        .value_kind:     hidden_global_offset_x
      - .offset:         272
        .size:           8
        .value_kind:     hidden_global_offset_y
      - .offset:         280
        .size:           8
        .value_kind:     hidden_global_offset_z
      - .offset:         288
        .size:           2
        .value_kind:     hidden_grid_dims
      - .offset:         344
        .size:           4
        .value_kind:     hidden_dynamic_lds_size
    .group_segment_fixed_size: 0
    .kernarg_segment_align: 8
    .kernarg_segment_size: 480
    .language:       OpenCL C
    .language_version:
      - 2
      - 0
    .max_flat_workgroup_size: 512
    .name:           _Z8fwd_mega4Args
    .private_segment_fixed_size: 0
    .sgpr_count:     108
    .sgpr_spill_count: 24
    .symbol:         _Z8fwd_mega4Args.kd
    .uniform_work_group_size: 1
    .uses_dynamic_stack: false
    .vgpr_count:     256
    .vgpr_spill_count: 0
    .wavefront_size: 64
